# 8-phase GEMM main loops: counted vmcnt ladder (vmcnt(10) in 6 of 8 segments) so each LDS-DMA stage gets 5 segments of flight time; tail waits adjusted
# baseline (speedup 1.0000x reference)
.LBB0_109:
	ds_read_b128 v[152:155], v196
	ds_read_b128 v[156:159], v196 offset:1024
	ds_read_b128 v[160:163], v196 offset:2048
	ds_read_b128 v[164:167], v196 offset:3072
	v_add_u32_e32 v150, 0xc000, v130
	v_lshl_add_u64 v[172:173], s[70:71], 0, v[142:143]
	v_readfirstlane_b32 s38, v150
	v_add_u32_e32 v151, 0xe000, v130
	v_lshl_add_u64 v[188:189], v[172:173], 0, s[6:7]
	s_mov_b32 m0, s38
	v_readfirstlane_b32 s38, v151
	ds_read_b128 v[168:171], v197
	ds_read_b128 v[204:207], v197 offset:1024
	ds_read_b128 v[208:211], v198
	ds_read_b128 v[212:215], v198 offset:1024
	ds_read_b128 v[216:219], v199
	ds_read_b128 v[220:223], v199 offset:1024
	ds_read_b128 v[224:227], v200
	ds_read_b128 v[228:231], v200 offset:1024
	global_load_lds_dwordx4 v[188:189], off
	v_lshl_add_u64 v[188:189], v[172:173], 0, s[4:5]
	s_mov_b32 m0, s38
	s_nop 0
	global_load_lds_dwordx4 v[188:189], off
	s_waitcnt lgkmcnt(8)
	s_waitcnt vmcnt(10)
	s_barrier
	s_waitcnt lgkmcnt(0)
	s_setprio 1
	s_waitcnt lgkmcnt(0)
	v_mfma_f32_16x16x32_bf16 v[124:127], v[152:155], v[168:171], v[124:127]
	v_mfma_f32_16x16x32_bf16 v[120:123], v[160:163], v[168:171], v[120:123]
	v_mfma_f32_16x16x32_bf16 v[116:119], v[152:155], v[208:211], v[116:119]
	v_mfma_f32_16x16x32_bf16 v[112:115], v[160:163], v[208:211], v[112:115]
	v_mfma_f32_16x16x32_bf16 v[108:111], v[152:155], v[216:219], v[108:111]
	v_mfma_f32_16x16x32_bf16 v[104:107], v[160:163], v[216:219], v[104:107]
	v_mfma_f32_16x16x32_bf16 v[100:103], v[152:155], v[224:227], v[100:103]
	v_mfma_f32_16x16x32_bf16 v[96:99], v[160:163], v[224:227], v[96:99]
	v_mfma_f32_16x16x32_bf16 v[124:127], v[156:159], v[204:207], v[124:127]
	v_mfma_f32_16x16x32_bf16 v[120:123], v[164:167], v[204:207], v[120:123]
	v_mfma_f32_16x16x32_bf16 v[116:119], v[156:159], v[212:215], v[116:119]
	v_mfma_f32_16x16x32_bf16 v[112:115], v[164:167], v[212:215], v[112:115]
	v_mfma_f32_16x16x32_bf16 v[108:111], v[156:159], v[220:223], v[108:111]
	v_mfma_f32_16x16x32_bf16 v[104:107], v[164:167], v[220:223], v[104:107]
	v_mfma_f32_16x16x32_bf16 v[100:103], v[156:159], v[228:231], v[100:103]
	v_mfma_f32_16x16x32_bf16 v[96:99], v[164:167], v[228:231], v[96:99]
	s_setprio 0
	s_barrier
	v_lshl_add_u64 v[188:189], s[48:49], 0, v[142:143]
	s_mov_b64 s[38:39], 0x156c0100
	v_lshl_add_u64 v[190:191], v[188:189], 0, s[38:39]
	v_readfirstlane_b32 s38, v128
	s_mov_b32 m0, s38
	s_mov_b64 s[38:39], 0x15718100
	ds_read_b128 v[232:235], v201
	ds_read_b128 v[236:239], v201 offset:1024
	ds_read_b128 v[240:243], v201 offset:2048
	ds_read_b128 v[244:247], v201 offset:3072
	global_load_lds_dwordx4 v[190:191], off
	v_lshl_add_u64 v[190:191], v[188:189], 0, s[38:39]
	v_readfirstlane_b32 s38, v129
	s_mov_b32 m0, s38
	s_nop 0
	global_load_lds_dwordx4 v[190:191], off
	s_waitcnt vmcnt(10)
	s_barrier
	s_waitcnt lgkmcnt(0)
	s_setprio 1
	s_waitcnt lgkmcnt(0)
	v_mfma_f32_16x16x32_bf16 v[92:95], v[232:235], v[168:171], v[92:95]
	v_mfma_f32_16x16x32_bf16 v[88:91], v[240:243], v[168:171], v[88:91]
	v_mfma_f32_16x16x32_bf16 v[84:87], v[232:235], v[208:211], v[84:87]
	v_mfma_f32_16x16x32_bf16 v[80:83], v[240:243], v[208:211], v[80:83]
	v_mfma_f32_16x16x32_bf16 v[76:79], v[232:235], v[216:219], v[76:79]
	v_mfma_f32_16x16x32_bf16 v[72:75], v[240:243], v[216:219], v[72:75]
	v_mfma_f32_16x16x32_bf16 v[68:71], v[232:235], v[224:227], v[68:71]
	v_mfma_f32_16x16x32_bf16 v[64:67], v[240:243], v[224:227], v[64:67]
	v_mfma_f32_16x16x32_bf16 v[92:95], v[236:239], v[204:207], v[92:95]
	v_mfma_f32_16x16x32_bf16 v[88:91], v[244:247], v[204:207], v[88:91]
	v_mfma_f32_16x16x32_bf16 v[84:87], v[236:239], v[212:215], v[84:87]
	v_mfma_f32_16x16x32_bf16 v[80:83], v[244:247], v[212:215], v[80:83]
	v_mfma_f32_16x16x32_bf16 v[76:79], v[236:239], v[220:223], v[76:79]
	v_mfma_f32_16x16x32_bf16 v[72:75], v[244:247], v[220:223], v[72:75]
	v_mfma_f32_16x16x32_bf16 v[68:71], v[236:239], v[228:231], v[68:71]
	v_mfma_f32_16x16x32_bf16 v[64:67], v[244:247], v[228:231], v[64:67]
	s_setprio 0
	v_readfirstlane_b32 s38, v130
	v_lshl_add_u64 v[190:191], v[172:173], 0, s[26:27]
	s_mov_b32 m0, s38
	s_mov_b64 s[38:39], 0x58100
	s_barrier
	ds_read_b128 v[168:171], v197 offset:16384
	ds_read_b128 v[204:207], v197 offset:17408
	ds_read_b128 v[208:211], v198 offset:16384
	ds_read_b128 v[212:215], v198 offset:17408
	ds_read_b128 v[216:219], v199 offset:16384
	ds_read_b128 v[220:223], v199 offset:17408
	ds_read_b128 v[224:227], v200 offset:16384
	ds_read_b128 v[228:231], v200 offset:17408
	global_load_lds_dwordx4 v[190:191], off
	v_lshl_add_u64 v[190:191], v[172:173], 0, s[38:39]
	v_readfirstlane_b32 s38, v131
	s_mov_b32 m0, s38
	s_nop 0
	global_load_lds_dwordx4 v[190:191], off
	s_barrier
	s_waitcnt lgkmcnt(0)
	s_setprio 1
	s_waitcnt lgkmcnt(0)
	v_mfma_f32_16x16x32_bf16 v[60:63], v[152:155], v[168:171], v[60:63]
	v_mfma_f32_16x16x32_bf16 v[56:59], v[160:163], v[168:171], v[56:59]
	v_mfma_f32_16x16x32_bf16 v[52:55], v[152:155], v[208:211], v[52:55]
	v_mfma_f32_16x16x32_bf16 v[48:51], v[160:163], v[208:211], v[48:51]
	v_mfma_f32_16x16x32_bf16 v[44:47], v[152:155], v[216:219], v[44:47]
	v_mfma_f32_16x16x32_bf16 v[40:43], v[160:163], v[216:219], v[40:43]
	v_mfma_f32_16x16x32_bf16 v[36:39], v[152:155], v[224:227], v[36:39]
	v_mfma_f32_16x16x32_bf16 v[32:35], v[160:163], v[224:227], v[32:35]
	v_mfma_f32_16x16x32_bf16 v[60:63], v[156:159], v[204:207], v[60:63]
	v_mfma_f32_16x16x32_bf16 v[56:59], v[164:167], v[204:207], v[56:59]
	v_mfma_f32_16x16x32_bf16 v[52:55], v[156:159], v[212:215], v[52:55]
	v_mfma_f32_16x16x32_bf16 v[48:51], v[164:167], v[212:215], v[48:51]
	v_mfma_f32_16x16x32_bf16 v[44:47], v[156:159], v[220:223], v[44:47]
	v_mfma_f32_16x16x32_bf16 v[40:43], v[164:167], v[220:223], v[40:43]
	v_mfma_f32_16x16x32_bf16 v[36:39], v[156:159], v[228:231], v[36:39]
	v_mfma_f32_16x16x32_bf16 v[32:35], v[164:167], v[228:231], v[32:35]
	s_setprio 0
	s_barrier
	s_mov_b64 s[38:39], 0x15770100
	v_lshl_add_u64 v[152:153], v[188:189], 0, s[38:39]
	v_readfirstlane_b32 s38, v132
	s_mov_b32 m0, s38
	s_mov_b64 s[38:39], 0x157c8100
	global_load_lds_dwordx4 v[152:153], off
	v_lshl_add_u64 v[152:153], v[188:189], 0, s[38:39]
	v_readfirstlane_b32 s38, v133
	s_mov_b32 m0, s38
	s_nop 0
	global_load_lds_dwordx4 v[152:153], off
	s_waitcnt vmcnt(10)
	s_barrier
	s_setprio 1
	v_mfma_f32_16x16x32_bf16 v[28:31], v[232:235], v[168:171], v[28:31]
	v_mfma_f32_16x16x32_bf16 v[24:27], v[240:243], v[168:171], v[24:27]
	v_mfma_f32_16x16x32_bf16 v[20:23], v[232:235], v[208:211], v[20:23]
	v_mfma_f32_16x16x32_bf16 v[16:19], v[240:243], v[208:211], v[16:19]
	v_mfma_f32_16x16x32_bf16 v[12:15], v[232:235], v[216:219], v[12:15]
	v_mfma_f32_16x16x32_bf16 v[8:11], v[240:243], v[216:219], v[8:11]
	v_mfma_f32_16x16x32_bf16 v[4:7], v[232:235], v[224:227], v[4:7]
	v_mfma_f32_16x16x32_bf16 v[0:3], v[240:243], v[224:227], v[0:3]
	v_mfma_f32_16x16x32_bf16 v[28:31], v[236:239], v[204:207], v[28:31]
	v_mfma_f32_16x16x32_bf16 v[24:27], v[244:247], v[204:207], v[24:27]
	v_mfma_f32_16x16x32_bf16 v[20:23], v[236:239], v[212:215], v[20:23]
	v_mfma_f32_16x16x32_bf16 v[16:19], v[244:247], v[212:215], v[16:19]
	v_mfma_f32_16x16x32_bf16 v[12:15], v[236:239], v[220:223], v[12:15]
	v_mfma_f32_16x16x32_bf16 v[8:11], v[244:247], v[220:223], v[8:11]
	v_mfma_f32_16x16x32_bf16 v[4:7], v[236:239], v[228:231], v[4:7]
	v_mfma_f32_16x16x32_bf16 v[0:3], v[244:247], v[228:231], v[0:3]
	s_setprio 0
	s_barrier
	ds_read_b128 v[152:155], v202
	ds_read_b128 v[156:159], v202 offset:1024
	ds_read_b128 v[160:163], v202 offset:2048
	ds_read_b128 v[164:167], v202 offset:3072
	s_mov_b64 s[38:39], 0xb0100
	v_lshl_add_u64 v[190:191], v[172:173], 0, s[38:39]
	v_readfirstlane_b32 s38, v134
	s_mov_b32 m0, s38
	s_mov_b64 s[38:39], 0x108100
	ds_read_b128 v[168:171], v197 offset:32768
	ds_read_b128 v[204:207], v197 offset:33792
	ds_read_b128 v[208:211], v198 offset:32768
	ds_read_b128 v[212:215], v198 offset:33792
	ds_read_b128 v[216:219], v199 offset:32768
	ds_read_b128 v[220:223], v199 offset:33792
	ds_read_b128 v[224:227], v200 offset:32768
	ds_read_b128 v[228:231], v200 offset:33792
	global_load_lds_dwordx4 v[190:191], off
	v_lshl_add_u64 v[190:191], v[172:173], 0, s[38:39]
	v_readfirstlane_b32 s38, v135
	s_mov_b32 m0, s38
	s_nop 0
	global_load_lds_dwordx4 v[190:191], off
	s_waitcnt lgkmcnt(8)
	s_waitcnt vmcnt(10)
	s_barrier
	s_waitcnt lgkmcnt(0)
	s_setprio 1
	s_waitcnt lgkmcnt(0)
	v_mfma_f32_16x16x32_bf16 v[124:127], v[152:155], v[168:171], v[124:127]
	v_mfma_f32_16x16x32_bf16 v[120:123], v[160:163], v[168:171], v[120:123]
	v_mfma_f32_16x16x32_bf16 v[116:119], v[152:155], v[208:211], v[116:119]
	v_mfma_f32_16x16x32_bf16 v[112:115], v[160:163], v[208:211], v[112:115]
	v_mfma_f32_16x16x32_bf16 v[108:111], v[152:155], v[216:219], v[108:111]
	v_mfma_f32_16x16x32_bf16 v[104:107], v[160:163], v[216:219], v[104:107]
	v_mfma_f32_16x16x32_bf16 v[100:103], v[152:155], v[224:227], v[100:103]
	v_mfma_f32_16x16x32_bf16 v[96:99], v[160:163], v[224:227], v[96:99]
	v_mfma_f32_16x16x32_bf16 v[124:127], v[156:159], v[204:207], v[124:127]
	v_mfma_f32_16x16x32_bf16 v[120:123], v[164:167], v[204:207], v[120:123]
	v_mfma_f32_16x16x32_bf16 v[116:119], v[156:159], v[212:215], v[116:119]
	v_mfma_f32_16x16x32_bf16 v[112:115], v[164:167], v[212:215], v[112:115]
	v_mfma_f32_16x16x32_bf16 v[108:111], v[156:159], v[220:223], v[108:111]
	v_mfma_f32_16x16x32_bf16 v[104:107], v[164:167], v[220:223], v[104:107]
	v_mfma_f32_16x16x32_bf16 v[100:103], v[156:159], v[228:231], v[100:103]
	v_mfma_f32_16x16x32_bf16 v[96:99], v[164:167], v[228:231], v[96:99]
	s_setprio 0
	s_barrier
	s_mov_b64 s[38:39], 0x156c0180
	v_lshl_add_u64 v[190:191], v[188:189], 0, s[38:39]
	v_readfirstlane_b32 s38, v144
	s_mov_b32 m0, s38
	s_mov_b64 s[38:39], 0x15718180
	ds_read_b128 v[232:235], v203
	ds_read_b128 v[236:239], v203 offset:1024
	ds_read_b128 v[240:243], v203 offset:2048
	ds_read_b128 v[244:247], v203 offset:3072
	global_load_lds_dwordx4 v[190:191], off
	v_lshl_add_u64 v[190:191], v[188:189], 0, s[38:39]
	v_readfirstlane_b32 s38, v145
	s_mov_b32 m0, s38
	s_nop 0
	global_load_lds_dwordx4 v[190:191], off
	s_waitcnt vmcnt(10)
	s_barrier
	s_waitcnt lgkmcnt(0)
	s_setprio 1
	s_waitcnt lgkmcnt(0)
	v_mfma_f32_16x16x32_bf16 v[92:95], v[232:235], v[168:171], v[92:95]
	v_mfma_f32_16x16x32_bf16 v[88:91], v[240:243], v[168:171], v[88:91]
	v_mfma_f32_16x16x32_bf16 v[84:87], v[232:235], v[208:211], v[84:87]
	v_mfma_f32_16x16x32_bf16 v[80:83], v[240:243], v[208:211], v[80:83]
	v_mfma_f32_16x16x32_bf16 v[76:79], v[232:235], v[216:219], v[76:79]
	v_mfma_f32_16x16x32_bf16 v[72:75], v[240:243], v[216:219], v[72:75]
	v_mfma_f32_16x16x32_bf16 v[68:71], v[232:235], v[224:227], v[68:71]
	v_mfma_f32_16x16x32_bf16 v[64:67], v[240:243], v[224:227], v[64:67]
	v_mfma_f32_16x16x32_bf16 v[92:95], v[236:239], v[204:207], v[92:95]
	v_mfma_f32_16x16x32_bf16 v[88:91], v[244:247], v[204:207], v[88:91]
	v_mfma_f32_16x16x32_bf16 v[84:87], v[236:239], v[212:215], v[84:87]
	v_mfma_f32_16x16x32_bf16 v[80:83], v[244:247], v[212:215], v[80:83]
	v_mfma_f32_16x16x32_bf16 v[76:79], v[236:239], v[220:223], v[76:79]
	v_mfma_f32_16x16x32_bf16 v[72:75], v[244:247], v[220:223], v[72:75]
	v_mfma_f32_16x16x32_bf16 v[68:71], v[236:239], v[228:231], v[68:71]
	v_mfma_f32_16x16x32_bf16 v[64:67], v[244:247], v[228:231], v[64:67]
	s_setprio 0
	v_readfirstlane_b32 s38, v146
	s_mov_b32 m0, s38
	s_mov_b64 s[38:39], 0x58180
	v_lshl_add_u64 v[190:191], v[172:173], 0, s[8:9]
	v_lshl_add_u64 v[172:173], v[172:173], 0, s[38:39]
	v_readfirstlane_b32 s38, v147
	s_barrier
	ds_read_b128 v[168:171], v197 offset:49152
	ds_read_b128 v[204:207], v197 offset:50176
	ds_read_b128 v[208:211], v198 offset:49152
	ds_read_b128 v[212:215], v198 offset:50176
	ds_read_b128 v[216:219], v199 offset:49152
	ds_read_b128 v[220:223], v199 offset:50176
	ds_read_b128 v[224:227], v200 offset:49152
	ds_read_b128 v[228:231], v200 offset:50176
	global_load_lds_dwordx4 v[190:191], off
	s_mov_b32 m0, s38
	s_nop 0
	global_load_lds_dwordx4 v[172:173], off
	s_barrier
	s_waitcnt lgkmcnt(0)
	s_setprio 1
	s_waitcnt lgkmcnt(0)
	v_mfma_f32_16x16x32_bf16 v[60:63], v[152:155], v[168:171], v[60:63]
	v_mfma_f32_16x16x32_bf16 v[56:59], v[160:163], v[168:171], v[56:59]
	v_mfma_f32_16x16x32_bf16 v[52:55], v[152:155], v[208:211], v[52:55]
	v_mfma_f32_16x16x32_bf16 v[48:51], v[160:163], v[208:211], v[48:51]
	v_mfma_f32_16x16x32_bf16 v[44:47], v[152:155], v[216:219], v[44:47]
	v_mfma_f32_16x16x32_bf16 v[40:43], v[160:163], v[216:219], v[40:43]
	v_mfma_f32_16x16x32_bf16 v[36:39], v[152:155], v[224:227], v[36:39]
	v_mfma_f32_16x16x32_bf16 v[32:35], v[160:163], v[224:227], v[32:35]
	v_mfma_f32_16x16x32_bf16 v[60:63], v[156:159], v[204:207], v[60:63]
	v_mfma_f32_16x16x32_bf16 v[56:59], v[164:167], v[204:207], v[56:59]
	v_mfma_f32_16x16x32_bf16 v[52:55], v[156:159], v[212:215], v[52:55]
	v_mfma_f32_16x16x32_bf16 v[48:51], v[164:167], v[212:215], v[48:51]
	v_mfma_f32_16x16x32_bf16 v[44:47], v[156:159], v[220:223], v[44:47]
	v_mfma_f32_16x16x32_bf16 v[40:43], v[164:167], v[220:223], v[40:43]
	v_mfma_f32_16x16x32_bf16 v[36:39], v[156:159], v[228:231], v[36:39]
	v_mfma_f32_16x16x32_bf16 v[32:35], v[164:167], v[228:231], v[32:35]
	s_setprio 0
	s_barrier
	s_mov_b64 s[38:39], 0x15770180
	v_lshl_add_u64 v[152:153], v[188:189], 0, s[38:39]
	v_readfirstlane_b32 s38, v148
	s_mov_b32 m0, s38
	s_mov_b64 s[38:39], 0x157c8180
	global_load_lds_dwordx4 v[152:153], off
	v_lshl_add_u64 v[152:153], v[188:189], 0, s[38:39]
	v_readfirstlane_b32 s38, v149
	s_mov_b32 m0, s38
	s_nop 0
	global_load_lds_dwordx4 v[152:153], off
	s_waitcnt vmcnt(10)
	s_barrier
	s_setprio 1
	v_mfma_f32_16x16x32_bf16 v[28:31], v[232:235], v[168:171], v[28:31]
	v_mfma_f32_16x16x32_bf16 v[24:27], v[240:243], v[168:171], v[24:27]
	v_mfma_f32_16x16x32_bf16 v[20:23], v[232:235], v[208:211], v[20:23]
	v_mfma_f32_16x16x32_bf16 v[16:19], v[240:243], v[208:211], v[16:19]
	v_mfma_f32_16x16x32_bf16 v[12:15], v[232:235], v[216:219], v[12:15]
	v_mfma_f32_16x16x32_bf16 v[8:11], v[240:243], v[216:219], v[8:11]
	v_mfma_f32_16x16x32_bf16 v[4:7], v[232:235], v[224:227], v[4:7]
	v_mfma_f32_16x16x32_bf16 v[0:3], v[240:243], v[224:227], v[0:3]
	v_mfma_f32_16x16x32_bf16 v[28:31], v[236:239], v[204:207], v[28:31]
	v_mfma_f32_16x16x32_bf16 v[24:27], v[244:247], v[204:207], v[24:27]
	v_mfma_f32_16x16x32_bf16 v[20:23], v[236:239], v[212:215], v[20:23]
	v_mfma_f32_16x16x32_bf16 v[16:19], v[244:247], v[212:215], v[16:19]
	v_mfma_f32_16x16x32_bf16 v[12:15], v[236:239], v[220:223], v[12:15]
	v_mfma_f32_16x16x32_bf16 v[8:11], v[244:247], v[220:223], v[8:11]
	v_mfma_f32_16x16x32_bf16 v[4:7], v[236:239], v[228:231], v[4:7]
	v_mfma_f32_16x16x32_bf16 v[0:3], v[244:247], v[228:231], v[0:3]
	s_setprio 0
	s_add_i32 s35, s35, 2
	s_add_u32 s48, s48, 0x100
	s_addc_u32 s49, s49, 0
	s_add_u32 s70, s70, 0x100
	s_addc_u32 s71, s71, 0
	s_cmp_gt_u32 s35, 39
	s_barrier
	s_cbranch_scc0 .LBB0_109
	v_lshl_add_u64 v[148:149], v[136:137], 1, s[44:45]
	s_mov_b64 s[38:39], 0x1580
	v_readfirstlane_b32 s35, v150
	v_lshl_add_u64 v[172:173], v[148:149], 0, s[38:39]
	s_mov_b32 m0, s35
	s_mov_b64 s[38:39], 0x59580
	v_readfirstlane_b32 s35, v151
	ds_read_b128 v[128:131], v196
	ds_read_b128 v[132:135], v196 offset:1024
	ds_read_b128 v[144:147], v196 offset:2048
	ds_read_b128 v[152:155], v196 offset:3072
	ds_read_b128 v[156:159], v197
	ds_read_b128 v[160:163], v197 offset:1024
	ds_read_b128 v[164:167], v198
	ds_read_b128 v[168:171], v198 offset:1024
	ds_read_b128 v[204:207], v199
	ds_read_b128 v[208:211], v199 offset:1024
	ds_read_b128 v[212:215], v200
	ds_read_b128 v[216:219], v200 offset:1024
	global_load_lds_dwordx4 v[172:173], off
	v_lshl_add_u64 v[148:149], v[148:149], 0, s[38:39]
	s_mov_b32 m0, s35
	s_nop 0
	global_load_lds_dwordx4 v[148:149], off
	s_waitcnt vmcnt(10)
	s_barrier
	s_waitcnt lgkmcnt(0)
	s_setprio 1
	s_waitcnt lgkmcnt(0)
	v_mfma_f32_16x16x32_bf16 v[124:127], v[128:131], v[156:159], v[124:127]
	v_mfma_f32_16x16x32_bf16 v[120:123], v[144:147], v[156:159], v[120:123]
	v_mfma_f32_16x16x32_bf16 v[116:119], v[128:131], v[164:167], v[116:119]
	v_mfma_f32_16x16x32_bf16 v[104:107], v[144:147], v[204:207], v[104:107]
	v_mfma_f32_16x16x32_bf16 v[100:103], v[128:131], v[212:215], v[100:103]
	v_mfma_f32_16x16x32_bf16 v[96:99], v[144:147], v[212:215], v[96:99]
	v_mfma_f32_16x16x32_bf16 v[124:127], v[132:135], v[160:163], v[124:127]
	v_mfma_f32_16x16x32_bf16 v[120:123], v[152:155], v[160:163], v[120:123]
	v_mfma_f32_16x16x32_bf16 v[116:119], v[132:135], v[168:171], v[116:119]
	v_mfma_f32_16x16x32_bf16 v[112:115], v[144:147], v[164:167], v[112:115]
	v_mfma_f32_16x16x32_bf16 v[108:111], v[128:131], v[204:207], v[108:111]
	v_mfma_f32_16x16x32_bf16 v[104:107], v[152:155], v[208:211], v[104:107]
	v_mfma_f32_16x16x32_bf16 v[100:103], v[132:135], v[216:219], v[100:103]
	v_mfma_f32_16x16x32_bf16 v[96:99], v[152:155], v[216:219], v[96:99]
	v_mfma_f32_16x16x32_bf16 v[112:115], v[152:155], v[168:171], v[112:115]
	v_mfma_f32_16x16x32_bf16 v[108:111], v[132:135], v[208:211], v[108:111]
	s_setprio 0
	s_barrier
	ds_read_b128 v[148:151], v201
	ds_read_b128 v[220:223], v201 offset:1024
	ds_read_b128 v[224:227], v201 offset:2048
	ds_read_b128 v[228:231], v201 offset:3072
	s_waitcnt vmcnt(8)
	s_barrier
	s_waitcnt lgkmcnt(0)
	s_setprio 1
	s_waitcnt lgkmcnt(0)
	v_mfma_f32_16x16x32_bf16 v[92:95], v[148:151], v[156:159], v[92:95]
	v_mfma_f32_16x16x32_bf16 v[88:91], v[224:227], v[156:159], v[88:91]
	v_mfma_f32_16x16x32_bf16 v[84:87], v[148:151], v[164:167], v[84:87]
	v_mfma_f32_16x16x32_bf16 v[80:83], v[224:227], v[164:167], v[80:83]
	v_mfma_f32_16x16x32_bf16 v[76:79], v[148:151], v[204:207], v[76:79]
	v_mfma_f32_16x16x32_bf16 v[72:75], v[224:227], v[204:207], v[72:75]
	v_mfma_f32_16x16x32_bf16 v[68:71], v[148:151], v[212:215], v[68:71]
	v_mfma_f32_16x16x32_bf16 v[64:67], v[224:227], v[212:215], v[64:67]
	v_mfma_f32_16x16x32_bf16 v[92:95], v[220:223], v[160:163], v[92:95]
	v_mfma_f32_16x16x32_bf16 v[88:91], v[228:231], v[160:163], v[88:91]
	v_mfma_f32_16x16x32_bf16 v[84:87], v[220:223], v[168:171], v[84:87]
	v_mfma_f32_16x16x32_bf16 v[80:83], v[228:231], v[168:171], v[80:83]
	v_mfma_f32_16x16x32_bf16 v[76:79], v[220:223], v[208:211], v[76:79]
	v_mfma_f32_16x16x32_bf16 v[72:75], v[228:231], v[208:211], v[72:75]
	v_mfma_f32_16x16x32_bf16 v[68:71], v[220:223], v[216:219], v[68:71]
	v_mfma_f32_16x16x32_bf16 v[64:67], v[228:231], v[216:219], v[64:67]
	s_setprio 0
	s_barrier
	ds_read_b128 v[156:159], v197 offset:16384
	ds_read_b128 v[160:163], v197 offset:17408
	ds_read_b128 v[164:167], v198 offset:16384
	ds_read_b128 v[168:171], v198 offset:17408
	ds_read_b128 v[204:207], v199 offset:16384
	ds_read_b128 v[208:211], v199 offset:17408
	ds_read_b128 v[212:215], v200 offset:16384
	ds_read_b128 v[216:219], v200 offset:17408
	s_waitcnt vmcnt(4)
	s_barrier
	s_waitcnt lgkmcnt(0)
	s_setprio 1
	s_waitcnt lgkmcnt(0)
	v_mfma_f32_16x16x32_bf16 v[60:63], v[128:131], v[156:159], v[60:63]
	v_mfma_f32_16x16x32_bf16 v[56:59], v[144:147], v[156:159], v[56:59]
	v_mfma_f32_16x16x32_bf16 v[52:55], v[128:131], v[164:167], v[52:55]
	v_mfma_f32_16x16x32_bf16 v[48:51], v[144:147], v[164:167], v[48:51]
	v_mfma_f32_16x16x32_bf16 v[44:47], v[128:131], v[204:207], v[44:47]
	v_mfma_f32_16x16x32_bf16 v[40:43], v[144:147], v[204:207], v[40:43]
	v_mfma_f32_16x16x32_bf16 v[36:39], v[128:131], v[212:215], v[36:39]
	v_mfma_f32_16x16x32_bf16 v[32:35], v[144:147], v[212:215], v[32:35]
	v_mfma_f32_16x16x32_bf16 v[60:63], v[132:135], v[160:163], v[60:63]
	v_mfma_f32_16x16x32_bf16 v[56:59], v[152:155], v[160:163], v[56:59]
	v_mfma_f32_16x16x32_bf16 v[52:55], v[132:135], v[168:171], v[52:55]
	v_mfma_f32_16x16x32_bf16 v[48:51], v[152:155], v[168:171], v[48:51]
	v_mfma_f32_16x16x32_bf16 v[44:47], v[132:135], v[208:211], v[44:47]
	v_mfma_f32_16x16x32_bf16 v[40:43], v[152:155], v[208:211], v[40:43]
	v_mfma_f32_16x16x32_bf16 v[36:39], v[132:135], v[216:219], v[36:39]
	v_mfma_f32_16x16x32_bf16 v[32:35], v[152:155], v[216:219], v[32:35]
	s_setprio 0
	s_setprio 1
	v_mfma_f32_16x16x32_bf16 v[28:31], v[148:151], v[156:159], v[28:31]
	v_mfma_f32_16x16x32_bf16 v[24:27], v[224:227], v[156:159], v[24:27]
	v_mfma_f32_16x16x32_bf16 v[20:23], v[148:151], v[164:167], v[20:23]
	v_mfma_f32_16x16x32_bf16 v[16:19], v[224:227], v[164:167], v[16:19]
	v_mfma_f32_16x16x32_bf16 v[12:15], v[148:151], v[204:207], v[12:15]
	v_mfma_f32_16x16x32_bf16 v[8:11], v[224:227], v[204:207], v[8:11]
	v_mfma_f32_16x16x32_bf16 v[4:7], v[148:151], v[212:215], v[4:7]
	v_mfma_f32_16x16x32_bf16 v[0:3], v[224:227], v[212:215], v[0:3]
	v_mfma_f32_16x16x32_bf16 v[28:31], v[220:223], v[160:163], v[28:31]
	v_mfma_f32_16x16x32_bf16 v[24:27], v[228:231], v[160:163], v[24:27]
	v_mfma_f32_16x16x32_bf16 v[20:23], v[220:223], v[168:171], v[20:23]
	v_mfma_f32_16x16x32_bf16 v[16:19], v[228:231], v[168:171], v[16:19]
	v_mfma_f32_16x16x32_bf16 v[12:15], v[220:223], v[208:211], v[12:15]
	v_mfma_f32_16x16x32_bf16 v[8:11], v[228:231], v[208:211], v[8:11]
	v_mfma_f32_16x16x32_bf16 v[4:7], v[220:223], v[216:219], v[4:7]
	v_mfma_f32_16x16x32_bf16 v[0:3], v[228:231], v[216:219], v[0:3]
	s_setprio 0
	s_barrier
	ds_read_b128 v[144:147], v202
	ds_read_b128 v[148:151], v202 offset:1024
	ds_read_b128 v[152:155], v202 offset:2048
	ds_read_b128 v[156:159], v202 offset:3072
	ds_read_b128 v[160:163], v197 offset:32768
	ds_read_b128 v[164:167], v197 offset:33792
	ds_read_b128 v[168:171], v198 offset:32768
	ds_read_b128 v[204:207], v198 offset:33792
	ds_read_b128 v[208:211], v199 offset:32768
	ds_read_b128 v[212:215], v199 offset:33792
	ds_read_b128 v[216:219], v200 offset:32768
	ds_read_b128 v[220:223], v200 offset:33792
	s_waitcnt vmcnt(2)
	s_barrier
	s_waitcnt lgkmcnt(0)
	s_setprio 1
	s_waitcnt lgkmcnt(0)
	v_mfma_f32_16x16x32_bf16 v[124:127], v[144:147], v[160:163], v[124:127]
	v_mfma_f32_16x16x32_bf16 v[120:123], v[152:155], v[160:163], v[120:123]
	v_mfma_f32_16x16x32_bf16 v[116:119], v[144:147], v[168:171], v[116:119]
	v_mfma_f32_16x16x32_bf16 v[112:115], v[152:155], v[168:171], v[112:115]
	v_mfma_f32_16x16x32_bf16 v[108:111], v[144:147], v[208:211], v[108:111]
	v_mfma_f32_16x16x32_bf16 v[104:107], v[152:155], v[208:211], v[104:107]
	v_mfma_f32_16x16x32_bf16 v[100:103], v[144:147], v[216:219], v[100:103]
	v_mfma_f32_16x16x32_bf16 v[96:99], v[152:155], v[216:219], v[96:99]
	v_mfma_f32_16x16x32_bf16 v[132:135], v[148:151], v[164:167], v[124:127]
	v_mfma_f32_16x16x32_bf16 v[128:131], v[156:159], v[164:167], v[120:123]
	v_mfma_f32_16x16x32_bf16 v[124:127], v[148:151], v[204:207], v[116:119]
	v_mfma_f32_16x16x32_bf16 v[120:123], v[156:159], v[204:207], v[112:115]
	v_mfma_f32_16x16x32_bf16 v[116:119], v[148:151], v[212:215], v[108:111]
	v_mfma_f32_16x16x32_bf16 v[104:107], v[156:159], v[212:215], v[104:107]
	v_mfma_f32_16x16x32_bf16 v[100:103], v[148:151], v[220:223], v[100:103]
	v_mfma_f32_16x16x32_bf16 v[96:99], v[156:159], v[220:223], v[96:99]
	s_setprio 0
	s_barrier
	ds_read_b128 v[108:111], v203
	ds_read_b128 v[112:115], v203 offset:1024
	ds_read_b128 v[224:227], v203 offset:2048
	ds_read_b128 v[228:231], v203 offset:3072
	s_waitcnt vmcnt(0)
	s_barrier
	s_waitcnt lgkmcnt(0)
	s_setprio 1
	s_waitcnt lgkmcnt(0)
	v_mfma_f32_16x16x32_bf16 v[92:95], v[108:111], v[160:163], v[92:95]
	v_mfma_f32_16x16x32_bf16 v[88:91], v[224:227], v[160:163], v[88:91]
	v_mfma_f32_16x16x32_bf16 v[84:87], v[108:111], v[168:171], v[84:87]
	v_mfma_f32_16x16x32_bf16 v[80:83], v[224:227], v[168:171], v[80:83]
	v_mfma_f32_16x16x32_bf16 v[76:79], v[108:111], v[208:211], v[76:79]
	v_mfma_f32_16x16x32_bf16 v[72:75], v[224:227], v[208:211], v[72:75]
	v_mfma_f32_16x16x32_bf16 v[68:71], v[108:111], v[216:219], v[68:71]
	v_mfma_f32_16x16x32_bf16 v[64:67], v[224:227], v[216:219], v[64:67]
	v_mfma_f32_16x16x32_bf16 v[92:95], v[112:115], v[164:167], v[92:95]
	v_mfma_f32_16x16x32_bf16 v[88:91], v[228:231], v[164:167], v[88:91]
	v_mfma_f32_16x16x32_bf16 v[84:87], v[112:115], v[204:207], v[84:87]
	v_mfma_f32_16x16x32_bf16 v[80:83], v[228:231], v[204:207], v[80:83]
	v_mfma_f32_16x16x32_bf16 v[76:79], v[112:115], v[212:215], v[76:79]
	v_mfma_f32_16x16x32_bf16 v[72:75], v[228:231], v[212:215], v[72:75]
	v_mfma_f32_16x16x32_bf16 v[68:71], v[112:115], v[220:223], v[68:71]
	v_mfma_f32_16x16x32_bf16 v[64:67], v[228:231], v[220:223], v[64:67]
	s_setprio 0
	s_barrier
	ds_read_b128 v[160:163], v197 offset:49152
	ds_read_b128 v[164:167], v197 offset:50176
	ds_read_b128 v[168:171], v198 offset:49152
	ds_read_b128 v[204:207], v198 offset:50176
	ds_read_b128 v[208:211], v199 offset:49152
	ds_read_b128 v[212:215], v199 offset:50176
	ds_read_b128 v[216:219], v200 offset:49152
	ds_read_b128 v[220:223], v200 offset:50176
	s_barrier
	s_waitcnt lgkmcnt(0)
	s_setprio 1
	s_waitcnt lgkmcnt(0)
	v_mfma_f32_16x16x32_bf16 v[60:63], v[144:147], v[160:163], v[60:63]
	v_mfma_f32_16x16x32_bf16 v[56:59], v[152:155], v[160:163], v[56:59]
	v_mfma_f32_16x16x32_bf16 v[52:55], v[144:147], v[168:171], v[52:55]
	v_mfma_f32_16x16x32_bf16 v[48:51], v[152:155], v[168:171], v[48:51]
	v_mfma_f32_16x16x32_bf16 v[44:47], v[144:147], v[208:211], v[44:47]
	v_mfma_f32_16x16x32_bf16 v[40:43], v[152:155], v[208:211], v[40:43]
	v_mfma_f32_16x16x32_bf16 v[36:39], v[144:147], v[216:219], v[36:39]
	v_mfma_f32_16x16x32_bf16 v[32:35], v[152:155], v[216:219], v[32:35]
	v_mfma_f32_16x16x32_bf16 v[60:63], v[148:151], v[164:167], v[60:63]
	v_mfma_f32_16x16x32_bf16 v[56:59], v[156:159], v[164:167], v[56:59]
	v_mfma_f32_16x16x32_bf16 v[52:55], v[148:151], v[204:207], v[52:55]
	v_mfma_f32_16x16x32_bf16 v[48:51], v[156:159], v[204:207], v[48:51]
	v_mfma_f32_16x16x32_bf16 v[44:47], v[148:151], v[212:215], v[44:47]
	v_mfma_f32_16x16x32_bf16 v[40:43], v[156:159], v[212:215], v[40:43]
	v_mfma_f32_16x16x32_bf16 v[36:39], v[148:151], v[220:223], v[36:39]
	v_mfma_f32_16x16x32_bf16 v[32:35], v[156:159], v[220:223], v[32:35]
	s_setprio 0
	s_setprio 1
	v_mfma_f32_16x16x32_bf16 v[28:31], v[108:111], v[160:163], v[28:31]
	v_mfma_f32_16x16x32_bf16 v[24:27], v[224:227], v[160:163], v[24:27]
	v_mfma_f32_16x16x32_bf16 v[20:23], v[108:111], v[168:171], v[20:23]
	v_mfma_f32_16x16x32_bf16 v[16:19], v[224:227], v[168:171], v[16:19]
	v_mfma_f32_16x16x32_bf16 v[12:15], v[108:111], v[208:211], v[12:15]
	v_mfma_f32_16x16x32_bf16 v[8:11], v[224:227], v[208:211], v[8:11]
	v_mfma_f32_16x16x32_bf16 v[4:7], v[108:111], v[216:219], v[4:7]
	v_mfma_f32_16x16x32_bf16 v[0:3], v[224:227], v[216:219], v[0:3]
	v_mfma_f32_16x16x32_bf16 v[28:31], v[112:115], v[164:167], v[28:31]
	v_mfma_f32_16x16x32_bf16 v[24:27], v[228:231], v[164:167], v[24:27]
	v_mfma_f32_16x16x32_bf16 v[20:23], v[112:115], v[204:207], v[20:23]
	v_mfma_f32_16x16x32_bf16 v[16:19], v[228:231], v[204:207], v[16:19]
	v_mfma_f32_16x16x32_bf16 v[12:15], v[112:115], v[212:215], v[12:15]
	v_mfma_f32_16x16x32_bf16 v[8:11], v[228:231], v[212:215], v[8:11]
	v_mfma_f32_16x16x32_bf16 v[4:7], v[112:115], v[220:223], v[4:7]
	v_mfma_f32_16x16x32_bf16 v[0:3], v[228:231], v[220:223], v[0:3]
	s_setprio 0
	s_barrier
	s_and_saveexec_b64 s[44:45], s[40:41]
	s_cbranch_execz .LBB0_105
	s_barrier
	s_branch .LBB0_105

.LBB0_126:
	ds_read_b128 v[166:169], v142
	ds_read_b128 v[170:173], v142 offset:1024
	ds_read_b128 v[194:197], v142 offset:2048
	ds_read_b128 v[198:201], v142 offset:3072
	v_add_u32_e32 v165, 0xc000, v152
	v_lshl_add_u64 v[190:191], s[72:73], 0, v[128:129]
	v_readfirstlane_b32 s23, v165
	v_add_u32_e32 v164, 0xe000, v152
	v_lshl_add_u64 v[234:235], v[190:191], 0, s[4:5]
	s_mov_b32 m0, s23
	v_readfirstlane_b32 s23, v164
	ds_read_b128 v[202:205], v143
	ds_read_b128 v[206:209], v143 offset:1024
	ds_read_b128 v[210:213], v144
	ds_read_b128 v[214:217], v144 offset:1024
	ds_read_b128 v[218:221], v145
	ds_read_b128 v[222:225], v145 offset:1024
	ds_read_b128 v[226:229], v146
	ds_read_b128 v[230:233], v146 offset:1024
	global_load_lds_dwordx4 v[234:235], off
	v_lshl_add_u64 v[234:235], v[190:191], 0, s[6:7]
	s_mov_b32 m0, s23
	s_nop 0
	global_load_lds_dwordx4 v[234:235], off
	s_waitcnt lgkmcnt(8)
	s_waitcnt vmcnt(10)
	s_barrier
	s_waitcnt lgkmcnt(0)
	s_setprio 1
	s_waitcnt lgkmcnt(0)
	v_mfma_f32_16x16x32_bf16 v[124:127], v[166:169], v[202:205], v[124:127]
	v_mfma_f32_16x16x32_bf16 v[120:123], v[194:197], v[202:205], v[120:123]
	v_mfma_f32_16x16x32_bf16 v[116:119], v[166:169], v[210:213], v[116:119]
	v_mfma_f32_16x16x32_bf16 v[112:115], v[194:197], v[210:213], v[112:115]
	v_mfma_f32_16x16x32_bf16 v[108:111], v[166:169], v[218:221], v[108:111]
	v_mfma_f32_16x16x32_bf16 v[104:107], v[194:197], v[218:221], v[104:107]
	v_mfma_f32_16x16x32_bf16 v[100:103], v[166:169], v[226:229], v[100:103]
	v_mfma_f32_16x16x32_bf16 v[96:99], v[194:197], v[226:229], v[96:99]
	v_mfma_f32_16x16x32_bf16 v[124:127], v[170:173], v[206:209], v[124:127]
	v_mfma_f32_16x16x32_bf16 v[120:123], v[198:201], v[206:209], v[120:123]
	v_mfma_f32_16x16x32_bf16 v[116:119], v[170:173], v[214:217], v[116:119]
	v_mfma_f32_16x16x32_bf16 v[112:115], v[198:201], v[214:217], v[112:115]
	v_mfma_f32_16x16x32_bf16 v[108:111], v[170:173], v[222:225], v[108:111]
	v_mfma_f32_16x16x32_bf16 v[104:107], v[198:201], v[222:225], v[104:107]
	v_mfma_f32_16x16x32_bf16 v[100:103], v[170:173], v[230:233], v[100:103]
	v_mfma_f32_16x16x32_bf16 v[96:99], v[198:201], v[230:233], v[96:99]
	s_setprio 0
	s_barrier
	v_lshl_add_u64 v[192:193], s[70:71], 0, v[128:129]
	s_mov_b64 s[34:35], 0x14bc0100
	v_readfirstlane_b32 s23, v150
	v_lshl_add_u64 v[188:189], v[192:193], 0, s[34:35]
	s_mov_b32 m0, s23
	s_mov_b64 s[34:35], 0x14be0100
	v_readfirstlane_b32 s23, v151
	ds_read_b128 v[234:237], v147
	ds_read_b128 v[238:241], v147 offset:1024
	ds_read_b128 v[242:245], v147 offset:2048
	ds_read_b128 v[246:249], v147 offset:3072
	global_load_lds_dwordx4 v[188:189], off
	v_lshl_add_u64 v[188:189], v[192:193], 0, s[34:35]
	s_mov_b32 m0, s23
	s_nop 0
	global_load_lds_dwordx4 v[188:189], off
	s_waitcnt vmcnt(10)
	s_barrier
	s_waitcnt lgkmcnt(0)
	s_setprio 1
	s_waitcnt lgkmcnt(0)
	v_mfma_f32_16x16x32_bf16 v[92:95], v[234:237], v[202:205], v[92:95]
	v_mfma_f32_16x16x32_bf16 v[88:91], v[242:245], v[202:205], v[88:91]
	v_mfma_f32_16x16x32_bf16 v[84:87], v[234:237], v[210:213], v[84:87]
	v_mfma_f32_16x16x32_bf16 v[80:83], v[242:245], v[210:213], v[80:83]
	v_mfma_f32_16x16x32_bf16 v[76:79], v[234:237], v[218:221], v[76:79]
	v_mfma_f32_16x16x32_bf16 v[72:75], v[242:245], v[218:221], v[72:75]
	v_mfma_f32_16x16x32_bf16 v[68:71], v[234:237], v[226:229], v[68:71]
	v_mfma_f32_16x16x32_bf16 v[64:67], v[242:245], v[226:229], v[64:67]
	v_mfma_f32_16x16x32_bf16 v[92:95], v[238:241], v[206:209], v[92:95]
	v_mfma_f32_16x16x32_bf16 v[88:91], v[246:249], v[206:209], v[88:91]
	v_mfma_f32_16x16x32_bf16 v[84:87], v[238:241], v[214:217], v[84:87]
	v_mfma_f32_16x16x32_bf16 v[80:83], v[246:249], v[214:217], v[80:83]
	v_mfma_f32_16x16x32_bf16 v[76:79], v[238:241], v[222:225], v[76:79]
	v_mfma_f32_16x16x32_bf16 v[72:75], v[246:249], v[222:225], v[72:75]
	v_mfma_f32_16x16x32_bf16 v[68:71], v[238:241], v[230:233], v[68:71]
	v_mfma_f32_16x16x32_bf16 v[64:67], v[246:249], v[230:233], v[64:67]
	s_setprio 0
	v_readfirstlane_b32 s23, v152
	v_lshl_add_u64 v[188:189], v[190:191], 0, s[8:9]
	s_mov_b32 m0, s23
	v_readfirstlane_b32 s23, v153
	s_barrier
	ds_read_b128 v[202:205], v143 offset:16384
	ds_read_b128 v[206:209], v143 offset:17408
	ds_read_b128 v[210:213], v144 offset:16384
	ds_read_b128 v[214:217], v144 offset:17408
	ds_read_b128 v[218:221], v145 offset:16384
	ds_read_b128 v[222:225], v145 offset:17408
	ds_read_b128 v[226:229], v146 offset:16384
	ds_read_b128 v[230:233], v146 offset:17408
	global_load_lds_dwordx4 v[188:189], off
	v_lshl_add_u64 v[188:189], v[190:191], 0, s[10:11]
	s_mov_b32 m0, s23
	s_nop 0
	global_load_lds_dwordx4 v[188:189], off
	s_barrier
	s_waitcnt lgkmcnt(0)
	s_setprio 1
	s_waitcnt lgkmcnt(0)
	v_mfma_f32_16x16x32_bf16 v[60:63], v[166:169], v[202:205], v[60:63]
	v_mfma_f32_16x16x32_bf16 v[56:59], v[194:197], v[202:205], v[56:59]
	v_mfma_f32_16x16x32_bf16 v[52:55], v[166:169], v[210:213], v[52:55]
	v_mfma_f32_16x16x32_bf16 v[48:51], v[194:197], v[210:213], v[48:51]
	v_mfma_f32_16x16x32_bf16 v[44:47], v[166:169], v[218:221], v[44:47]
	v_mfma_f32_16x16x32_bf16 v[40:43], v[194:197], v[218:221], v[40:43]
	v_mfma_f32_16x16x32_bf16 v[36:39], v[166:169], v[226:229], v[36:39]
	v_mfma_f32_16x16x32_bf16 v[32:35], v[194:197], v[226:229], v[32:35]
	v_mfma_f32_16x16x32_bf16 v[60:63], v[170:173], v[206:209], v[60:63]
	v_mfma_f32_16x16x32_bf16 v[56:59], v[198:201], v[206:209], v[56:59]
	v_mfma_f32_16x16x32_bf16 v[52:55], v[170:173], v[214:217], v[52:55]
	v_mfma_f32_16x16x32_bf16 v[48:51], v[198:201], v[214:217], v[48:51]
	v_mfma_f32_16x16x32_bf16 v[44:47], v[170:173], v[222:225], v[44:47]
	v_mfma_f32_16x16x32_bf16 v[40:43], v[198:201], v[222:225], v[40:43]
	v_mfma_f32_16x16x32_bf16 v[36:39], v[170:173], v[230:233], v[36:39]
	v_mfma_f32_16x16x32_bf16 v[32:35], v[198:201], v[230:233], v[32:35]
	s_setprio 0
	s_barrier
	s_mov_b64 s[34:35], 0x14c00100
	v_readfirstlane_b32 s23, v154
	v_lshl_add_u64 v[166:167], v[192:193], 0, s[34:35]
	s_mov_b32 m0, s23
	s_mov_b64 s[34:35], 0x14c20100
	v_readfirstlane_b32 s23, v155
	global_load_lds_dwordx4 v[166:167], off
	v_lshl_add_u64 v[166:167], v[192:193], 0, s[34:35]
	s_mov_b32 m0, s23
	s_nop 0
	global_load_lds_dwordx4 v[166:167], off
	s_waitcnt vmcnt(10)
	s_barrier
	s_setprio 1
	v_mfma_f32_16x16x32_bf16 v[28:31], v[234:237], v[202:205], v[28:31]
	v_mfma_f32_16x16x32_bf16 v[24:27], v[242:245], v[202:205], v[24:27]
	v_mfma_f32_16x16x32_bf16 v[20:23], v[234:237], v[210:213], v[20:23]
	v_mfma_f32_16x16x32_bf16 v[16:19], v[242:245], v[210:213], v[16:19]
	v_mfma_f32_16x16x32_bf16 v[12:15], v[234:237], v[218:221], v[12:15]
	v_mfma_f32_16x16x32_bf16 v[8:11], v[242:245], v[218:221], v[8:11]
	v_mfma_f32_16x16x32_bf16 v[4:7], v[234:237], v[226:229], v[4:7]
	v_mfma_f32_16x16x32_bf16 v[0:3], v[242:245], v[226:229], v[0:3]
	v_mfma_f32_16x16x32_bf16 v[28:31], v[238:241], v[206:209], v[28:31]
	v_mfma_f32_16x16x32_bf16 v[24:27], v[246:249], v[206:209], v[24:27]
	v_mfma_f32_16x16x32_bf16 v[20:23], v[238:241], v[214:217], v[20:23]
	v_mfma_f32_16x16x32_bf16 v[16:19], v[246:249], v[214:217], v[16:19]
	v_mfma_f32_16x16x32_bf16 v[12:15], v[238:241], v[222:225], v[12:15]
	v_mfma_f32_16x16x32_bf16 v[8:11], v[246:249], v[222:225], v[8:11]
	v_mfma_f32_16x16x32_bf16 v[4:7], v[238:241], v[230:233], v[4:7]
	v_mfma_f32_16x16x32_bf16 v[0:3], v[246:249], v[230:233], v[0:3]
	s_setprio 0
	s_barrier
	ds_read_b128 v[166:169], v148
	ds_read_b128 v[170:173], v148 offset:1024
	ds_read_b128 v[194:197], v148 offset:2048
	ds_read_b128 v[198:201], v148 offset:3072
	v_readfirstlane_b32 s23, v156
	v_lshl_add_u64 v[188:189], v[190:191], 0, s[38:39]
	s_mov_b32 m0, s23
	v_readfirstlane_b32 s23, v157
	ds_read_b128 v[202:205], v143 offset:32768
	ds_read_b128 v[206:209], v143 offset:33792
	ds_read_b128 v[210:213], v144 offset:32768
	ds_read_b128 v[214:217], v144 offset:33792
	ds_read_b128 v[218:221], v145 offset:32768
	ds_read_b128 v[222:225], v145 offset:33792
	ds_read_b128 v[226:229], v146 offset:32768
	ds_read_b128 v[230:233], v146 offset:33792
	global_load_lds_dwordx4 v[188:189], off
	v_lshl_add_u64 v[188:189], v[190:191], 0, s[16:17]
	s_mov_b32 m0, s23
	s_nop 0
	global_load_lds_dwordx4 v[188:189], off
	s_waitcnt lgkmcnt(8)
	s_waitcnt vmcnt(10)
	s_barrier
	s_waitcnt lgkmcnt(0)
	s_setprio 1
	s_waitcnt lgkmcnt(0)
	v_mfma_f32_16x16x32_bf16 v[124:127], v[166:169], v[202:205], v[124:127]
	v_mfma_f32_16x16x32_bf16 v[120:123], v[194:197], v[202:205], v[120:123]
	v_mfma_f32_16x16x32_bf16 v[116:119], v[166:169], v[210:213], v[116:119]
	v_mfma_f32_16x16x32_bf16 v[112:115], v[194:197], v[210:213], v[112:115]
	v_mfma_f32_16x16x32_bf16 v[108:111], v[166:169], v[218:221], v[108:111]
	v_mfma_f32_16x16x32_bf16 v[104:107], v[194:197], v[218:221], v[104:107]
	v_mfma_f32_16x16x32_bf16 v[100:103], v[166:169], v[226:229], v[100:103]
	v_mfma_f32_16x16x32_bf16 v[96:99], v[194:197], v[226:229], v[96:99]
	v_mfma_f32_16x16x32_bf16 v[124:127], v[170:173], v[206:209], v[124:127]
	v_mfma_f32_16x16x32_bf16 v[120:123], v[198:201], v[206:209], v[120:123]
	v_mfma_f32_16x16x32_bf16 v[116:119], v[170:173], v[214:217], v[116:119]
	v_mfma_f32_16x16x32_bf16 v[112:115], v[198:201], v[214:217], v[112:115]
	v_mfma_f32_16x16x32_bf16 v[108:111], v[170:173], v[222:225], v[108:111]
	v_mfma_f32_16x16x32_bf16 v[104:107], v[198:201], v[222:225], v[104:107]
	v_mfma_f32_16x16x32_bf16 v[100:103], v[170:173], v[230:233], v[100:103]
	v_mfma_f32_16x16x32_bf16 v[96:99], v[198:201], v[230:233], v[96:99]
	s_setprio 0
	s_barrier
	s_mov_b64 s[34:35], 0x14bc0180
	v_readfirstlane_b32 s23, v158
	v_lshl_add_u64 v[188:189], v[192:193], 0, s[34:35]
	s_mov_b32 m0, s23
	s_mov_b64 s[34:35], 0x14be0180
	v_readfirstlane_b32 s23, v159
	ds_read_b128 v[234:237], v149
	ds_read_b128 v[238:241], v149 offset:1024
	ds_read_b128 v[242:245], v149 offset:2048
	ds_read_b128 v[246:249], v149 offset:3072
	global_load_lds_dwordx4 v[188:189], off
	v_lshl_add_u64 v[188:189], v[192:193], 0, s[34:35]
	s_mov_b32 m0, s23
	s_nop 0
	global_load_lds_dwordx4 v[188:189], off
	s_waitcnt vmcnt(10)
	s_barrier
	s_waitcnt lgkmcnt(0)
	s_setprio 1
	s_waitcnt lgkmcnt(0)
	v_mfma_f32_16x16x32_bf16 v[92:95], v[234:237], v[202:205], v[92:95]
	v_mfma_f32_16x16x32_bf16 v[88:91], v[242:245], v[202:205], v[88:91]
	v_mfma_f32_16x16x32_bf16 v[84:87], v[234:237], v[210:213], v[84:87]
	v_mfma_f32_16x16x32_bf16 v[80:83], v[242:245], v[210:213], v[80:83]
	v_mfma_f32_16x16x32_bf16 v[76:79], v[234:237], v[218:221], v[76:79]
	v_mfma_f32_16x16x32_bf16 v[72:75], v[242:245], v[218:221], v[72:75]
	v_mfma_f32_16x16x32_bf16 v[68:71], v[234:237], v[226:229], v[68:71]
	v_mfma_f32_16x16x32_bf16 v[64:67], v[242:245], v[226:229], v[64:67]
	v_mfma_f32_16x16x32_bf16 v[92:95], v[238:241], v[206:209], v[92:95]
	v_mfma_f32_16x16x32_bf16 v[88:91], v[246:249], v[206:209], v[88:91]
	v_mfma_f32_16x16x32_bf16 v[84:87], v[238:241], v[214:217], v[84:87]
	v_mfma_f32_16x16x32_bf16 v[80:83], v[246:249], v[214:217], v[80:83]
	v_mfma_f32_16x16x32_bf16 v[76:79], v[238:241], v[222:225], v[76:79]
	v_mfma_f32_16x16x32_bf16 v[72:75], v[246:249], v[222:225], v[72:75]
	v_mfma_f32_16x16x32_bf16 v[68:71], v[238:241], v[230:233], v[68:71]
	v_mfma_f32_16x16x32_bf16 v[64:67], v[246:249], v[230:233], v[64:67]
	s_setprio 0
	v_readfirstlane_b32 s23, v160
	v_lshl_add_u64 v[188:189], v[190:191], 0, s[18:19]
	s_mov_b32 m0, s23
	v_readfirstlane_b32 s23, v161
	s_barrier
	ds_read_b128 v[202:205], v143 offset:49152
	ds_read_b128 v[206:209], v143 offset:50176
	ds_read_b128 v[210:213], v144 offset:49152
	ds_read_b128 v[214:217], v144 offset:50176
	ds_read_b128 v[218:221], v145 offset:49152
	ds_read_b128 v[222:225], v145 offset:50176
	ds_read_b128 v[226:229], v146 offset:49152
	ds_read_b128 v[230:233], v146 offset:50176
	global_load_lds_dwordx4 v[188:189], off
	v_lshl_add_u64 v[188:189], v[190:191], 0, s[86:87]
	s_mov_b32 m0, s23
	s_nop 0
	global_load_lds_dwordx4 v[188:189], off
	s_barrier
	s_waitcnt lgkmcnt(0)
	s_setprio 1
	s_waitcnt lgkmcnt(0)
	v_mfma_f32_16x16x32_bf16 v[60:63], v[166:169], v[202:205], v[60:63]
	v_mfma_f32_16x16x32_bf16 v[56:59], v[194:197], v[202:205], v[56:59]
	v_mfma_f32_16x16x32_bf16 v[52:55], v[166:169], v[210:213], v[52:55]
	v_mfma_f32_16x16x32_bf16 v[48:51], v[194:197], v[210:213], v[48:51]
	v_mfma_f32_16x16x32_bf16 v[44:47], v[166:169], v[218:221], v[44:47]
	v_mfma_f32_16x16x32_bf16 v[40:43], v[194:197], v[218:221], v[40:43]
	v_mfma_f32_16x16x32_bf16 v[36:39], v[166:169], v[226:229], v[36:39]
	v_mfma_f32_16x16x32_bf16 v[32:35], v[194:197], v[226:229], v[32:35]
	v_mfma_f32_16x16x32_bf16 v[60:63], v[170:173], v[206:209], v[60:63]
	v_mfma_f32_16x16x32_bf16 v[56:59], v[198:201], v[206:209], v[56:59]
	v_mfma_f32_16x16x32_bf16 v[52:55], v[170:173], v[214:217], v[52:55]
	v_mfma_f32_16x16x32_bf16 v[48:51], v[198:201], v[214:217], v[48:51]
	v_mfma_f32_16x16x32_bf16 v[44:47], v[170:173], v[222:225], v[44:47]
	v_mfma_f32_16x16x32_bf16 v[40:43], v[198:201], v[222:225], v[40:43]
	v_mfma_f32_16x16x32_bf16 v[36:39], v[170:173], v[230:233], v[36:39]
	v_mfma_f32_16x16x32_bf16 v[32:35], v[198:201], v[230:233], v[32:35]
	s_setprio 0
	s_barrier
	s_mov_b64 s[34:35], 0x14c00180
	v_readfirstlane_b32 s23, v162
	v_lshl_add_u64 v[166:167], v[192:193], 0, s[34:35]
	s_mov_b32 m0, s23
	s_mov_b64 s[34:35], 0x14c20180
	v_readfirstlane_b32 s23, v163
	global_load_lds_dwordx4 v[166:167], off
	v_lshl_add_u64 v[166:167], v[192:193], 0, s[34:35]
	s_mov_b32 m0, s23
	s_nop 0
	global_load_lds_dwordx4 v[166:167], off
	s_waitcnt vmcnt(10)
	s_barrier
	s_setprio 1
	v_mfma_f32_16x16x32_bf16 v[28:31], v[234:237], v[202:205], v[28:31]
	v_mfma_f32_16x16x32_bf16 v[24:27], v[242:245], v[202:205], v[24:27]
	v_mfma_f32_16x16x32_bf16 v[20:23], v[234:237], v[210:213], v[20:23]
	v_mfma_f32_16x16x32_bf16 v[16:19], v[242:245], v[210:213], v[16:19]
	v_mfma_f32_16x16x32_bf16 v[12:15], v[234:237], v[218:221], v[12:15]
	v_mfma_f32_16x16x32_bf16 v[8:11], v[242:245], v[218:221], v[8:11]
	v_mfma_f32_16x16x32_bf16 v[4:7], v[234:237], v[226:229], v[4:7]
	v_mfma_f32_16x16x32_bf16 v[0:3], v[242:245], v[226:229], v[0:3]
	v_mfma_f32_16x16x32_bf16 v[28:31], v[238:241], v[206:209], v[28:31]
	v_mfma_f32_16x16x32_bf16 v[24:27], v[246:249], v[206:209], v[24:27]
	v_mfma_f32_16x16x32_bf16 v[20:23], v[238:241], v[214:217], v[20:23]
	v_mfma_f32_16x16x32_bf16 v[16:19], v[246:249], v[214:217], v[16:19]
	v_mfma_f32_16x16x32_bf16 v[12:15], v[238:241], v[222:225], v[12:15]
	v_mfma_f32_16x16x32_bf16 v[8:11], v[246:249], v[222:225], v[8:11]
	v_mfma_f32_16x16x32_bf16 v[4:7], v[238:241], v[230:233], v[4:7]
	v_mfma_f32_16x16x32_bf16 v[0:3], v[246:249], v[230:233], v[0:3]
	s_setprio 0
	s_add_i32 s22, s22, 2
	s_add_u32 s70, s70, 0x100
	s_addc_u32 s71, s71, 0
	s_add_u32 s72, s72, 0x100
	s_addc_u32 s73, s73, 0
	s_cmp_lt_u32 s22, 12
	s_barrier
	s_cbranch_scc1 .LBB0_126
	v_readlane_b32 s34, v252, 33
	s_add_i32 s34, s76, s34
	s_cmpk_lt_i32 s34, 0xfc
	s_cbranch_scc1 .Lgu_tpf
	s_mov_b64 s[4:5], 0x780
	v_readfirstlane_b32 s22, v165
	v_lshl_add_u64 v[130:131], v[130:131], 0, s[4:5]
	s_mov_b32 m0, s22
	ds_read_b128 v[150:153], v142
	ds_read_b128 v[154:157], v142 offset:1024
	ds_read_b128 v[158:161], v142 offset:2048
	ds_read_b128 v[166:169], v142 offset:3072
	ds_read_b128 v[170:173], v143
	ds_read_b128 v[194:197], v143 offset:1024
	ds_read_b128 v[198:201], v144
	ds_read_b128 v[202:205], v144 offset:1024
	ds_read_b128 v[206:209], v145
	ds_read_b128 v[210:213], v145 offset:1024
	ds_read_b128 v[214:217], v146
	ds_read_b128 v[218:221], v146 offset:1024
	global_load_lds_dwordx4 v[130:131], off
	v_lshl_add_u64 v[130:131], v[136:137], 1, s[48:49]
	s_mov_b64 s[4:5], 0x20780
	v_readfirstlane_b32 s22, v164
	v_lshl_add_u64 v[130:131], v[130:131], 0, s[4:5]
	s_mov_b32 m0, s22
	s_nop 0
	global_load_lds_dwordx4 v[130:131], off
	s_waitcnt vmcnt(10)
	s_barrier
	s_waitcnt lgkmcnt(0)
	s_setprio 1
	s_waitcnt lgkmcnt(0)
	v_mfma_f32_16x16x32_bf16 v[124:127], v[150:153], v[170:173], v[124:127]
	v_mfma_f32_16x16x32_bf16 v[120:123], v[158:161], v[170:173], v[120:123]
	v_mfma_f32_16x16x32_bf16 v[116:119], v[150:153], v[198:201], v[116:119]
	v_mfma_f32_16x16x32_bf16 v[112:115], v[158:161], v[198:201], v[112:115]
	v_mfma_f32_16x16x32_bf16 v[108:111], v[150:153], v[206:209], v[108:111]
	v_mfma_f32_16x16x32_bf16 v[104:107], v[158:161], v[206:209], v[104:107]
	v_mfma_f32_16x16x32_bf16 v[100:103], v[150:153], v[214:217], v[100:103]
	v_mfma_f32_16x16x32_bf16 v[96:99], v[158:161], v[214:217], v[96:99]
	v_mfma_f32_16x16x32_bf16 v[124:127], v[154:157], v[194:197], v[124:127]
	v_mfma_f32_16x16x32_bf16 v[120:123], v[166:169], v[194:197], v[120:123]
	v_mfma_f32_16x16x32_bf16 v[116:119], v[154:157], v[202:205], v[116:119]
	v_mfma_f32_16x16x32_bf16 v[112:115], v[166:169], v[202:205], v[112:115]
	v_mfma_f32_16x16x32_bf16 v[108:111], v[154:157], v[210:213], v[108:111]
	v_mfma_f32_16x16x32_bf16 v[104:107], v[166:169], v[210:213], v[104:107]
	v_mfma_f32_16x16x32_bf16 v[100:103], v[154:157], v[218:221], v[100:103]
	v_mfma_f32_16x16x32_bf16 v[96:99], v[166:169], v[218:221], v[96:99]
	s_setprio 0
	s_barrier
	ds_read_b128 v[162:165], v147
	ds_read_b128 v[222:225], v147 offset:1024
	ds_read_b128 v[226:229], v147 offset:2048
	ds_read_b128 v[230:233], v147 offset:3072
	s_waitcnt vmcnt(8)
	s_barrier
	s_waitcnt lgkmcnt(0)
	s_setprio 1
	s_waitcnt lgkmcnt(0)
	v_mfma_f32_16x16x32_bf16 v[92:95], v[162:165], v[170:173], v[92:95]
	v_mfma_f32_16x16x32_bf16 v[88:91], v[226:229], v[170:173], v[88:91]
	v_mfma_f32_16x16x32_bf16 v[84:87], v[162:165], v[198:201], v[84:87]
	v_mfma_f32_16x16x32_bf16 v[80:83], v[226:229], v[198:201], v[80:83]
	v_mfma_f32_16x16x32_bf16 v[76:79], v[162:165], v[206:209], v[76:79]
	v_mfma_f32_16x16x32_bf16 v[72:75], v[226:229], v[206:209], v[72:75]
	v_mfma_f32_16x16x32_bf16 v[68:71], v[162:165], v[214:217], v[68:71]
	v_mfma_f32_16x16x32_bf16 v[64:67], v[226:229], v[214:217], v[64:67]
	v_mfma_f32_16x16x32_bf16 v[92:95], v[222:225], v[194:197], v[92:95]
	v_mfma_f32_16x16x32_bf16 v[88:91], v[230:233], v[194:197], v[88:91]
	v_mfma_f32_16x16x32_bf16 v[84:87], v[222:225], v[202:205], v[84:87]
	v_mfma_f32_16x16x32_bf16 v[80:83], v[230:233], v[202:205], v[80:83]
	v_mfma_f32_16x16x32_bf16 v[76:79], v[222:225], v[210:213], v[76:79]
	v_mfma_f32_16x16x32_bf16 v[72:75], v[230:233], v[210:213], v[72:75]
	v_mfma_f32_16x16x32_bf16 v[68:71], v[222:225], v[218:221], v[68:71]
	v_mfma_f32_16x16x32_bf16 v[64:67], v[230:233], v[218:221], v[64:67]
	s_setprio 0
	s_barrier
	ds_read_b128 v[170:173], v143 offset:16384
	ds_read_b128 v[194:197], v143 offset:17408
	ds_read_b128 v[198:201], v144 offset:16384
	ds_read_b128 v[202:205], v144 offset:17408
	ds_read_b128 v[206:209], v145 offset:16384
	ds_read_b128 v[210:213], v145 offset:17408
	ds_read_b128 v[214:217], v146 offset:16384
	ds_read_b128 v[218:221], v146 offset:17408
	s_waitcnt vmcnt(4)
	s_barrier
	s_waitcnt lgkmcnt(0)
	s_setprio 1
	s_waitcnt lgkmcnt(0)
	v_mfma_f32_16x16x32_bf16 v[60:63], v[150:153], v[170:173], v[60:63]
	v_mfma_f32_16x16x32_bf16 v[56:59], v[158:161], v[170:173], v[56:59]
	v_mfma_f32_16x16x32_bf16 v[52:55], v[150:153], v[198:201], v[52:55]
	v_mfma_f32_16x16x32_bf16 v[48:51], v[158:161], v[198:201], v[48:51]
	v_mfma_f32_16x16x32_bf16 v[44:47], v[150:153], v[206:209], v[44:47]
	v_mfma_f32_16x16x32_bf16 v[40:43], v[158:161], v[206:209], v[40:43]
	v_mfma_f32_16x16x32_bf16 v[36:39], v[150:153], v[214:217], v[36:39]
	v_mfma_f32_16x16x32_bf16 v[32:35], v[158:161], v[214:217], v[32:35]
	v_mfma_f32_16x16x32_bf16 v[60:63], v[154:157], v[194:197], v[60:63]
	v_mfma_f32_16x16x32_bf16 v[56:59], v[166:169], v[194:197], v[56:59]
	v_mfma_f32_16x16x32_bf16 v[52:55], v[154:157], v[202:205], v[52:55]
	v_mfma_f32_16x16x32_bf16 v[48:51], v[166:169], v[202:205], v[48:51]
	v_mfma_f32_16x16x32_bf16 v[44:47], v[154:157], v[210:213], v[44:47]
	v_mfma_f32_16x16x32_bf16 v[40:43], v[166:169], v[210:213], v[40:43]
	v_mfma_f32_16x16x32_bf16 v[36:39], v[154:157], v[218:221], v[36:39]
	v_mfma_f32_16x16x32_bf16 v[32:35], v[166:169], v[218:221], v[32:35]
	s_setprio 0
	s_setprio 1
	v_mfma_f32_16x16x32_bf16 v[28:31], v[162:165], v[170:173], v[28:31]
	v_mfma_f32_16x16x32_bf16 v[24:27], v[226:229], v[170:173], v[24:27]
	v_mfma_f32_16x16x32_bf16 v[20:23], v[162:165], v[198:201], v[20:23]
	v_mfma_f32_16x16x32_bf16 v[16:19], v[226:229], v[198:201], v[16:19]
	v_mfma_f32_16x16x32_bf16 v[12:15], v[162:165], v[206:209], v[12:15]
	v_mfma_f32_16x16x32_bf16 v[8:11], v[226:229], v[206:209], v[8:11]
	v_mfma_f32_16x16x32_bf16 v[4:7], v[162:165], v[214:217], v[4:7]
	v_mfma_f32_16x16x32_bf16 v[0:3], v[226:229], v[214:217], v[0:3]
	v_mfma_f32_16x16x32_bf16 v[28:31], v[222:225], v[194:197], v[28:31]
	v_mfma_f32_16x16x32_bf16 v[24:27], v[230:233], v[194:197], v[24:27]
	v_mfma_f32_16x16x32_bf16 v[20:23], v[222:225], v[202:205], v[20:23]
	v_mfma_f32_16x16x32_bf16 v[16:19], v[230:233], v[202:205], v[16:19]
	v_mfma_f32_16x16x32_bf16 v[12:15], v[222:225], v[210:213], v[12:15]
	v_mfma_f32_16x16x32_bf16 v[8:11], v[230:233], v[210:213], v[8:11]
	v_mfma_f32_16x16x32_bf16 v[4:7], v[222:225], v[218:221], v[4:7]
	v_mfma_f32_16x16x32_bf16 v[0:3], v[230:233], v[218:221], v[0:3]
	s_setprio 0
	s_barrier
	ds_read_b128 v[150:153], v148
	ds_read_b128 v[154:157], v148 offset:1024
	ds_read_b128 v[158:161], v148 offset:2048
	ds_read_b128 v[162:165], v148 offset:3072
	ds_read_b128 v[166:169], v143 offset:32768
	ds_read_b128 v[170:173], v143 offset:33792
	ds_read_b128 v[194:197], v144 offset:32768
	ds_read_b128 v[198:201], v144 offset:33792
	ds_read_b128 v[202:205], v145 offset:32768
	ds_read_b128 v[206:209], v145 offset:33792
	ds_read_b128 v[210:213], v146 offset:32768
	ds_read_b128 v[214:217], v146 offset:33792
	s_waitcnt vmcnt(2)
	s_barrier
	s_waitcnt lgkmcnt(0)
	s_setprio 1
	s_waitcnt lgkmcnt(0)
	v_mfma_f32_16x16x32_bf16 v[124:127], v[150:153], v[166:169], v[124:127]
	v_mfma_f32_16x16x32_bf16 v[120:123], v[158:161], v[166:169], v[120:123]
	v_mfma_f32_16x16x32_bf16 v[116:119], v[150:153], v[194:197], v[116:119]
	v_mfma_f32_16x16x32_bf16 v[112:115], v[158:161], v[194:197], v[112:115]
	v_mfma_f32_16x16x32_bf16 v[108:111], v[150:153], v[202:205], v[108:111]
	v_mfma_f32_16x16x32_bf16 v[104:107], v[158:161], v[202:205], v[104:107]
	v_mfma_f32_16x16x32_bf16 v[100:103], v[150:153], v[210:213], v[100:103]
	v_mfma_f32_16x16x32_bf16 v[96:99], v[158:161], v[210:213], v[96:99]
	v_mfma_f32_16x16x32_bf16 v[124:127], v[154:157], v[170:173], v[124:127]
	v_mfma_f32_16x16x32_bf16 v[120:123], v[162:165], v[170:173], v[120:123]
	v_mfma_f32_16x16x32_bf16 v[116:119], v[154:157], v[198:201], v[116:119]
	v_mfma_f32_16x16x32_bf16 v[112:115], v[162:165], v[198:201], v[112:115]
	v_mfma_f32_16x16x32_bf16 v[108:111], v[154:157], v[206:209], v[108:111]
	v_mfma_f32_16x16x32_bf16 v[104:107], v[162:165], v[206:209], v[104:107]
	v_mfma_f32_16x16x32_bf16 v[100:103], v[154:157], v[214:217], v[100:103]
	v_mfma_f32_16x16x32_bf16 v[96:99], v[162:165], v[214:217], v[96:99]
	s_setprio 0
	s_barrier
	ds_read_b128 v[218:221], v149
	ds_read_b128 v[222:225], v149 offset:1024
	ds_read_b128 v[226:229], v149 offset:2048
	ds_read_b128 v[230:233], v149 offset:3072
	s_waitcnt vmcnt(0)
	s_barrier
	s_waitcnt lgkmcnt(0)
	s_setprio 1
	s_waitcnt lgkmcnt(0)
	v_mfma_f32_16x16x32_bf16 v[92:95], v[218:221], v[166:169], v[92:95]
	v_mfma_f32_16x16x32_bf16 v[88:91], v[226:229], v[166:169], v[88:91]
	v_mfma_f32_16x16x32_bf16 v[84:87], v[218:221], v[194:197], v[84:87]
	v_mfma_f32_16x16x32_bf16 v[80:83], v[226:229], v[194:197], v[80:83]
	v_mfma_f32_16x16x32_bf16 v[76:79], v[218:221], v[202:205], v[76:79]
	v_mfma_f32_16x16x32_bf16 v[72:75], v[226:229], v[202:205], v[72:75]
	v_mfma_f32_16x16x32_bf16 v[68:71], v[218:221], v[210:213], v[68:71]
	v_mfma_f32_16x16x32_bf16 v[64:67], v[226:229], v[210:213], v[64:67]
	v_mfma_f32_16x16x32_bf16 v[92:95], v[222:225], v[170:173], v[92:95]
	v_mfma_f32_16x16x32_bf16 v[88:91], v[230:233], v[170:173], v[88:91]
	v_mfma_f32_16x16x32_bf16 v[84:87], v[222:225], v[198:201], v[84:87]
	v_mfma_f32_16x16x32_bf16 v[80:83], v[230:233], v[198:201], v[80:83]
	v_mfma_f32_16x16x32_bf16 v[76:79], v[222:225], v[206:209], v[76:79]
	v_mfma_f32_16x16x32_bf16 v[72:75], v[230:233], v[206:209], v[72:75]
	v_mfma_f32_16x16x32_bf16 v[68:71], v[222:225], v[214:217], v[68:71]
	v_mfma_f32_16x16x32_bf16 v[64:67], v[230:233], v[214:217], v[64:67]
	s_setprio 0
	s_barrier
	ds_read_b128 v[166:169], v143 offset:49152
	ds_read_b128 v[170:173], v143 offset:50176
	ds_read_b128 v[194:197], v144 offset:49152
	ds_read_b128 v[198:201], v144 offset:50176
	ds_read_b128 v[202:205], v145 offset:49152
	ds_read_b128 v[206:209], v145 offset:50176
	ds_read_b128 v[210:213], v146 offset:49152
	ds_read_b128 v[214:217], v146 offset:50176
	s_barrier
	s_waitcnt lgkmcnt(0)
	s_setprio 1
	s_waitcnt lgkmcnt(0)
	v_mfma_f32_16x16x32_bf16 v[60:63], v[150:153], v[166:169], v[60:63]
	v_mfma_f32_16x16x32_bf16 v[56:59], v[158:161], v[166:169], v[56:59]
	v_mfma_f32_16x16x32_bf16 v[52:55], v[150:153], v[194:197], v[52:55]
	v_mfma_f32_16x16x32_bf16 v[48:51], v[158:161], v[194:197], v[48:51]
	v_mfma_f32_16x16x32_bf16 v[44:47], v[150:153], v[202:205], v[44:47]
	v_mfma_f32_16x16x32_bf16 v[40:43], v[158:161], v[202:205], v[40:43]
	v_mfma_f32_16x16x32_bf16 v[36:39], v[150:153], v[210:213], v[36:39]
	v_mfma_f32_16x16x32_bf16 v[32:35], v[158:161], v[210:213], v[32:35]
	v_mfma_f32_16x16x32_bf16 v[60:63], v[154:157], v[170:173], v[60:63]
	v_mfma_f32_16x16x32_bf16 v[56:59], v[162:165], v[170:173], v[56:59]
	v_mfma_f32_16x16x32_bf16 v[52:55], v[154:157], v[198:201], v[52:55]
	v_mfma_f32_16x16x32_bf16 v[48:51], v[162:165], v[198:201], v[48:51]
	v_mfma_f32_16x16x32_bf16 v[44:47], v[154:157], v[206:209], v[44:47]
	v_mfma_f32_16x16x32_bf16 v[40:43], v[162:165], v[206:209], v[40:43]
	v_mfma_f32_16x16x32_bf16 v[36:39], v[154:157], v[214:217], v[36:39]
	v_mfma_f32_16x16x32_bf16 v[32:35], v[162:165], v[214:217], v[32:35]
	s_setprio 0
	s_setprio 1
	v_mfma_f32_16x16x32_bf16 v[28:31], v[218:221], v[166:169], v[28:31]
	v_mfma_f32_16x16x32_bf16 v[24:27], v[226:229], v[166:169], v[24:27]
	v_mfma_f32_16x16x32_bf16 v[20:23], v[218:221], v[194:197], v[20:23]
	v_mfma_f32_16x16x32_bf16 v[16:19], v[226:229], v[194:197], v[16:19]
	v_mfma_f32_16x16x32_bf16 v[12:15], v[218:221], v[202:205], v[12:15]
	v_mfma_f32_16x16x32_bf16 v[8:11], v[226:229], v[202:205], v[8:11]
	v_mfma_f32_16x16x32_bf16 v[4:7], v[218:221], v[210:213], v[4:7]
	v_mfma_f32_16x16x32_bf16 v[0:3], v[226:229], v[210:213], v[0:3]
	v_mfma_f32_16x16x32_bf16 v[28:31], v[222:225], v[170:173], v[28:31]
	v_mfma_f32_16x16x32_bf16 v[24:27], v[230:233], v[170:173], v[24:27]
	v_mfma_f32_16x16x32_bf16 v[20:23], v[222:225], v[198:201], v[20:23]
	v_mfma_f32_16x16x32_bf16 v[16:19], v[230:233], v[198:201], v[16:19]
	v_mfma_f32_16x16x32_bf16 v[12:15], v[222:225], v[206:209], v[12:15]
	v_mfma_f32_16x16x32_bf16 v[8:11], v[230:233], v[206:209], v[8:11]
	v_mfma_f32_16x16x32_bf16 v[4:7], v[222:225], v[214:217], v[4:7]
	v_mfma_f32_16x16x32_bf16 v[0:3], v[230:233], v[214:217], v[0:3]
	s_setprio 0
	s_barrier
	s_and_saveexec_b64 s[48:49], s[40:41]
	s_cbranch_execz .LBB0_122
	s_barrier
	s_branch .LBB0_122
.Lgu_tpf:
	s_mov_b64 s[4:5], 0x780
	v_readfirstlane_b32 s22, v165
	v_lshl_add_u64 v[130:131], v[130:131], 0, s[4:5]
	s_mov_b32 m0, s22
	ds_read_b128 v[150:153], v142
	ds_read_b128 v[154:157], v142 offset:1024
	ds_read_b128 v[158:161], v142 offset:2048
	ds_read_b128 v[166:169], v142 offset:3072
	ds_read_b128 v[170:173], v143
	ds_read_b128 v[194:197], v143 offset:1024
	ds_read_b128 v[198:201], v144
	ds_read_b128 v[202:205], v144 offset:1024
	ds_read_b128 v[206:209], v145
	ds_read_b128 v[210:213], v145 offset:1024
	ds_read_b128 v[214:217], v146
	ds_read_b128 v[218:221], v146 offset:1024
	global_load_lds_dwordx4 v[130:131], off
	v_lshl_add_u64 v[130:131], v[136:137], 1, s[48:49]
	s_mov_b64 s[4:5], 0x20780
	v_readfirstlane_b32 s22, v164
	v_lshl_add_u64 v[130:131], v[130:131], 0, s[4:5]
	s_mov_b32 m0, s22
	s_nop 0
	global_load_lds_dwordx4 v[130:131], off
	v_readlane_b32 s4, v253, 57
	s_add_i32 s4, s34, s4
	s_mul_hi_i32 s5, s4, 0x30c30c31
	s_lshr_b32 s6, s5, 31
	s_ashr_i32 s5, s5, 4
	s_add_i32 s5, s5, s6
	s_mul_i32 s6, s5, 0x54
	s_sub_i32 s6, s4, s6
	s_lshl_b32 s7, s6, 8
	s_and_b32 s7, s7, 0x300
	s_lshl_b32 s6, s6, 6
	s_and_b32 s6, s6, 0xffffff00
	s_lshl_b32 s5, s5, 10
	s_or_b32 s5, s7, s5
	s_lshl_b32 s6, s6, 11
	s_lshl_b32 s5, s5, 11
	v_readlane_b32 s70, v252, 39
	v_readlane_b32 s71, v252, 40
	s_add_u32 s70, s70, s6
	s_addc_u32 s71, s71, 0
	s_add_u32 s72, s30, s5
	s_addc_u32 s73, s31, 0
	v_readfirstlane_b32 s10, v132
	s_mov_b64 s[8:9], 0x20000
	s_mov_b64 s[38:39], 0x40000
	s_waitcnt vmcnt(10)
	s_barrier
	s_waitcnt lgkmcnt(0)
	s_setprio 1
	s_waitcnt lgkmcnt(0)
	v_mfma_f32_16x16x32_bf16 v[124:127], v[150:153], v[170:173], v[124:127]
	v_mfma_f32_16x16x32_bf16 v[120:123], v[158:161], v[170:173], v[120:123]
	v_mfma_f32_16x16x32_bf16 v[116:119], v[150:153], v[198:201], v[116:119]
	v_mfma_f32_16x16x32_bf16 v[112:115], v[158:161], v[198:201], v[112:115]
	v_mfma_f32_16x16x32_bf16 v[108:111], v[150:153], v[206:209], v[108:111]
	v_mfma_f32_16x16x32_bf16 v[104:107], v[158:161], v[206:209], v[104:107]
	v_mfma_f32_16x16x32_bf16 v[100:103], v[150:153], v[214:217], v[100:103]
	v_mfma_f32_16x16x32_bf16 v[96:99], v[158:161], v[214:217], v[96:99]
	v_mfma_f32_16x16x32_bf16 v[124:127], v[154:157], v[194:197], v[124:127]
	v_mfma_f32_16x16x32_bf16 v[120:123], v[166:169], v[194:197], v[120:123]
	v_mfma_f32_16x16x32_bf16 v[116:119], v[154:157], v[202:205], v[116:119]
	v_mfma_f32_16x16x32_bf16 v[112:115], v[166:169], v[202:205], v[112:115]
	v_mfma_f32_16x16x32_bf16 v[108:111], v[154:157], v[210:213], v[108:111]
	v_mfma_f32_16x16x32_bf16 v[104:107], v[166:169], v[210:213], v[104:107]
	v_mfma_f32_16x16x32_bf16 v[100:103], v[154:157], v[218:221], v[100:103]
	v_mfma_f32_16x16x32_bf16 v[96:99], v[166:169], v[218:221], v[96:99]
	s_setprio 0
	s_barrier
	ds_read_b128 v[162:165], v147
	ds_read_b128 v[222:225], v147 offset:1024
	ds_read_b128 v[226:229], v147 offset:2048
	ds_read_b128 v[230:233], v147 offset:3072
	s_waitcnt vmcnt(8)
	s_barrier
	s_waitcnt lgkmcnt(0)
	s_setprio 1
	s_waitcnt lgkmcnt(0)
	v_mfma_f32_16x16x32_bf16 v[92:95], v[162:165], v[170:173], v[92:95]
	v_mfma_f32_16x16x32_bf16 v[88:91], v[226:229], v[170:173], v[88:91]
	v_mfma_f32_16x16x32_bf16 v[84:87], v[162:165], v[198:201], v[84:87]
	v_mfma_f32_16x16x32_bf16 v[80:83], v[226:229], v[198:201], v[80:83]
	v_mfma_f32_16x16x32_bf16 v[76:79], v[162:165], v[206:209], v[76:79]
	v_mfma_f32_16x16x32_bf16 v[72:75], v[226:229], v[206:209], v[72:75]
	v_mfma_f32_16x16x32_bf16 v[68:71], v[162:165], v[214:217], v[68:71]
	v_mfma_f32_16x16x32_bf16 v[64:67], v[226:229], v[214:217], v[64:67]
	v_mfma_f32_16x16x32_bf16 v[92:95], v[222:225], v[194:197], v[92:95]
	v_mfma_f32_16x16x32_bf16 v[88:91], v[230:233], v[194:197], v[88:91]
	v_mfma_f32_16x16x32_bf16 v[84:87], v[222:225], v[202:205], v[84:87]
	v_mfma_f32_16x16x32_bf16 v[80:83], v[230:233], v[202:205], v[80:83]
	v_mfma_f32_16x16x32_bf16 v[76:79], v[222:225], v[210:213], v[76:79]
	v_mfma_f32_16x16x32_bf16 v[72:75], v[230:233], v[210:213], v[72:75]
	v_mfma_f32_16x16x32_bf16 v[68:71], v[222:225], v[218:221], v[68:71]
	v_mfma_f32_16x16x32_bf16 v[64:67], v[230:233], v[218:221], v[64:67]
	s_setprio 0
	s_barrier
	ds_read_b128 v[170:173], v143 offset:16384
	ds_read_b128 v[194:197], v143 offset:17408
	ds_read_b128 v[198:201], v144 offset:16384
	ds_read_b128 v[202:205], v144 offset:17408
	ds_read_b128 v[206:209], v145 offset:16384
	ds_read_b128 v[210:213], v145 offset:17408
	ds_read_b128 v[214:217], v146 offset:16384
	ds_read_b128 v[218:221], v146 offset:17408
	s_waitcnt vmcnt(4)
	s_barrier
	s_waitcnt lgkmcnt(0)
	s_setprio 1
	s_waitcnt lgkmcnt(0)
	v_mfma_f32_16x16x32_bf16 v[60:63], v[150:153], v[170:173], v[60:63]
	v_mfma_f32_16x16x32_bf16 v[56:59], v[158:161], v[170:173], v[56:59]
	v_mfma_f32_16x16x32_bf16 v[52:55], v[150:153], v[198:201], v[52:55]
	v_mfma_f32_16x16x32_bf16 v[48:51], v[158:161], v[198:201], v[48:51]
	v_mfma_f32_16x16x32_bf16 v[44:47], v[150:153], v[206:209], v[44:47]
	v_mfma_f32_16x16x32_bf16 v[40:43], v[158:161], v[206:209], v[40:43]
	v_mfma_f32_16x16x32_bf16 v[36:39], v[150:153], v[214:217], v[36:39]
	v_mfma_f32_16x16x32_bf16 v[32:35], v[158:161], v[214:217], v[32:35]
	v_mfma_f32_16x16x32_bf16 v[60:63], v[154:157], v[194:197], v[60:63]
	v_mfma_f32_16x16x32_bf16 v[56:59], v[166:169], v[194:197], v[56:59]
	v_mfma_f32_16x16x32_bf16 v[52:55], v[154:157], v[202:205], v[52:55]
	v_mfma_f32_16x16x32_bf16 v[48:51], v[166:169], v[202:205], v[48:51]
	v_mfma_f32_16x16x32_bf16 v[44:47], v[154:157], v[210:213], v[44:47]
	v_mfma_f32_16x16x32_bf16 v[40:43], v[166:169], v[210:213], v[40:43]
	v_mfma_f32_16x16x32_bf16 v[36:39], v[154:157], v[218:221], v[36:39]
	v_mfma_f32_16x16x32_bf16 v[32:35], v[166:169], v[218:221], v[32:35]
	s_setprio 0
	s_setprio 1
	v_mfma_f32_16x16x32_bf16 v[28:31], v[162:165], v[170:173], v[28:31]
	v_mfma_f32_16x16x32_bf16 v[24:27], v[226:229], v[170:173], v[24:27]
	v_mfma_f32_16x16x32_bf16 v[20:23], v[162:165], v[198:201], v[20:23]
	v_mfma_f32_16x16x32_bf16 v[16:19], v[226:229], v[198:201], v[16:19]
	v_mfma_f32_16x16x32_bf16 v[12:15], v[162:165], v[206:209], v[12:15]
	v_mfma_f32_16x16x32_bf16 v[8:11], v[226:229], v[206:209], v[8:11]
	v_mfma_f32_16x16x32_bf16 v[4:7], v[162:165], v[214:217], v[4:7]
	v_mfma_f32_16x16x32_bf16 v[0:3], v[226:229], v[214:217], v[0:3]
	v_mfma_f32_16x16x32_bf16 v[28:31], v[222:225], v[194:197], v[28:31]
	v_mfma_f32_16x16x32_bf16 v[24:27], v[230:233], v[194:197], v[24:27]
	v_mfma_f32_16x16x32_bf16 v[20:23], v[222:225], v[202:205], v[20:23]
	v_mfma_f32_16x16x32_bf16 v[16:19], v[230:233], v[202:205], v[16:19]
	v_mfma_f32_16x16x32_bf16 v[12:15], v[222:225], v[210:213], v[12:15]
	v_mfma_f32_16x16x32_bf16 v[8:11], v[230:233], v[210:213], v[8:11]
	v_mfma_f32_16x16x32_bf16 v[4:7], v[222:225], v[218:221], v[4:7]
	v_mfma_f32_16x16x32_bf16 v[0:3], v[230:233], v[218:221], v[0:3]
	s_setprio 0
	s_barrier
	ds_read_b128 v[150:153], v148
	ds_read_b128 v[154:157], v148 offset:1024
	ds_read_b128 v[158:161], v148 offset:2048
	ds_read_b128 v[162:165], v148 offset:3072
	ds_read_b128 v[166:169], v143 offset:32768
	ds_read_b128 v[170:173], v143 offset:33792
	ds_read_b128 v[194:197], v144 offset:32768
	ds_read_b128 v[198:201], v144 offset:33792
	ds_read_b128 v[202:205], v145 offset:32768
	ds_read_b128 v[206:209], v145 offset:33792
	ds_read_b128 v[210:213], v146 offset:32768
	ds_read_b128 v[214:217], v146 offset:33792
	s_waitcnt vmcnt(2)
	s_barrier
	s_waitcnt lgkmcnt(0)
	s_setprio 1
	s_waitcnt lgkmcnt(0)
	v_mfma_f32_16x16x32_bf16 v[124:127], v[150:153], v[166:169], v[124:127]
	v_mfma_f32_16x16x32_bf16 v[120:123], v[158:161], v[166:169], v[120:123]
	v_mfma_f32_16x16x32_bf16 v[116:119], v[150:153], v[194:197], v[116:119]
	v_mfma_f32_16x16x32_bf16 v[112:115], v[158:161], v[194:197], v[112:115]
	v_mfma_f32_16x16x32_bf16 v[108:111], v[150:153], v[202:205], v[108:111]
	v_mfma_f32_16x16x32_bf16 v[104:107], v[158:161], v[202:205], v[104:107]
	v_mfma_f32_16x16x32_bf16 v[100:103], v[150:153], v[210:213], v[100:103]
	v_mfma_f32_16x16x32_bf16 v[96:99], v[158:161], v[210:213], v[96:99]
	v_mfma_f32_16x16x32_bf16 v[124:127], v[154:157], v[170:173], v[124:127]
	v_mfma_f32_16x16x32_bf16 v[120:123], v[162:165], v[170:173], v[120:123]
	v_mfma_f32_16x16x32_bf16 v[116:119], v[154:157], v[198:201], v[116:119]
	v_mfma_f32_16x16x32_bf16 v[112:115], v[162:165], v[198:201], v[112:115]
	v_mfma_f32_16x16x32_bf16 v[108:111], v[154:157], v[206:209], v[108:111]
	v_mfma_f32_16x16x32_bf16 v[104:107], v[162:165], v[206:209], v[104:107]
	v_mfma_f32_16x16x32_bf16 v[100:103], v[154:157], v[214:217], v[100:103]
	v_mfma_f32_16x16x32_bf16 v[96:99], v[162:165], v[214:217], v[96:99]
	s_setprio 0
	v_lshlrev_b64 v[234:235], 1, v[136:137]
	v_lshl_add_u64 v[236:237], s[70:71], 0, v[234:235]
	v_lshl_add_u64 v[238:239], s[72:73], 0, v[234:235]
	s_add_i32 s11, s10, 0x10000
	s_mov_b32 m0, s11
	v_lshl_add_u64 v[240:241], v[236:237], 0, s[8:9]
	global_load_lds_dwordx4 v[236:237], off
	s_add_i32 s11, s10, 0x12000
	s_mov_b32 m0, s11
	s_nop 0
	global_load_lds_dwordx4 v[240:241], off
	s_barrier
	ds_read_b128 v[218:221], v149
	ds_read_b128 v[222:225], v149 offset:1024
	ds_read_b128 v[226:229], v149 offset:2048
	ds_read_b128 v[230:233], v149 offset:3072
	s_mov_b32 m0, s10
	v_lshl_add_u64 v[240:241], v[238:239], 0, s[8:9]
	global_load_lds_dwordx4 v[238:239], off
	s_add_i32 s11, s10, 0x2000
	s_mov_b32 m0, s11
	s_nop 0
	global_load_lds_dwordx4 v[240:241], off
	s_waitcnt vmcnt(4)
	s_barrier
	s_waitcnt lgkmcnt(0)
	s_setprio 1
	s_waitcnt lgkmcnt(0)
	v_mfma_f32_16x16x32_bf16 v[92:95], v[218:221], v[166:169], v[92:95]
	v_mfma_f32_16x16x32_bf16 v[88:91], v[226:229], v[166:169], v[88:91]
	v_mfma_f32_16x16x32_bf16 v[84:87], v[218:221], v[194:197], v[84:87]
	v_mfma_f32_16x16x32_bf16 v[80:83], v[226:229], v[194:197], v[80:83]
	v_mfma_f32_16x16x32_bf16 v[76:79], v[218:221], v[202:205], v[76:79]
	v_mfma_f32_16x16x32_bf16 v[72:75], v[226:229], v[202:205], v[72:75]
	v_mfma_f32_16x16x32_bf16 v[68:71], v[218:221], v[210:213], v[68:71]
	v_mfma_f32_16x16x32_bf16 v[64:67], v[226:229], v[210:213], v[64:67]
	v_mfma_f32_16x16x32_bf16 v[92:95], v[222:225], v[170:173], v[92:95]
	v_mfma_f32_16x16x32_bf16 v[88:91], v[230:233], v[170:173], v[88:91]
	v_mfma_f32_16x16x32_bf16 v[84:87], v[222:225], v[198:201], v[84:87]
	v_mfma_f32_16x16x32_bf16 v[80:83], v[230:233], v[198:201], v[80:83]
	v_mfma_f32_16x16x32_bf16 v[76:79], v[222:225], v[206:209], v[76:79]
	v_mfma_f32_16x16x32_bf16 v[72:75], v[230:233], v[206:209], v[72:75]
	v_mfma_f32_16x16x32_bf16 v[68:71], v[222:225], v[214:217], v[68:71]
	v_mfma_f32_16x16x32_bf16 v[64:67], v[230:233], v[214:217], v[64:67]
	s_setprio 0
	s_barrier
	ds_read_b128 v[166:169], v143 offset:49152
	ds_read_b128 v[170:173], v143 offset:50176
	ds_read_b128 v[194:197], v144 offset:49152
	ds_read_b128 v[198:201], v144 offset:50176
	ds_read_b128 v[202:205], v145 offset:49152
	ds_read_b128 v[206:209], v145 offset:50176
	ds_read_b128 v[210:213], v146 offset:49152
	ds_read_b128 v[214:217], v146 offset:50176
	v_lshl_add_u64 v[236:237], v[236:237], 0, s[38:39]
	s_add_i32 s11, s10, 0x14000
	s_mov_b32 m0, s11
	v_lshl_add_u64 v[240:241], v[236:237], 0, s[8:9]
	global_load_lds_dwordx4 v[236:237], off
	s_add_i32 s11, s10, 0x16000
	s_mov_b32 m0, s11
	s_nop 0
	global_load_lds_dwordx4 v[240:241], off
	s_barrier
	s_waitcnt lgkmcnt(0)
	s_setprio 1
	s_waitcnt lgkmcnt(0)
	v_mfma_f32_16x16x32_bf16 v[60:63], v[150:153], v[166:169], v[60:63]
	v_mfma_f32_16x16x32_bf16 v[56:59], v[158:161], v[166:169], v[56:59]
	v_mfma_f32_16x16x32_bf16 v[52:55], v[150:153], v[194:197], v[52:55]
	v_mfma_f32_16x16x32_bf16 v[48:51], v[158:161], v[194:197], v[48:51]
	v_mfma_f32_16x16x32_bf16 v[44:47], v[150:153], v[202:205], v[44:47]
	v_mfma_f32_16x16x32_bf16 v[40:43], v[158:161], v[202:205], v[40:43]
	v_mfma_f32_16x16x32_bf16 v[36:39], v[150:153], v[210:213], v[36:39]
	v_mfma_f32_16x16x32_bf16 v[32:35], v[158:161], v[210:213], v[32:35]
	v_mfma_f32_16x16x32_bf16 v[60:63], v[154:157], v[170:173], v[60:63]
	v_mfma_f32_16x16x32_bf16 v[56:59], v[162:165], v[170:173], v[56:59]
	v_mfma_f32_16x16x32_bf16 v[52:55], v[154:157], v[198:201], v[52:55]
	v_mfma_f32_16x16x32_bf16 v[48:51], v[162:165], v[198:201], v[48:51]
	v_mfma_f32_16x16x32_bf16 v[44:47], v[154:157], v[206:209], v[44:47]
	v_mfma_f32_16x16x32_bf16 v[40:43], v[162:165], v[206:209], v[40:43]
	v_mfma_f32_16x16x32_bf16 v[36:39], v[154:157], v[214:217], v[36:39]
	v_mfma_f32_16x16x32_bf16 v[32:35], v[162:165], v[214:217], v[32:35]
	s_setprio 0
	s_setprio 1
	v_mfma_f32_16x16x32_bf16 v[28:31], v[218:221], v[166:169], v[28:31]
	v_mfma_f32_16x16x32_bf16 v[24:27], v[226:229], v[166:169], v[24:27]
	v_mfma_f32_16x16x32_bf16 v[20:23], v[218:221], v[194:197], v[20:23]
	v_mfma_f32_16x16x32_bf16 v[16:19], v[226:229], v[194:197], v[16:19]
	v_mfma_f32_16x16x32_bf16 v[12:15], v[218:221], v[202:205], v[12:15]
	v_mfma_f32_16x16x32_bf16 v[8:11], v[226:229], v[202:205], v[8:11]
	v_mfma_f32_16x16x32_bf16 v[4:7], v[218:221], v[210:213], v[4:7]
	v_mfma_f32_16x16x32_bf16 v[0:3], v[226:229], v[210:213], v[0:3]
	v_mfma_f32_16x16x32_bf16 v[28:31], v[222:225], v[170:173], v[28:31]
	v_mfma_f32_16x16x32_bf16 v[24:27], v[230:233], v[170:173], v[24:27]
	v_mfma_f32_16x16x32_bf16 v[20:23], v[222:225], v[198:201], v[20:23]
	v_mfma_f32_16x16x32_bf16 v[16:19], v[230:233], v[198:201], v[16:19]
	v_mfma_f32_16x16x32_bf16 v[12:15], v[222:225], v[206:209], v[12:15]
	v_mfma_f32_16x16x32_bf16 v[8:11], v[230:233], v[206:209], v[8:11]
	v_mfma_f32_16x16x32_bf16 v[4:7], v[222:225], v[214:217], v[4:7]
	v_mfma_f32_16x16x32_bf16 v[0:3], v[230:233], v[214:217], v[0:3]
	s_setprio 0
	v_lshl_add_u64 v[238:239], v[238:239], 0, s[38:39]
	s_add_i32 s11, s10, 0x4000
	s_mov_b32 m0, s11
	v_lshl_add_u64 v[240:241], v[238:239], 0, s[8:9]
	global_load_lds_dwordx4 v[238:239], off
	s_add_i32 s11, s10, 0x6000
	s_mov_b32 m0, s11
	s_nop 0
	global_load_lds_dwordx4 v[240:241], off
	s_barrier
	s_and_saveexec_b64 s[48:49], s[40:41]
	s_cbranch_execz .LBB0_122
	s_barrier
	s_branch .LBB0_122

.LBB0_282:
	ds_read_b128 v[166:169], v153
	ds_read_b128 v[170:173], v153 offset:1024
	ds_read_b128 v[194:197], v153 offset:2048
	ds_read_b128 v[198:201], v153 offset:3072
	v_add_u32_e32 v164, 0xc000, v134
	v_lshl_add_u64 v[188:189], s[70:71], 0, v[128:129]
	v_readfirstlane_b32 s23, v164
	v_add_u32_e32 v163, 0xe000, v134
	v_lshl_add_u64 v[190:191], v[188:189], 0, s[4:5]
	s_mov_b32 m0, s23
	v_readfirstlane_b32 s23, v163
	ds_read_b128 v[202:205], v154
	ds_read_b128 v[206:209], v154 offset:1024
	ds_read_b128 v[210:213], v155
	ds_read_b128 v[214:217], v155 offset:1024
	ds_read_b128 v[218:221], v156
	ds_read_b128 v[222:225], v156 offset:1024
	ds_read_b128 v[226:229], v157
	ds_read_b128 v[230:233], v157 offset:1024
	global_load_lds_dwordx4 v[190:191], off
	v_lshl_add_u64 v[190:191], v[188:189], 0, s[6:7]
	s_mov_b32 m0, s23
	s_nop 0
	global_load_lds_dwordx4 v[190:191], off
	s_waitcnt lgkmcnt(8)
	s_waitcnt vmcnt(10)
	s_barrier
	s_waitcnt lgkmcnt(0)
	s_setprio 1
	s_waitcnt lgkmcnt(0)
	v_mfma_f32_16x16x32_bf16 v[124:127], v[166:169], v[202:205], v[124:127]
	v_mfma_f32_16x16x32_bf16 v[120:123], v[194:197], v[202:205], v[120:123]
	v_mfma_f32_16x16x32_bf16 v[116:119], v[166:169], v[210:213], v[116:119]
	v_mfma_f32_16x16x32_bf16 v[112:115], v[194:197], v[210:213], v[112:115]
	v_mfma_f32_16x16x32_bf16 v[108:111], v[166:169], v[218:221], v[108:111]
	v_mfma_f32_16x16x32_bf16 v[104:107], v[194:197], v[218:221], v[104:107]
	v_mfma_f32_16x16x32_bf16 v[100:103], v[166:169], v[226:229], v[100:103]
	v_mfma_f32_16x16x32_bf16 v[96:99], v[194:197], v[226:229], v[96:99]
	v_mfma_f32_16x16x32_bf16 v[124:127], v[170:173], v[206:209], v[124:127]
	v_mfma_f32_16x16x32_bf16 v[120:123], v[198:201], v[206:209], v[120:123]
	v_mfma_f32_16x16x32_bf16 v[116:119], v[170:173], v[214:217], v[116:119]
	v_mfma_f32_16x16x32_bf16 v[112:115], v[198:201], v[214:217], v[112:115]
	v_mfma_f32_16x16x32_bf16 v[108:111], v[170:173], v[222:225], v[108:111]
	v_mfma_f32_16x16x32_bf16 v[104:107], v[198:201], v[222:225], v[104:107]
	v_mfma_f32_16x16x32_bf16 v[100:103], v[170:173], v[230:233], v[100:103]
	v_mfma_f32_16x16x32_bf16 v[96:99], v[198:201], v[230:233], v[96:99]
	s_setprio 0
	s_barrier
	v_lshl_add_u64 v[190:191], s[48:49], 0, v[128:129]
	v_readfirstlane_b32 s23, v132
	v_lshl_add_u64 v[192:193], v[190:191], 0, s[38:39]
	s_mov_b32 m0, s23
	v_readfirstlane_b32 s23, v133
	ds_read_b128 v[234:237], v158
	ds_read_b128 v[238:241], v158 offset:1024
	ds_read_b128 v[242:245], v158 offset:2048
	ds_read_b128 v[246:249], v158 offset:3072
	global_load_lds_dwordx4 v[192:193], off
	v_lshl_add_u64 v[192:193], v[190:191], 0, s[76:77]
	s_mov_b32 m0, s23
	s_nop 0
	global_load_lds_dwordx4 v[192:193], off
	s_waitcnt vmcnt(10)
	s_barrier
	s_waitcnt lgkmcnt(0)
	s_setprio 1
	s_waitcnt lgkmcnt(0)
	v_mfma_f32_16x16x32_bf16 v[92:95], v[234:237], v[202:205], v[92:95]
	v_mfma_f32_16x16x32_bf16 v[88:91], v[242:245], v[202:205], v[88:91]
	v_mfma_f32_16x16x32_bf16 v[84:87], v[234:237], v[210:213], v[84:87]
	v_mfma_f32_16x16x32_bf16 v[80:83], v[242:245], v[210:213], v[80:83]
	v_mfma_f32_16x16x32_bf16 v[76:79], v[234:237], v[218:221], v[76:79]
	v_mfma_f32_16x16x32_bf16 v[72:75], v[242:245], v[218:221], v[72:75]
	v_mfma_f32_16x16x32_bf16 v[68:71], v[234:237], v[226:229], v[68:71]
	v_mfma_f32_16x16x32_bf16 v[64:67], v[242:245], v[226:229], v[64:67]
	v_mfma_f32_16x16x32_bf16 v[92:95], v[238:241], v[206:209], v[92:95]
	v_mfma_f32_16x16x32_bf16 v[88:91], v[246:249], v[206:209], v[88:91]
	v_mfma_f32_16x16x32_bf16 v[84:87], v[238:241], v[214:217], v[84:87]
	v_mfma_f32_16x16x32_bf16 v[80:83], v[246:249], v[214:217], v[80:83]
	v_mfma_f32_16x16x32_bf16 v[76:79], v[238:241], v[222:225], v[76:79]
	v_mfma_f32_16x16x32_bf16 v[72:75], v[246:249], v[222:225], v[72:75]
	v_mfma_f32_16x16x32_bf16 v[68:71], v[238:241], v[230:233], v[68:71]
	v_mfma_f32_16x16x32_bf16 v[64:67], v[246:249], v[230:233], v[64:67]
	s_setprio 0
	v_readfirstlane_b32 s23, v134
	v_lshl_add_u64 v[192:193], v[188:189], 0, s[8:9]
	s_mov_b32 m0, s23
	v_readfirstlane_b32 s23, v135
	s_barrier
	ds_read_b128 v[202:205], v154 offset:16384
	ds_read_b128 v[206:209], v154 offset:17408
	ds_read_b128 v[210:213], v155 offset:16384
	ds_read_b128 v[214:217], v155 offset:17408
	ds_read_b128 v[218:221], v156 offset:16384
	ds_read_b128 v[222:225], v156 offset:17408
	ds_read_b128 v[226:229], v157 offset:16384
	ds_read_b128 v[230:233], v157 offset:17408
	global_load_lds_dwordx4 v[192:193], off
	v_lshl_add_u64 v[192:193], v[188:189], 0, s[10:11]
	s_mov_b32 m0, s23
	s_nop 0
	global_load_lds_dwordx4 v[192:193], off
	s_barrier
	s_waitcnt lgkmcnt(0)
	s_setprio 1
	s_waitcnt lgkmcnt(0)
	v_mfma_f32_16x16x32_bf16 v[60:63], v[166:169], v[202:205], v[60:63]
	v_mfma_f32_16x16x32_bf16 v[56:59], v[194:197], v[202:205], v[56:59]
	v_mfma_f32_16x16x32_bf16 v[52:55], v[166:169], v[210:213], v[52:55]
	v_mfma_f32_16x16x32_bf16 v[48:51], v[194:197], v[210:213], v[48:51]
	v_mfma_f32_16x16x32_bf16 v[44:47], v[166:169], v[218:221], v[44:47]
	v_mfma_f32_16x16x32_bf16 v[40:43], v[194:197], v[218:221], v[40:43]
	v_mfma_f32_16x16x32_bf16 v[36:39], v[166:169], v[226:229], v[36:39]
	v_mfma_f32_16x16x32_bf16 v[32:35], v[194:197], v[226:229], v[32:35]
	v_mfma_f32_16x16x32_bf16 v[60:63], v[170:173], v[206:209], v[60:63]
	v_mfma_f32_16x16x32_bf16 v[56:59], v[198:201], v[206:209], v[56:59]
	v_mfma_f32_16x16x32_bf16 v[52:55], v[170:173], v[214:217], v[52:55]
	v_mfma_f32_16x16x32_bf16 v[48:51], v[198:201], v[214:217], v[48:51]
	v_mfma_f32_16x16x32_bf16 v[44:47], v[170:173], v[222:225], v[44:47]
	v_mfma_f32_16x16x32_bf16 v[40:43], v[198:201], v[222:225], v[40:43]
	v_mfma_f32_16x16x32_bf16 v[36:39], v[170:173], v[230:233], v[36:39]
	v_mfma_f32_16x16x32_bf16 v[32:35], v[198:201], v[230:233], v[32:35]
	s_setprio 0
	s_barrier
	v_readfirstlane_b32 s23, v142
	v_lshl_add_u64 v[166:167], v[190:191], 0, s[78:79]
	s_mov_b32 m0, s23
	v_readfirstlane_b32 s23, v143
	global_load_lds_dwordx4 v[166:167], off
	v_lshl_add_u64 v[166:167], v[190:191], 0, s[80:81]
	s_mov_b32 m0, s23
	s_nop 0
	global_load_lds_dwordx4 v[166:167], off
	s_waitcnt vmcnt(10)
	s_barrier
	s_setprio 1
	v_mfma_f32_16x16x32_bf16 v[28:31], v[234:237], v[202:205], v[28:31]
	v_mfma_f32_16x16x32_bf16 v[24:27], v[242:245], v[202:205], v[24:27]
	v_mfma_f32_16x16x32_bf16 v[20:23], v[234:237], v[210:213], v[20:23]
	v_mfma_f32_16x16x32_bf16 v[16:19], v[242:245], v[210:213], v[16:19]
	v_mfma_f32_16x16x32_bf16 v[12:15], v[234:237], v[218:221], v[12:15]
	v_mfma_f32_16x16x32_bf16 v[8:11], v[242:245], v[218:221], v[8:11]
	v_mfma_f32_16x16x32_bf16 v[4:7], v[234:237], v[226:229], v[4:7]
	v_mfma_f32_16x16x32_bf16 v[0:3], v[242:245], v[226:229], v[0:3]
	v_mfma_f32_16x16x32_bf16 v[28:31], v[238:241], v[206:209], v[28:31]
	v_mfma_f32_16x16x32_bf16 v[24:27], v[246:249], v[206:209], v[24:27]
	v_mfma_f32_16x16x32_bf16 v[20:23], v[238:241], v[214:217], v[20:23]
	v_mfma_f32_16x16x32_bf16 v[16:19], v[246:249], v[214:217], v[16:19]
	v_mfma_f32_16x16x32_bf16 v[12:15], v[238:241], v[222:225], v[12:15]
	v_mfma_f32_16x16x32_bf16 v[8:11], v[246:249], v[222:225], v[8:11]
	v_mfma_f32_16x16x32_bf16 v[4:7], v[238:241], v[230:233], v[4:7]
	v_mfma_f32_16x16x32_bf16 v[0:3], v[246:249], v[230:233], v[0:3]
	s_setprio 0
	s_barrier
	ds_read_b128 v[166:169], v159
	ds_read_b128 v[170:173], v159 offset:1024
	ds_read_b128 v[194:197], v159 offset:2048
	ds_read_b128 v[198:201], v159 offset:3072
	v_readfirstlane_b32 s23, v144
	v_lshl_add_u64 v[192:193], v[188:189], 0, s[34:35]
	s_mov_b32 m0, s23
	v_readfirstlane_b32 s23, v145
	ds_read_b128 v[202:205], v154 offset:32768
	ds_read_b128 v[206:209], v154 offset:33792
	ds_read_b128 v[210:213], v155 offset:32768
	ds_read_b128 v[214:217], v155 offset:33792
	ds_read_b128 v[218:221], v156 offset:32768
	ds_read_b128 v[222:225], v156 offset:33792
	ds_read_b128 v[226:229], v157 offset:32768
	ds_read_b128 v[230:233], v157 offset:33792
	global_load_lds_dwordx4 v[192:193], off
	v_lshl_add_u64 v[192:193], v[188:189], 0, s[46:47]
	s_mov_b32 m0, s23
	s_nop 0
	global_load_lds_dwordx4 v[192:193], off
	s_waitcnt lgkmcnt(8)
	s_waitcnt vmcnt(10)
	s_barrier
	s_waitcnt lgkmcnt(0)
	s_setprio 1
	s_waitcnt lgkmcnt(0)
	v_mfma_f32_16x16x32_bf16 v[124:127], v[166:169], v[202:205], v[124:127]
	v_mfma_f32_16x16x32_bf16 v[120:123], v[194:197], v[202:205], v[120:123]
	v_mfma_f32_16x16x32_bf16 v[116:119], v[166:169], v[210:213], v[116:119]
	v_mfma_f32_16x16x32_bf16 v[112:115], v[194:197], v[210:213], v[112:115]
	v_mfma_f32_16x16x32_bf16 v[108:111], v[166:169], v[218:221], v[108:111]
	v_mfma_f32_16x16x32_bf16 v[104:107], v[194:197], v[218:221], v[104:107]
	v_mfma_f32_16x16x32_bf16 v[100:103], v[166:169], v[226:229], v[100:103]
	v_mfma_f32_16x16x32_bf16 v[96:99], v[194:197], v[226:229], v[96:99]
	v_mfma_f32_16x16x32_bf16 v[124:127], v[170:173], v[206:209], v[124:127]
	v_mfma_f32_16x16x32_bf16 v[120:123], v[198:201], v[206:209], v[120:123]
	v_mfma_f32_16x16x32_bf16 v[116:119], v[170:173], v[214:217], v[116:119]
	v_mfma_f32_16x16x32_bf16 v[112:115], v[198:201], v[214:217], v[112:115]
	v_mfma_f32_16x16x32_bf16 v[108:111], v[170:173], v[222:225], v[108:111]
	v_mfma_f32_16x16x32_bf16 v[104:107], v[198:201], v[222:225], v[104:107]
	v_mfma_f32_16x16x32_bf16 v[100:103], v[170:173], v[230:233], v[100:103]
	v_mfma_f32_16x16x32_bf16 v[96:99], v[198:201], v[230:233], v[96:99]
	s_setprio 0
	s_barrier
	v_readfirstlane_b32 s23, v146
	v_lshl_add_u64 v[192:193], v[190:191], 0, s[82:83]
	s_mov_b32 m0, s23
	v_readfirstlane_b32 s23, v147
	ds_read_b128 v[234:237], v160
	ds_read_b128 v[238:241], v160 offset:1024
	ds_read_b128 v[242:245], v160 offset:2048
	ds_read_b128 v[246:249], v160 offset:3072
	global_load_lds_dwordx4 v[192:193], off
	v_lshl_add_u64 v[192:193], v[190:191], 0, s[90:91]
	s_mov_b32 m0, s23
	s_nop 0
	global_load_lds_dwordx4 v[192:193], off
	s_waitcnt vmcnt(10)
	s_barrier
	s_waitcnt lgkmcnt(0)
	s_setprio 1
	s_waitcnt lgkmcnt(0)
	v_mfma_f32_16x16x32_bf16 v[92:95], v[234:237], v[202:205], v[92:95]
	v_mfma_f32_16x16x32_bf16 v[88:91], v[242:245], v[202:205], v[88:91]
	v_mfma_f32_16x16x32_bf16 v[84:87], v[234:237], v[210:213], v[84:87]
	v_mfma_f32_16x16x32_bf16 v[80:83], v[242:245], v[210:213], v[80:83]
	v_mfma_f32_16x16x32_bf16 v[76:79], v[234:237], v[218:221], v[76:79]
	v_mfma_f32_16x16x32_bf16 v[72:75], v[242:245], v[218:221], v[72:75]
	v_mfma_f32_16x16x32_bf16 v[68:71], v[234:237], v[226:229], v[68:71]
	v_mfma_f32_16x16x32_bf16 v[64:67], v[242:245], v[226:229], v[64:67]
	v_mfma_f32_16x16x32_bf16 v[92:95], v[238:241], v[206:209], v[92:95]
	v_mfma_f32_16x16x32_bf16 v[88:91], v[246:249], v[206:209], v[88:91]
	v_mfma_f32_16x16x32_bf16 v[84:87], v[238:241], v[214:217], v[84:87]
	v_mfma_f32_16x16x32_bf16 v[80:83], v[246:249], v[214:217], v[80:83]
	v_mfma_f32_16x16x32_bf16 v[76:79], v[238:241], v[222:225], v[76:79]
	v_mfma_f32_16x16x32_bf16 v[72:75], v[246:249], v[222:225], v[72:75]
	v_mfma_f32_16x16x32_bf16 v[68:71], v[238:241], v[230:233], v[68:71]
	v_mfma_f32_16x16x32_bf16 v[64:67], v[246:249], v[230:233], v[64:67]
	s_setprio 0
	v_readfirstlane_b32 s23, v148
	v_lshl_add_u64 v[192:193], v[188:189], 0, s[50:51]
	s_mov_b32 m0, s23
	v_readfirstlane_b32 s23, v149
	s_barrier
	ds_read_b128 v[202:205], v154 offset:49152
	ds_read_b128 v[206:209], v154 offset:50176
	ds_read_b128 v[210:213], v155 offset:49152
	ds_read_b128 v[214:217], v155 offset:50176
	ds_read_b128 v[218:221], v156 offset:49152
	ds_read_b128 v[222:225], v156 offset:50176
	ds_read_b128 v[226:229], v157 offset:49152
	ds_read_b128 v[230:233], v157 offset:50176
	global_load_lds_dwordx4 v[192:193], off
	v_lshl_add_u64 v[188:189], v[188:189], 0, s[86:87]
	s_mov_b32 m0, s23
	s_nop 0
	global_load_lds_dwordx4 v[188:189], off
	s_barrier
	s_waitcnt lgkmcnt(0)
	s_setprio 1
	s_waitcnt lgkmcnt(0)
	v_mfma_f32_16x16x32_bf16 v[60:63], v[166:169], v[202:205], v[60:63]
	v_mfma_f32_16x16x32_bf16 v[56:59], v[194:197], v[202:205], v[56:59]
	v_mfma_f32_16x16x32_bf16 v[52:55], v[166:169], v[210:213], v[52:55]
	v_mfma_f32_16x16x32_bf16 v[48:51], v[194:197], v[210:213], v[48:51]
	v_mfma_f32_16x16x32_bf16 v[44:47], v[166:169], v[218:221], v[44:47]
	v_mfma_f32_16x16x32_bf16 v[40:43], v[194:197], v[218:221], v[40:43]
	v_mfma_f32_16x16x32_bf16 v[36:39], v[166:169], v[226:229], v[36:39]
	v_mfma_f32_16x16x32_bf16 v[32:35], v[194:197], v[226:229], v[32:35]
	v_mfma_f32_16x16x32_bf16 v[60:63], v[170:173], v[206:209], v[60:63]
	v_mfma_f32_16x16x32_bf16 v[56:59], v[198:201], v[206:209], v[56:59]
	v_mfma_f32_16x16x32_bf16 v[52:55], v[170:173], v[214:217], v[52:55]
	v_mfma_f32_16x16x32_bf16 v[48:51], v[198:201], v[214:217], v[48:51]
	v_mfma_f32_16x16x32_bf16 v[44:47], v[170:173], v[222:225], v[44:47]
	v_mfma_f32_16x16x32_bf16 v[40:43], v[198:201], v[222:225], v[40:43]
	v_mfma_f32_16x16x32_bf16 v[36:39], v[170:173], v[230:233], v[36:39]
	v_mfma_f32_16x16x32_bf16 v[32:35], v[198:201], v[230:233], v[32:35]
	s_setprio 0
	s_barrier
	v_readfirstlane_b32 s23, v161
	v_lshl_add_u64 v[166:167], v[190:191], 0, s[16:17]
	s_mov_b32 m0, s23
	v_readfirstlane_b32 s23, v162
	global_load_lds_dwordx4 v[166:167], off
	v_lshl_add_u64 v[166:167], v[190:191], 0, s[18:19]
	s_mov_b32 m0, s23
	s_nop 0
	global_load_lds_dwordx4 v[166:167], off
	s_waitcnt vmcnt(10)
	s_barrier
	s_setprio 1
	v_mfma_f32_16x16x32_bf16 v[28:31], v[234:237], v[202:205], v[28:31]
	v_mfma_f32_16x16x32_bf16 v[24:27], v[242:245], v[202:205], v[24:27]
	v_mfma_f32_16x16x32_bf16 v[20:23], v[234:237], v[210:213], v[20:23]
	v_mfma_f32_16x16x32_bf16 v[16:19], v[242:245], v[210:213], v[16:19]
	v_mfma_f32_16x16x32_bf16 v[12:15], v[234:237], v[218:221], v[12:15]
	v_mfma_f32_16x16x32_bf16 v[8:11], v[242:245], v[218:221], v[8:11]
	v_mfma_f32_16x16x32_bf16 v[4:7], v[234:237], v[226:229], v[4:7]
	v_mfma_f32_16x16x32_bf16 v[0:3], v[242:245], v[226:229], v[0:3]
	v_mfma_f32_16x16x32_bf16 v[28:31], v[238:241], v[206:209], v[28:31]
	v_mfma_f32_16x16x32_bf16 v[24:27], v[246:249], v[206:209], v[24:27]
	v_mfma_f32_16x16x32_bf16 v[20:23], v[238:241], v[214:217], v[20:23]
	v_mfma_f32_16x16x32_bf16 v[16:19], v[246:249], v[214:217], v[16:19]
	v_mfma_f32_16x16x32_bf16 v[12:15], v[238:241], v[222:225], v[12:15]
	v_mfma_f32_16x16x32_bf16 v[8:11], v[246:249], v[222:225], v[8:11]
	v_mfma_f32_16x16x32_bf16 v[4:7], v[238:241], v[230:233], v[4:7]
	v_mfma_f32_16x16x32_bf16 v[0:3], v[246:249], v[230:233], v[0:3]
	s_setprio 0
	s_add_i32 s3, s3, 2
	s_add_u32 s48, s48, 0x100
	s_addc_u32 s49, s49, 0
	s_add_u32 s70, s70, 0x100
	s_addc_u32 s71, s71, 0
	s_cmp_gt_u32 s3, 11
	s_barrier
	s_cbranch_scc0 .LBB0_282
	s_mov_b64 s[4:5], 0x780
	v_readfirstlane_b32 s3, v164
	v_lshl_add_u64 v[130:131], v[130:131], 0, s[4:5]
	s_mov_b32 m0, s3
	ds_read_b128 v[132:135], v153
	ds_read_b128 v[142:145], v153 offset:1024
	ds_read_b128 v[146:149], v153 offset:2048
	ds_read_b128 v[166:169], v153 offset:3072
	ds_read_b128 v[170:173], v154
	ds_read_b128 v[194:197], v154 offset:1024
	ds_read_b128 v[198:201], v155
	ds_read_b128 v[202:205], v155 offset:1024
	ds_read_b128 v[206:209], v156
	ds_read_b128 v[210:213], v156 offset:1024
	ds_read_b128 v[214:217], v157
	ds_read_b128 v[218:221], v157 offset:1024
	global_load_lds_dwordx4 v[130:131], off
	v_lshl_add_u64 v[130:131], v[136:137], 1, s[44:45]
	s_mov_b64 s[4:5], 0x20780
	v_readfirstlane_b32 s3, v163
	v_lshl_add_u64 v[130:131], v[130:131], 0, s[4:5]
	s_mov_b32 m0, s3
	s_nop 0
	global_load_lds_dwordx4 v[130:131], off
	s_waitcnt vmcnt(10)
	s_barrier
	s_waitcnt lgkmcnt(0)
	s_setprio 1
	s_waitcnt lgkmcnt(0)
	v_mfma_f32_16x16x32_bf16 v[124:127], v[132:135], v[170:173], v[124:127]
	v_mfma_f32_16x16x32_bf16 v[120:123], v[146:149], v[170:173], v[120:123]
	v_mfma_f32_16x16x32_bf16 v[116:119], v[132:135], v[198:201], v[116:119]
	v_mfma_f32_16x16x32_bf16 v[112:115], v[146:149], v[198:201], v[112:115]
	v_mfma_f32_16x16x32_bf16 v[108:111], v[132:135], v[206:209], v[108:111]
	v_mfma_f32_16x16x32_bf16 v[104:107], v[146:149], v[206:209], v[104:107]
	v_mfma_f32_16x16x32_bf16 v[100:103], v[132:135], v[214:217], v[100:103]
	v_mfma_f32_16x16x32_bf16 v[96:99], v[146:149], v[214:217], v[96:99]
	v_mfma_f32_16x16x32_bf16 v[124:127], v[142:145], v[194:197], v[124:127]
	v_mfma_f32_16x16x32_bf16 v[120:123], v[166:169], v[194:197], v[120:123]
	v_mfma_f32_16x16x32_bf16 v[116:119], v[142:145], v[202:205], v[116:119]
	v_mfma_f32_16x16x32_bf16 v[112:115], v[166:169], v[202:205], v[112:115]
	v_mfma_f32_16x16x32_bf16 v[108:111], v[142:145], v[210:213], v[108:111]
	v_mfma_f32_16x16x32_bf16 v[104:107], v[166:169], v[210:213], v[104:107]
	v_mfma_f32_16x16x32_bf16 v[100:103], v[142:145], v[218:221], v[100:103]
	v_mfma_f32_16x16x32_bf16 v[96:99], v[166:169], v[218:221], v[96:99]
	s_setprio 0
	s_barrier
	ds_read_b128 v[162:165], v158
	ds_read_b128 v[222:225], v158 offset:1024
	ds_read_b128 v[226:229], v158 offset:2048
	ds_read_b128 v[230:233], v158 offset:3072
	s_waitcnt vmcnt(8)
	s_barrier
	s_waitcnt lgkmcnt(0)
	s_setprio 1
	s_waitcnt lgkmcnt(0)
	v_mfma_f32_16x16x32_bf16 v[84:87], v[162:165], v[198:201], v[84:87]
	v_mfma_f32_16x16x32_bf16 v[80:83], v[226:229], v[198:201], v[80:83]
	v_mfma_f32_16x16x32_bf16 v[76:79], v[162:165], v[206:209], v[76:79]
	v_mfma_f32_16x16x32_bf16 v[72:75], v[226:229], v[206:209], v[72:75]
	v_mfma_f32_16x16x32_bf16 v[68:71], v[162:165], v[214:217], v[68:71]
	v_mfma_f32_16x16x32_bf16 v[64:67], v[226:229], v[214:217], v[64:67]
	v_mfma_f32_16x16x32_bf16 v[92:95], v[162:165], v[170:173], v[92:95]
	v_mfma_f32_16x16x32_bf16 v[88:91], v[226:229], v[170:173], v[88:91]
	v_mfma_f32_16x16x32_bf16 v[84:87], v[222:225], v[202:205], v[84:87]
	v_mfma_f32_16x16x32_bf16 v[80:83], v[230:233], v[202:205], v[80:83]
	v_mfma_f32_16x16x32_bf16 v[76:79], v[222:225], v[210:213], v[76:79]
	v_mfma_f32_16x16x32_bf16 v[72:75], v[230:233], v[210:213], v[72:75]
	v_mfma_f32_16x16x32_bf16 v[68:71], v[222:225], v[218:221], v[68:71]
	v_mfma_f32_16x16x32_bf16 v[64:67], v[230:233], v[218:221], v[64:67]
	v_mfma_f32_16x16x32_bf16 v[234:237], v[222:225], v[194:197], v[92:95]
	v_mfma_f32_16x16x32_bf16 v[170:173], v[230:233], v[194:197], v[88:91]
	s_setprio 0
	s_barrier
	s_nop 0
	ds_read_b128 v[88:91], v154 offset:16384
	ds_read_b128 v[92:95], v154 offset:17408
	ds_read_b128 v[194:197], v155 offset:16384
	ds_read_b128 v[198:201], v155 offset:17408
	ds_read_b128 v[202:205], v156 offset:16384
	ds_read_b128 v[206:209], v156 offset:17408
	ds_read_b128 v[210:213], v157 offset:16384
	ds_read_b128 v[214:217], v157 offset:17408
	s_waitcnt vmcnt(4)
	s_barrier
	s_waitcnt lgkmcnt(0)
	s_setprio 1
	s_waitcnt lgkmcnt(0)
	v_mfma_f32_16x16x32_bf16 v[60:63], v[132:135], v[88:91], v[60:63]
	v_mfma_f32_16x16x32_bf16 v[56:59], v[146:149], v[88:91], v[56:59]
	v_mfma_f32_16x16x32_bf16 v[52:55], v[132:135], v[194:197], v[52:55]
	v_mfma_f32_16x16x32_bf16 v[48:51], v[146:149], v[194:197], v[48:51]
	v_mfma_f32_16x16x32_bf16 v[44:47], v[132:135], v[202:205], v[44:47]
	v_mfma_f32_16x16x32_bf16 v[40:43], v[146:149], v[202:205], v[40:43]
	v_mfma_f32_16x16x32_bf16 v[36:39], v[132:135], v[210:213], v[36:39]
	v_mfma_f32_16x16x32_bf16 v[32:35], v[146:149], v[210:213], v[32:35]
	v_mfma_f32_16x16x32_bf16 v[60:63], v[142:145], v[92:95], v[60:63]
	v_mfma_f32_16x16x32_bf16 v[56:59], v[166:169], v[92:95], v[56:59]
	v_mfma_f32_16x16x32_bf16 v[52:55], v[142:145], v[198:201], v[52:55]
	v_mfma_f32_16x16x32_bf16 v[48:51], v[166:169], v[198:201], v[48:51]
	v_mfma_f32_16x16x32_bf16 v[44:47], v[142:145], v[206:209], v[44:47]
	v_mfma_f32_16x16x32_bf16 v[40:43], v[166:169], v[206:209], v[40:43]
	v_mfma_f32_16x16x32_bf16 v[36:39], v[142:145], v[214:217], v[36:39]
	v_mfma_f32_16x16x32_bf16 v[32:35], v[166:169], v[214:217], v[32:35]
	s_setprio 0
	s_setprio 1
	v_mfma_f32_16x16x32_bf16 v[28:31], v[162:165], v[88:91], v[28:31]
	v_mfma_f32_16x16x32_bf16 v[24:27], v[226:229], v[88:91], v[24:27]
	v_mfma_f32_16x16x32_bf16 v[20:23], v[162:165], v[194:197], v[20:23]
	v_mfma_f32_16x16x32_bf16 v[16:19], v[226:229], v[194:197], v[16:19]
	v_mfma_f32_16x16x32_bf16 v[12:15], v[162:165], v[202:205], v[12:15]
	v_mfma_f32_16x16x32_bf16 v[8:11], v[226:229], v[202:205], v[8:11]
	v_mfma_f32_16x16x32_bf16 v[4:7], v[162:165], v[210:213], v[4:7]
	v_mfma_f32_16x16x32_bf16 v[0:3], v[226:229], v[210:213], v[0:3]
	v_mfma_f32_16x16x32_bf16 v[28:31], v[222:225], v[92:95], v[28:31]
	v_mfma_f32_16x16x32_bf16 v[24:27], v[230:233], v[92:95], v[24:27]
	v_mfma_f32_16x16x32_bf16 v[20:23], v[222:225], v[198:201], v[20:23]
	v_mfma_f32_16x16x32_bf16 v[16:19], v[230:233], v[198:201], v[16:19]
	v_mfma_f32_16x16x32_bf16 v[12:15], v[222:225], v[206:209], v[12:15]
	v_mfma_f32_16x16x32_bf16 v[8:11], v[230:233], v[206:209], v[8:11]
	v_mfma_f32_16x16x32_bf16 v[4:7], v[222:225], v[214:217], v[4:7]
	v_mfma_f32_16x16x32_bf16 v[0:3], v[230:233], v[214:217], v[0:3]
	s_setprio 0
	s_barrier
	ds_read_b128 v[130:133], v159
	ds_read_b128 v[142:145], v159 offset:1024
	ds_read_b128 v[146:149], v159 offset:2048
	ds_read_b128 v[162:165], v159 offset:3072
	ds_read_b128 v[166:169], v154 offset:32768
	ds_read_b128 v[194:197], v154 offset:33792
	ds_read_b128 v[198:201], v155 offset:32768
	ds_read_b128 v[202:205], v155 offset:33792
	ds_read_b128 v[206:209], v156 offset:32768
	ds_read_b128 v[210:213], v156 offset:33792
	ds_read_b128 v[214:217], v157 offset:32768
	ds_read_b128 v[218:221], v157 offset:33792
	s_waitcnt vmcnt(2)
	s_barrier
	s_waitcnt lgkmcnt(0)
	s_setprio 1
	s_waitcnt lgkmcnt(0)
	v_mfma_f32_16x16x32_bf16 v[88:91], v[130:133], v[166:169], v[124:127]
	v_mfma_f32_16x16x32_bf16 v[124:127], v[142:145], v[194:197], v[88:91]
	v_mfma_f32_16x16x32_bf16 v[88:91], v[146:149], v[166:169], v[120:123]
	v_mfma_f32_16x16x32_bf16 v[120:123], v[162:165], v[194:197], v[88:91]
	v_mfma_f32_16x16x32_bf16 v[88:91], v[130:133], v[198:201], v[116:119]
	v_mfma_f32_16x16x32_bf16 v[116:119], v[142:145], v[202:205], v[88:91]
	v_mfma_f32_16x16x32_bf16 v[88:91], v[146:149], v[198:201], v[112:115]
	v_mfma_f32_16x16x32_bf16 v[112:115], v[162:165], v[202:205], v[88:91]
	v_mfma_f32_16x16x32_bf16 v[88:91], v[130:133], v[206:209], v[108:111]
	v_mfma_f32_16x16x32_bf16 v[108:111], v[142:145], v[210:213], v[88:91]
	v_mfma_f32_16x16x32_bf16 v[88:91], v[146:149], v[206:209], v[104:107]
	v_mfma_f32_16x16x32_bf16 v[104:107], v[162:165], v[210:213], v[88:91]
	v_mfma_f32_16x16x32_bf16 v[88:91], v[130:133], v[214:217], v[100:103]
	v_mfma_f32_16x16x32_bf16 v[92:95], v[142:145], v[218:221], v[88:91]
	v_mfma_f32_16x16x32_bf16 v[88:91], v[146:149], v[214:217], v[96:99]
	v_mfma_f32_16x16x32_bf16 v[88:91], v[162:165], v[218:221], v[88:91]
	s_setprio 0
	s_barrier
	ds_read_b128 v[222:225], v160
	ds_read_b128 v[226:229], v160 offset:1024
	ds_read_b128 v[230:233], v160 offset:2048
	ds_read_b128 v[238:241], v160 offset:3072
	s_waitcnt vmcnt(0)
	s_barrier
	s_waitcnt lgkmcnt(0)
	s_setprio 1
	s_waitcnt lgkmcnt(0)
	v_mfma_f32_16x16x32_bf16 v[96:99], v[222:225], v[166:169], v[234:237]
	v_mfma_f32_16x16x32_bf16 v[100:103], v[226:229], v[194:197], v[96:99]
	v_mfma_f32_16x16x32_bf16 v[96:99], v[230:233], v[166:169], v[170:173]
	v_mfma_f32_16x16x32_bf16 v[84:87], v[222:225], v[198:201], v[84:87]
	v_mfma_f32_16x16x32_bf16 v[80:83], v[230:233], v[198:201], v[80:83]
	v_mfma_f32_16x16x32_bf16 v[76:79], v[222:225], v[206:209], v[76:79]
	v_mfma_f32_16x16x32_bf16 v[72:75], v[230:233], v[206:209], v[72:75]
	v_mfma_f32_16x16x32_bf16 v[68:71], v[222:225], v[214:217], v[68:71]
	v_mfma_f32_16x16x32_bf16 v[64:67], v[230:233], v[214:217], v[64:67]
	v_mfma_f32_16x16x32_bf16 v[96:99], v[238:241], v[194:197], v[96:99]
	v_mfma_f32_16x16x32_bf16 v[84:87], v[226:229], v[202:205], v[84:87]
	v_mfma_f32_16x16x32_bf16 v[80:83], v[238:241], v[202:205], v[80:83]
	v_mfma_f32_16x16x32_bf16 v[76:79], v[226:229], v[210:213], v[76:79]
	v_mfma_f32_16x16x32_bf16 v[72:75], v[238:241], v[210:213], v[72:75]
	v_mfma_f32_16x16x32_bf16 v[68:71], v[226:229], v[218:221], v[68:71]
	v_mfma_f32_16x16x32_bf16 v[64:67], v[238:241], v[218:221], v[64:67]
	s_setprio 0
	s_barrier
	ds_read_b128 v[166:169], v154 offset:49152
	ds_read_b128 v[170:173], v154 offset:50176
	ds_read_b128 v[194:197], v155 offset:49152
	ds_read_b128 v[198:201], v155 offset:50176
	ds_read_b128 v[202:205], v156 offset:49152
	ds_read_b128 v[206:209], v156 offset:50176
	ds_read_b128 v[210:213], v157 offset:49152
	ds_read_b128 v[214:217], v157 offset:50176
	s_barrier
	s_waitcnt lgkmcnt(0)
	s_setprio 1
	s_waitcnt lgkmcnt(0)
	v_mfma_f32_16x16x32_bf16 v[60:63], v[130:133], v[166:169], v[60:63]
	v_mfma_f32_16x16x32_bf16 v[56:59], v[146:149], v[166:169], v[56:59]
	v_mfma_f32_16x16x32_bf16 v[52:55], v[130:133], v[194:197], v[52:55]
	v_mfma_f32_16x16x32_bf16 v[48:51], v[146:149], v[194:197], v[48:51]
	v_mfma_f32_16x16x32_bf16 v[44:47], v[130:133], v[202:205], v[44:47]
	v_mfma_f32_16x16x32_bf16 v[40:43], v[146:149], v[202:205], v[40:43]
	v_mfma_f32_16x16x32_bf16 v[36:39], v[130:133], v[210:213], v[36:39]
	v_mfma_f32_16x16x32_bf16 v[32:35], v[146:149], v[210:213], v[32:35]
	v_mfma_f32_16x16x32_bf16 v[60:63], v[142:145], v[170:173], v[60:63]
	v_mfma_f32_16x16x32_bf16 v[56:59], v[162:165], v[170:173], v[56:59]
	v_mfma_f32_16x16x32_bf16 v[52:55], v[142:145], v[198:201], v[52:55]
	v_mfma_f32_16x16x32_bf16 v[48:51], v[162:165], v[198:201], v[48:51]
	v_mfma_f32_16x16x32_bf16 v[44:47], v[142:145], v[206:209], v[44:47]
	v_mfma_f32_16x16x32_bf16 v[40:43], v[162:165], v[206:209], v[40:43]
	v_mfma_f32_16x16x32_bf16 v[36:39], v[142:145], v[214:217], v[36:39]
	v_mfma_f32_16x16x32_bf16 v[32:35], v[162:165], v[214:217], v[32:35]
	s_setprio 0
	s_setprio 1
	v_mfma_f32_16x16x32_bf16 v[28:31], v[222:225], v[166:169], v[28:31]
	v_mfma_f32_16x16x32_bf16 v[24:27], v[230:233], v[166:169], v[24:27]
	v_mfma_f32_16x16x32_bf16 v[20:23], v[222:225], v[194:197], v[20:23]
	v_mfma_f32_16x16x32_bf16 v[16:19], v[230:233], v[194:197], v[16:19]
	v_mfma_f32_16x16x32_bf16 v[12:15], v[222:225], v[202:205], v[12:15]
	v_mfma_f32_16x16x32_bf16 v[8:11], v[230:233], v[202:205], v[8:11]
	v_mfma_f32_16x16x32_bf16 v[4:7], v[222:225], v[210:213], v[4:7]
	v_mfma_f32_16x16x32_bf16 v[0:3], v[230:233], v[210:213], v[0:3]
	v_mfma_f32_16x16x32_bf16 v[28:31], v[226:229], v[170:173], v[28:31]
	v_mfma_f32_16x16x32_bf16 v[24:27], v[238:241], v[170:173], v[24:27]
	v_mfma_f32_16x16x32_bf16 v[20:23], v[226:229], v[198:201], v[20:23]
	v_mfma_f32_16x16x32_bf16 v[16:19], v[238:241], v[198:201], v[16:19]
	v_mfma_f32_16x16x32_bf16 v[12:15], v[226:229], v[206:209], v[12:15]
	v_mfma_f32_16x16x32_bf16 v[8:11], v[238:241], v[206:209], v[8:11]
	v_mfma_f32_16x16x32_bf16 v[4:7], v[226:229], v[214:217], v[4:7]
	v_mfma_f32_16x16x32_bf16 v[0:3], v[238:241], v[214:217], v[0:3]
	s_setprio 0
	s_barrier
	s_and_saveexec_b64 s[44:45], s[40:41]
	s_cbranch_execz .LBB0_278
	s_barrier
	s_branch .LBB0_278

.LBB0_324:
	ds_read_b128 v[166:169], v145
	ds_read_b128 v[170:173], v145 offset:1024
	ds_read_b128 v[194:197], v145 offset:2048
	ds_read_b128 v[198:201], v145 offset:3072
	v_add_u32_e32 v164, 0xc000, v134
	v_lshl_add_u64 v[188:189], s[48:49], 0, v[128:129]
	v_readfirstlane_b32 s3, v164
	v_add_u32_e32 v163, 0xe000, v134
	v_lshl_add_u64 v[190:191], v[188:189], 0, s[4:5]
	s_mov_b32 m0, s3
	v_readfirstlane_b32 s3, v163
	ds_read_b128 v[202:205], v146
	ds_read_b128 v[206:209], v146 offset:1024
	ds_read_b128 v[210:213], v147
	ds_read_b128 v[214:217], v147 offset:1024
	ds_read_b128 v[218:221], v148
	ds_read_b128 v[222:225], v148 offset:1024
	ds_read_b128 v[226:229], v149
	ds_read_b128 v[230:233], v149 offset:1024
	global_load_lds_dwordx4 v[190:191], off
	v_lshl_add_u64 v[190:191], v[188:189], 0, s[6:7]
	s_mov_b32 m0, s3
	s_nop 0
	global_load_lds_dwordx4 v[190:191], off
	s_waitcnt lgkmcnt(8)
	s_waitcnt vmcnt(10)
	s_barrier
	s_waitcnt lgkmcnt(0)
	s_setprio 1
	s_waitcnt lgkmcnt(0)
	v_mfma_f32_16x16x32_bf16 v[124:127], v[166:169], v[202:205], v[124:127]
	v_mfma_f32_16x16x32_bf16 v[120:123], v[194:197], v[202:205], v[120:123]
	v_mfma_f32_16x16x32_bf16 v[116:119], v[166:169], v[210:213], v[116:119]
	v_mfma_f32_16x16x32_bf16 v[112:115], v[194:197], v[210:213], v[112:115]
	v_mfma_f32_16x16x32_bf16 v[108:111], v[166:169], v[218:221], v[108:111]
	v_mfma_f32_16x16x32_bf16 v[104:107], v[194:197], v[218:221], v[104:107]
	v_mfma_f32_16x16x32_bf16 v[100:103], v[166:169], v[226:229], v[100:103]
	v_mfma_f32_16x16x32_bf16 v[96:99], v[194:197], v[226:229], v[96:99]
	v_mfma_f32_16x16x32_bf16 v[124:127], v[170:173], v[206:209], v[124:127]
	v_mfma_f32_16x16x32_bf16 v[120:123], v[198:201], v[206:209], v[120:123]
	v_mfma_f32_16x16x32_bf16 v[116:119], v[170:173], v[214:217], v[116:119]
	v_mfma_f32_16x16x32_bf16 v[112:115], v[198:201], v[214:217], v[112:115]
	v_mfma_f32_16x16x32_bf16 v[108:111], v[170:173], v[222:225], v[108:111]
	v_mfma_f32_16x16x32_bf16 v[104:107], v[198:201], v[222:225], v[104:107]
	v_mfma_f32_16x16x32_bf16 v[100:103], v[170:173], v[230:233], v[100:103]
	v_mfma_f32_16x16x32_bf16 v[96:99], v[198:201], v[230:233], v[96:99]
	s_setprio 0
	s_barrier
	v_lshl_add_u64 v[190:191], s[44:45], 0, v[128:129]
	v_readfirstlane_b32 s3, v132
	v_lshl_add_u64 v[192:193], v[190:191], 0, s[12:13]
	s_mov_b32 m0, s3
	v_readfirstlane_b32 s3, v133
	ds_read_b128 v[234:237], v150
	ds_read_b128 v[238:241], v150 offset:1024
	ds_read_b128 v[242:245], v150 offset:2048
	ds_read_b128 v[246:249], v150 offset:3072
	global_load_lds_dwordx4 v[192:193], off
	v_lshl_add_u64 v[192:193], v[190:191], 0, s[16:17]
	s_mov_b32 m0, s3
	s_nop 0
	global_load_lds_dwordx4 v[192:193], off
	s_waitcnt vmcnt(10)
	s_barrier
	s_waitcnt lgkmcnt(0)
	s_setprio 1
	s_waitcnt lgkmcnt(0)
	v_mfma_f32_16x16x32_bf16 v[92:95], v[234:237], v[202:205], v[92:95]
	v_mfma_f32_16x16x32_bf16 v[88:91], v[242:245], v[202:205], v[88:91]
	v_mfma_f32_16x16x32_bf16 v[84:87], v[234:237], v[210:213], v[84:87]
	v_mfma_f32_16x16x32_bf16 v[80:83], v[242:245], v[210:213], v[80:83]
	v_mfma_f32_16x16x32_bf16 v[76:79], v[234:237], v[218:221], v[76:79]
	v_mfma_f32_16x16x32_bf16 v[72:75], v[242:245], v[218:221], v[72:75]
	v_mfma_f32_16x16x32_bf16 v[68:71], v[234:237], v[226:229], v[68:71]
	v_mfma_f32_16x16x32_bf16 v[64:67], v[242:245], v[226:229], v[64:67]
	v_mfma_f32_16x16x32_bf16 v[92:95], v[238:241], v[206:209], v[92:95]
	v_mfma_f32_16x16x32_bf16 v[88:91], v[246:249], v[206:209], v[88:91]
	v_mfma_f32_16x16x32_bf16 v[84:87], v[238:241], v[214:217], v[84:87]
	v_mfma_f32_16x16x32_bf16 v[80:83], v[246:249], v[214:217], v[80:83]
	v_mfma_f32_16x16x32_bf16 v[76:79], v[238:241], v[222:225], v[76:79]
	v_mfma_f32_16x16x32_bf16 v[72:75], v[246:249], v[222:225], v[72:75]
	v_mfma_f32_16x16x32_bf16 v[68:71], v[238:241], v[230:233], v[68:71]
	v_mfma_f32_16x16x32_bf16 v[64:67], v[246:249], v[230:233], v[64:67]
	s_setprio 0
	v_readfirstlane_b32 s3, v134
	v_lshl_add_u64 v[192:193], v[188:189], 0, s[8:9]
	s_mov_b32 m0, s3
	v_readfirstlane_b32 s3, v135
	s_barrier
	ds_read_b128 v[202:205], v146 offset:16384
	ds_read_b128 v[206:209], v146 offset:17408
	ds_read_b128 v[210:213], v147 offset:16384
	ds_read_b128 v[214:217], v147 offset:17408
	ds_read_b128 v[218:221], v148 offset:16384
	ds_read_b128 v[222:225], v148 offset:17408
	ds_read_b128 v[226:229], v149 offset:16384
	ds_read_b128 v[230:233], v149 offset:17408
	global_load_lds_dwordx4 v[192:193], off
	v_lshl_add_u64 v[192:193], v[188:189], 0, s[10:11]
	s_mov_b32 m0, s3
	s_nop 0
	global_load_lds_dwordx4 v[192:193], off
	s_barrier
	s_waitcnt lgkmcnt(0)
	s_setprio 1
	s_waitcnt lgkmcnt(0)
	v_mfma_f32_16x16x32_bf16 v[60:63], v[166:169], v[202:205], v[60:63]
	v_mfma_f32_16x16x32_bf16 v[56:59], v[194:197], v[202:205], v[56:59]
	v_mfma_f32_16x16x32_bf16 v[52:55], v[166:169], v[210:213], v[52:55]
	v_mfma_f32_16x16x32_bf16 v[48:51], v[194:197], v[210:213], v[48:51]
	v_mfma_f32_16x16x32_bf16 v[44:47], v[166:169], v[218:221], v[44:47]
	v_mfma_f32_16x16x32_bf16 v[40:43], v[194:197], v[218:221], v[40:43]
	v_mfma_f32_16x16x32_bf16 v[36:39], v[166:169], v[226:229], v[36:39]
	v_mfma_f32_16x16x32_bf16 v[32:35], v[194:197], v[226:229], v[32:35]
	v_mfma_f32_16x16x32_bf16 v[60:63], v[170:173], v[206:209], v[60:63]
	v_mfma_f32_16x16x32_bf16 v[56:59], v[198:201], v[206:209], v[56:59]
	v_mfma_f32_16x16x32_bf16 v[52:55], v[170:173], v[214:217], v[52:55]
	v_mfma_f32_16x16x32_bf16 v[48:51], v[198:201], v[214:217], v[48:51]
	v_mfma_f32_16x16x32_bf16 v[44:47], v[170:173], v[222:225], v[44:47]
	v_mfma_f32_16x16x32_bf16 v[40:43], v[198:201], v[222:225], v[40:43]
	v_mfma_f32_16x16x32_bf16 v[36:39], v[170:173], v[230:233], v[36:39]
	v_mfma_f32_16x16x32_bf16 v[32:35], v[198:201], v[230:233], v[32:35]
	s_setprio 0
	s_barrier
	v_readfirstlane_b32 s3, v153
	v_lshl_add_u64 v[166:167], v[190:191], 0, s[18:19]
	s_mov_b32 m0, s3
	v_readfirstlane_b32 s3, v154
	global_load_lds_dwordx4 v[166:167], off
	v_lshl_add_u64 v[166:167], v[190:191], 0, s[22:23]
	s_mov_b32 m0, s3
	s_nop 0
	global_load_lds_dwordx4 v[166:167], off
	s_waitcnt vmcnt(10)
	s_barrier
	s_setprio 1
	v_mfma_f32_16x16x32_bf16 v[28:31], v[234:237], v[202:205], v[28:31]
	v_mfma_f32_16x16x32_bf16 v[24:27], v[242:245], v[202:205], v[24:27]
	v_mfma_f32_16x16x32_bf16 v[20:23], v[234:237], v[210:213], v[20:23]
	v_mfma_f32_16x16x32_bf16 v[16:19], v[242:245], v[210:213], v[16:19]
	v_mfma_f32_16x16x32_bf16 v[12:15], v[234:237], v[218:221], v[12:15]
	v_mfma_f32_16x16x32_bf16 v[8:11], v[242:245], v[218:221], v[8:11]
	v_mfma_f32_16x16x32_bf16 v[4:7], v[234:237], v[226:229], v[4:7]
	v_mfma_f32_16x16x32_bf16 v[0:3], v[242:245], v[226:229], v[0:3]
	v_mfma_f32_16x16x32_bf16 v[28:31], v[238:241], v[206:209], v[28:31]
	v_mfma_f32_16x16x32_bf16 v[24:27], v[246:249], v[206:209], v[24:27]
	v_mfma_f32_16x16x32_bf16 v[20:23], v[238:241], v[214:217], v[20:23]
	v_mfma_f32_16x16x32_bf16 v[16:19], v[246:249], v[214:217], v[16:19]
	v_mfma_f32_16x16x32_bf16 v[12:15], v[238:241], v[222:225], v[12:15]
	v_mfma_f32_16x16x32_bf16 v[8:11], v[246:249], v[222:225], v[8:11]
	v_mfma_f32_16x16x32_bf16 v[4:7], v[238:241], v[230:233], v[4:7]
	v_mfma_f32_16x16x32_bf16 v[0:3], v[246:249], v[230:233], v[0:3]
	s_setprio 0
	s_barrier
	ds_read_b128 v[166:169], v151
	ds_read_b128 v[170:173], v151 offset:1024
	ds_read_b128 v[194:197], v151 offset:2048
	ds_read_b128 v[198:201], v151 offset:3072
	v_readfirstlane_b32 s3, v155
	v_lshl_add_u64 v[192:193], v[188:189], 0, s[14:15]
	s_mov_b32 m0, s3
	v_readfirstlane_b32 s3, v156
	ds_read_b128 v[202:205], v146 offset:32768
	ds_read_b128 v[206:209], v146 offset:33792
	ds_read_b128 v[210:213], v147 offset:32768
	ds_read_b128 v[214:217], v147 offset:33792
	ds_read_b128 v[218:221], v148 offset:32768
	ds_read_b128 v[222:225], v148 offset:33792
	ds_read_b128 v[226:229], v149 offset:32768
	ds_read_b128 v[230:233], v149 offset:33792
	global_load_lds_dwordx4 v[192:193], off
	v_lshl_add_u64 v[192:193], v[188:189], 0, s[46:47]
	s_mov_b32 m0, s3
	s_nop 0
	global_load_lds_dwordx4 v[192:193], off
	s_waitcnt lgkmcnt(8)
	s_waitcnt vmcnt(10)
	s_barrier
	s_waitcnt lgkmcnt(0)
	s_setprio 1
	s_waitcnt lgkmcnt(0)
	v_mfma_f32_16x16x32_bf16 v[124:127], v[166:169], v[202:205], v[124:127]
	v_mfma_f32_16x16x32_bf16 v[120:123], v[194:197], v[202:205], v[120:123]
	v_mfma_f32_16x16x32_bf16 v[116:119], v[166:169], v[210:213], v[116:119]
	v_mfma_f32_16x16x32_bf16 v[112:115], v[194:197], v[210:213], v[112:115]
	v_mfma_f32_16x16x32_bf16 v[108:111], v[166:169], v[218:221], v[108:111]
	v_mfma_f32_16x16x32_bf16 v[104:107], v[194:197], v[218:221], v[104:107]
	v_mfma_f32_16x16x32_bf16 v[100:103], v[166:169], v[226:229], v[100:103]
	v_mfma_f32_16x16x32_bf16 v[96:99], v[194:197], v[226:229], v[96:99]
	v_mfma_f32_16x16x32_bf16 v[124:127], v[170:173], v[206:209], v[124:127]
	v_mfma_f32_16x16x32_bf16 v[120:123], v[198:201], v[206:209], v[120:123]
	v_mfma_f32_16x16x32_bf16 v[116:119], v[170:173], v[214:217], v[116:119]
	v_mfma_f32_16x16x32_bf16 v[112:115], v[198:201], v[214:217], v[112:115]
	v_mfma_f32_16x16x32_bf16 v[108:111], v[170:173], v[222:225], v[108:111]
	v_mfma_f32_16x16x32_bf16 v[104:107], v[198:201], v[222:225], v[104:107]
	v_mfma_f32_16x16x32_bf16 v[100:103], v[170:173], v[230:233], v[100:103]
	v_mfma_f32_16x16x32_bf16 v[96:99], v[198:201], v[230:233], v[96:99]
	s_setprio 0
	s_barrier
	v_readfirstlane_b32 s3, v157
	v_lshl_add_u64 v[192:193], v[190:191], 0, s[34:35]
	s_mov_b32 m0, s3
	v_readfirstlane_b32 s3, v158
	ds_read_b128 v[234:237], v152
	ds_read_b128 v[238:241], v152 offset:1024
	ds_read_b128 v[242:245], v152 offset:2048
	ds_read_b128 v[246:249], v152 offset:3072
	global_load_lds_dwordx4 v[192:193], off
	v_lshl_add_u64 v[192:193], v[190:191], 0, s[38:39]
	s_mov_b32 m0, s3
	s_nop 0
	global_load_lds_dwordx4 v[192:193], off
	s_waitcnt vmcnt(10)
	s_barrier
	s_waitcnt lgkmcnt(0)
	s_setprio 1
	s_waitcnt lgkmcnt(0)
	v_mfma_f32_16x16x32_bf16 v[92:95], v[234:237], v[202:205], v[92:95]
	v_mfma_f32_16x16x32_bf16 v[88:91], v[242:245], v[202:205], v[88:91]
	v_mfma_f32_16x16x32_bf16 v[84:87], v[234:237], v[210:213], v[84:87]
	v_mfma_f32_16x16x32_bf16 v[80:83], v[242:245], v[210:213], v[80:83]
	v_mfma_f32_16x16x32_bf16 v[76:79], v[234:237], v[218:221], v[76:79]
	v_mfma_f32_16x16x32_bf16 v[72:75], v[242:245], v[218:221], v[72:75]
	v_mfma_f32_16x16x32_bf16 v[68:71], v[234:237], v[226:229], v[68:71]
	v_mfma_f32_16x16x32_bf16 v[64:67], v[242:245], v[226:229], v[64:67]
	v_mfma_f32_16x16x32_bf16 v[92:95], v[238:241], v[206:209], v[92:95]
	v_mfma_f32_16x16x32_bf16 v[88:91], v[246:249], v[206:209], v[88:91]
	v_mfma_f32_16x16x32_bf16 v[84:87], v[238:241], v[214:217], v[84:87]
	v_mfma_f32_16x16x32_bf16 v[80:83], v[246:249], v[214:217], v[80:83]
	v_mfma_f32_16x16x32_bf16 v[76:79], v[238:241], v[222:225], v[76:79]
	v_mfma_f32_16x16x32_bf16 v[72:75], v[246:249], v[222:225], v[72:75]
	v_mfma_f32_16x16x32_bf16 v[68:71], v[238:241], v[230:233], v[68:71]
	v_mfma_f32_16x16x32_bf16 v[64:67], v[246:249], v[230:233], v[64:67]
	s_setprio 0
	v_readfirstlane_b32 s3, v159
	v_lshl_add_u64 v[192:193], v[188:189], 0, s[50:51]
	s_mov_b32 m0, s3
	v_readfirstlane_b32 s3, v160
	s_barrier
	ds_read_b128 v[202:205], v146 offset:49152
	ds_read_b128 v[206:209], v146 offset:50176
	ds_read_b128 v[210:213], v147 offset:49152
	ds_read_b128 v[214:217], v147 offset:50176
	ds_read_b128 v[218:221], v148 offset:49152
	ds_read_b128 v[222:225], v148 offset:50176
	ds_read_b128 v[226:229], v149 offset:49152
	ds_read_b128 v[230:233], v149 offset:50176
	global_load_lds_dwordx4 v[192:193], off
	v_lshl_add_u64 v[188:189], v[188:189], 0, s[86:87]
	s_mov_b32 m0, s3
	s_nop 0
	global_load_lds_dwordx4 v[188:189], off
	s_barrier
	s_waitcnt lgkmcnt(0)
	s_setprio 1
	s_waitcnt lgkmcnt(0)
	v_mfma_f32_16x16x32_bf16 v[60:63], v[166:169], v[202:205], v[60:63]
	v_mfma_f32_16x16x32_bf16 v[56:59], v[194:197], v[202:205], v[56:59]
	v_mfma_f32_16x16x32_bf16 v[52:55], v[166:169], v[210:213], v[52:55]
	v_mfma_f32_16x16x32_bf16 v[48:51], v[194:197], v[210:213], v[48:51]
	v_mfma_f32_16x16x32_bf16 v[44:47], v[166:169], v[218:221], v[44:47]
	v_mfma_f32_16x16x32_bf16 v[40:43], v[194:197], v[218:221], v[40:43]
	v_mfma_f32_16x16x32_bf16 v[36:39], v[166:169], v[226:229], v[36:39]
	v_mfma_f32_16x16x32_bf16 v[32:35], v[194:197], v[226:229], v[32:35]
	v_mfma_f32_16x16x32_bf16 v[60:63], v[170:173], v[206:209], v[60:63]
	v_mfma_f32_16x16x32_bf16 v[56:59], v[198:201], v[206:209], v[56:59]
	v_mfma_f32_16x16x32_bf16 v[52:55], v[170:173], v[214:217], v[52:55]
	v_mfma_f32_16x16x32_bf16 v[48:51], v[198:201], v[214:217], v[48:51]
	v_mfma_f32_16x16x32_bf16 v[44:47], v[170:173], v[222:225], v[44:47]
	v_mfma_f32_16x16x32_bf16 v[40:43], v[198:201], v[222:225], v[40:43]
	v_mfma_f32_16x16x32_bf16 v[36:39], v[170:173], v[230:233], v[36:39]
	v_mfma_f32_16x16x32_bf16 v[32:35], v[198:201], v[230:233], v[32:35]
	s_setprio 0
	s_barrier
	v_readfirstlane_b32 s3, v161
	v_lshl_add_u64 v[166:167], v[190:191], 0, s[72:73]
	s_mov_b32 m0, s3
	v_readfirstlane_b32 s3, v162
	global_load_lds_dwordx4 v[166:167], off
	v_lshl_add_u64 v[166:167], v[190:191], 0, s[76:77]
	s_mov_b32 m0, s3
	s_nop 0
	global_load_lds_dwordx4 v[166:167], off
	s_waitcnt vmcnt(10)
	s_barrier
	s_setprio 1
	v_mfma_f32_16x16x32_bf16 v[28:31], v[234:237], v[202:205], v[28:31]
	v_mfma_f32_16x16x32_bf16 v[24:27], v[242:245], v[202:205], v[24:27]
	v_mfma_f32_16x16x32_bf16 v[20:23], v[234:237], v[210:213], v[20:23]
	v_mfma_f32_16x16x32_bf16 v[16:19], v[242:245], v[210:213], v[16:19]
	v_mfma_f32_16x16x32_bf16 v[12:15], v[234:237], v[218:221], v[12:15]
	v_mfma_f32_16x16x32_bf16 v[8:11], v[242:245], v[218:221], v[8:11]
	v_mfma_f32_16x16x32_bf16 v[4:7], v[234:237], v[226:229], v[4:7]
	v_mfma_f32_16x16x32_bf16 v[0:3], v[242:245], v[226:229], v[0:3]
	v_mfma_f32_16x16x32_bf16 v[28:31], v[238:241], v[206:209], v[28:31]
	v_mfma_f32_16x16x32_bf16 v[24:27], v[246:249], v[206:209], v[24:27]
	v_mfma_f32_16x16x32_bf16 v[20:23], v[238:241], v[214:217], v[20:23]
	v_mfma_f32_16x16x32_bf16 v[16:19], v[246:249], v[214:217], v[16:19]
	v_mfma_f32_16x16x32_bf16 v[12:15], v[238:241], v[222:225], v[12:15]
	v_mfma_f32_16x16x32_bf16 v[8:11], v[246:249], v[222:225], v[8:11]
	v_mfma_f32_16x16x32_bf16 v[4:7], v[238:241], v[230:233], v[4:7]
	v_mfma_f32_16x16x32_bf16 v[0:3], v[246:249], v[230:233], v[0:3]
	s_setprio 0
	s_add_i32 s1, s1, 2
	s_add_u32 s44, s44, 0x100
	s_addc_u32 s45, s45, 0
	s_add_u32 s48, s48, 0x100
	s_addc_u32 s49, s49, 0
	s_cmp_lt_u32 s1, 12
	s_barrier
	s_cbranch_scc1 .LBB0_324
	s_mov_b64 s[4:5], 0x780
	v_readfirstlane_b32 s1, v164
	v_lshl_add_u64 v[130:131], v[130:131], 0, s[4:5]
	s_mov_b32 m0, s1
	ds_read_b128 v[132:135], v145
	ds_read_b128 v[154:157], v145 offset:1024
	ds_read_b128 v[158:161], v145 offset:2048
	ds_read_b128 v[166:169], v145 offset:3072
	ds_read_b128 v[170:173], v146
	ds_read_b128 v[194:197], v146 offset:1024
	ds_read_b128 v[198:201], v147
	ds_read_b128 v[202:205], v147 offset:1024
	ds_read_b128 v[206:209], v148
	ds_read_b128 v[210:213], v148 offset:1024
	ds_read_b128 v[214:217], v149
	ds_read_b128 v[218:221], v149 offset:1024
	global_load_lds_dwordx4 v[130:131], off
	v_lshl_add_u64 v[130:131], v[136:137], 1, s[42:43]
	s_mov_b64 s[4:5], 0x20780
	v_readfirstlane_b32 s1, v163
	v_lshl_add_u64 v[130:131], v[130:131], 0, s[4:5]
	s_mov_b32 m0, s1
	s_nop 0
	global_load_lds_dwordx4 v[130:131], off
	s_waitcnt vmcnt(10)
	s_barrier
	s_waitcnt lgkmcnt(0)
	s_setprio 1
	s_waitcnt lgkmcnt(0)
	v_mfma_f32_16x16x32_bf16 v[124:127], v[132:135], v[170:173], v[124:127]
	v_mfma_f32_16x16x32_bf16 v[120:123], v[158:161], v[170:173], v[120:123]
	v_mfma_f32_16x16x32_bf16 v[116:119], v[132:135], v[198:201], v[116:119]
	v_mfma_f32_16x16x32_bf16 v[112:115], v[158:161], v[198:201], v[112:115]
	v_mfma_f32_16x16x32_bf16 v[108:111], v[132:135], v[206:209], v[108:111]
	v_mfma_f32_16x16x32_bf16 v[104:107], v[158:161], v[206:209], v[104:107]
	v_mfma_f32_16x16x32_bf16 v[100:103], v[132:135], v[214:217], v[100:103]
	v_mfma_f32_16x16x32_bf16 v[96:99], v[158:161], v[214:217], v[96:99]
	v_mfma_f32_16x16x32_bf16 v[124:127], v[154:157], v[194:197], v[124:127]
	v_mfma_f32_16x16x32_bf16 v[120:123], v[166:169], v[194:197], v[120:123]
	v_mfma_f32_16x16x32_bf16 v[116:119], v[154:157], v[202:205], v[116:119]
	v_mfma_f32_16x16x32_bf16 v[112:115], v[166:169], v[202:205], v[112:115]
	v_mfma_f32_16x16x32_bf16 v[108:111], v[154:157], v[210:213], v[108:111]
	v_mfma_f32_16x16x32_bf16 v[104:107], v[166:169], v[210:213], v[104:107]
	v_mfma_f32_16x16x32_bf16 v[100:103], v[154:157], v[218:221], v[100:103]
	v_mfma_f32_16x16x32_bf16 v[96:99], v[166:169], v[218:221], v[96:99]
	s_setprio 0
	s_barrier
	ds_read_b128 v[162:165], v150
	ds_read_b128 v[222:225], v150 offset:1024
	ds_read_b128 v[226:229], v150 offset:2048
	ds_read_b128 v[230:233], v150 offset:3072
	s_waitcnt vmcnt(8)
	s_barrier
	s_waitcnt lgkmcnt(0)
	s_setprio 1
	s_waitcnt lgkmcnt(0)
	v_mfma_f32_16x16x32_bf16 v[92:95], v[162:165], v[170:173], v[92:95]
	v_mfma_f32_16x16x32_bf16 v[88:91], v[226:229], v[170:173], v[88:91]
	v_mfma_f32_16x16x32_bf16 v[84:87], v[162:165], v[198:201], v[84:87]
	v_mfma_f32_16x16x32_bf16 v[80:83], v[226:229], v[198:201], v[80:83]
	v_mfma_f32_16x16x32_bf16 v[76:79], v[162:165], v[206:209], v[76:79]
	v_mfma_f32_16x16x32_bf16 v[72:75], v[226:229], v[206:209], v[72:75]
	v_mfma_f32_16x16x32_bf16 v[68:71], v[162:165], v[214:217], v[68:71]
	v_mfma_f32_16x16x32_bf16 v[64:67], v[226:229], v[214:217], v[64:67]
	v_mfma_f32_16x16x32_bf16 v[92:95], v[222:225], v[194:197], v[92:95]
	v_mfma_f32_16x16x32_bf16 v[88:91], v[230:233], v[194:197], v[88:91]
	v_mfma_f32_16x16x32_bf16 v[84:87], v[222:225], v[202:205], v[84:87]
	v_mfma_f32_16x16x32_bf16 v[80:83], v[230:233], v[202:205], v[80:83]
	v_mfma_f32_16x16x32_bf16 v[76:79], v[222:225], v[210:213], v[76:79]
	v_mfma_f32_16x16x32_bf16 v[72:75], v[230:233], v[210:213], v[72:75]
	v_mfma_f32_16x16x32_bf16 v[68:71], v[222:225], v[218:221], v[68:71]
	v_mfma_f32_16x16x32_bf16 v[64:67], v[230:233], v[218:221], v[64:67]
	s_setprio 0
	s_barrier
	ds_read_b128 v[170:173], v146 offset:16384
	ds_read_b128 v[194:197], v146 offset:17408
	ds_read_b128 v[198:201], v147 offset:16384
	ds_read_b128 v[202:205], v147 offset:17408
	ds_read_b128 v[206:209], v148 offset:16384
	ds_read_b128 v[210:213], v148 offset:17408
	ds_read_b128 v[214:217], v149 offset:16384
	ds_read_b128 v[218:221], v149 offset:17408
	s_waitcnt vmcnt(4)
	s_barrier
	s_waitcnt lgkmcnt(0)
	s_setprio 1
	s_waitcnt lgkmcnt(0)
	v_mfma_f32_16x16x32_bf16 v[60:63], v[132:135], v[170:173], v[60:63]
	v_mfma_f32_16x16x32_bf16 v[56:59], v[158:161], v[170:173], v[56:59]
	v_mfma_f32_16x16x32_bf16 v[52:55], v[132:135], v[198:201], v[52:55]
	v_mfma_f32_16x16x32_bf16 v[48:51], v[158:161], v[198:201], v[48:51]
	v_mfma_f32_16x16x32_bf16 v[44:47], v[132:135], v[206:209], v[44:47]
	v_mfma_f32_16x16x32_bf16 v[40:43], v[158:161], v[206:209], v[40:43]
	v_mfma_f32_16x16x32_bf16 v[36:39], v[132:135], v[214:217], v[36:39]
	v_mfma_f32_16x16x32_bf16 v[32:35], v[158:161], v[214:217], v[32:35]
	v_mfma_f32_16x16x32_bf16 v[60:63], v[154:157], v[194:197], v[60:63]
	v_mfma_f32_16x16x32_bf16 v[56:59], v[166:169], v[194:197], v[56:59]
	v_mfma_f32_16x16x32_bf16 v[52:55], v[154:157], v[202:205], v[52:55]
	v_mfma_f32_16x16x32_bf16 v[48:51], v[166:169], v[202:205], v[48:51]
	v_mfma_f32_16x16x32_bf16 v[44:47], v[154:157], v[210:213], v[44:47]
	v_mfma_f32_16x16x32_bf16 v[40:43], v[166:169], v[210:213], v[40:43]
	v_mfma_f32_16x16x32_bf16 v[36:39], v[154:157], v[218:221], v[36:39]
	v_mfma_f32_16x16x32_bf16 v[32:35], v[166:169], v[218:221], v[32:35]
	s_setprio 0
	s_setprio 1
	v_mfma_f32_16x16x32_bf16 v[28:31], v[162:165], v[170:173], v[28:31]
	v_mfma_f32_16x16x32_bf16 v[24:27], v[226:229], v[170:173], v[24:27]
	v_mfma_f32_16x16x32_bf16 v[20:23], v[162:165], v[198:201], v[20:23]
	v_mfma_f32_16x16x32_bf16 v[16:19], v[226:229], v[198:201], v[16:19]
	v_mfma_f32_16x16x32_bf16 v[12:15], v[162:165], v[206:209], v[12:15]
	v_mfma_f32_16x16x32_bf16 v[8:11], v[226:229], v[206:209], v[8:11]
	v_mfma_f32_16x16x32_bf16 v[4:7], v[162:165], v[214:217], v[4:7]
	v_mfma_f32_16x16x32_bf16 v[0:3], v[226:229], v[214:217], v[0:3]
	v_mfma_f32_16x16x32_bf16 v[28:31], v[222:225], v[194:197], v[28:31]
	v_mfma_f32_16x16x32_bf16 v[24:27], v[230:233], v[194:197], v[24:27]
	v_mfma_f32_16x16x32_bf16 v[20:23], v[222:225], v[202:205], v[20:23]
	v_mfma_f32_16x16x32_bf16 v[16:19], v[230:233], v[202:205], v[16:19]
	v_mfma_f32_16x16x32_bf16 v[12:15], v[222:225], v[210:213], v[12:15]
	v_mfma_f32_16x16x32_bf16 v[8:11], v[230:233], v[210:213], v[8:11]
	v_mfma_f32_16x16x32_bf16 v[4:7], v[222:225], v[218:221], v[4:7]
	v_mfma_f32_16x16x32_bf16 v[0:3], v[230:233], v[218:221], v[0:3]
	s_setprio 0
	s_barrier
	ds_read_b128 v[130:133], v151
	ds_read_b128 v[154:157], v151 offset:1024
	ds_read_b128 v[158:161], v151 offset:2048
	ds_read_b128 v[162:165], v151 offset:3072
	ds_read_b128 v[166:169], v146 offset:32768
	ds_read_b128 v[170:173], v146 offset:33792
	ds_read_b128 v[194:197], v147 offset:32768
	ds_read_b128 v[198:201], v147 offset:33792
	ds_read_b128 v[202:205], v148 offset:32768
	ds_read_b128 v[206:209], v148 offset:33792
	ds_read_b128 v[210:213], v149 offset:32768
	ds_read_b128 v[214:217], v149 offset:33792
	s_waitcnt vmcnt(2)
	s_barrier
	s_waitcnt lgkmcnt(0)
	s_setprio 1
	s_waitcnt lgkmcnt(0)
	v_mfma_f32_16x16x32_bf16 v[124:127], v[130:133], v[166:169], v[124:127]
	v_mfma_f32_16x16x32_bf16 v[120:123], v[158:161], v[166:169], v[120:123]
	v_mfma_f32_16x16x32_bf16 v[116:119], v[130:133], v[194:197], v[116:119]
	v_mfma_f32_16x16x32_bf16 v[112:115], v[158:161], v[194:197], v[112:115]
	v_mfma_f32_16x16x32_bf16 v[108:111], v[130:133], v[202:205], v[108:111]
	v_mfma_f32_16x16x32_bf16 v[104:107], v[158:161], v[202:205], v[104:107]
	v_mfma_f32_16x16x32_bf16 v[100:103], v[130:133], v[210:213], v[100:103]
	v_mfma_f32_16x16x32_bf16 v[96:99], v[158:161], v[210:213], v[96:99]
	v_mfma_f32_16x16x32_bf16 v[124:127], v[154:157], v[170:173], v[124:127]
	v_mfma_f32_16x16x32_bf16 v[120:123], v[162:165], v[170:173], v[120:123]
	v_mfma_f32_16x16x32_bf16 v[116:119], v[154:157], v[198:201], v[116:119]
	v_mfma_f32_16x16x32_bf16 v[112:115], v[162:165], v[198:201], v[112:115]
	v_mfma_f32_16x16x32_bf16 v[108:111], v[154:157], v[206:209], v[108:111]
	v_mfma_f32_16x16x32_bf16 v[104:107], v[162:165], v[206:209], v[104:107]
	v_mfma_f32_16x16x32_bf16 v[100:103], v[154:157], v[214:217], v[100:103]
	v_mfma_f32_16x16x32_bf16 v[96:99], v[162:165], v[214:217], v[96:99]
	s_setprio 0
	s_barrier
	ds_read_b128 v[218:221], v152
	ds_read_b128 v[222:225], v152 offset:1024
	ds_read_b128 v[226:229], v152 offset:2048
	ds_read_b128 v[230:233], v152 offset:3072
	s_waitcnt vmcnt(0)
	s_barrier
	s_waitcnt lgkmcnt(0)
	s_setprio 1
	s_waitcnt lgkmcnt(0)
	v_mfma_f32_16x16x32_bf16 v[92:95], v[218:221], v[166:169], v[92:95]
	v_mfma_f32_16x16x32_bf16 v[88:91], v[226:229], v[166:169], v[88:91]
	v_mfma_f32_16x16x32_bf16 v[84:87], v[218:221], v[194:197], v[84:87]
	v_mfma_f32_16x16x32_bf16 v[80:83], v[226:229], v[194:197], v[80:83]
	v_mfma_f32_16x16x32_bf16 v[76:79], v[218:221], v[202:205], v[76:79]
	v_mfma_f32_16x16x32_bf16 v[72:75], v[226:229], v[202:205], v[72:75]
	v_mfma_f32_16x16x32_bf16 v[68:71], v[218:221], v[210:213], v[68:71]
	v_mfma_f32_16x16x32_bf16 v[64:67], v[226:229], v[210:213], v[64:67]
	v_mfma_f32_16x16x32_bf16 v[92:95], v[222:225], v[170:173], v[92:95]
	v_mfma_f32_16x16x32_bf16 v[88:91], v[230:233], v[170:173], v[88:91]
	v_mfma_f32_16x16x32_bf16 v[84:87], v[222:225], v[198:201], v[84:87]
	v_mfma_f32_16x16x32_bf16 v[80:83], v[230:233], v[198:201], v[80:83]
	v_mfma_f32_16x16x32_bf16 v[76:79], v[222:225], v[206:209], v[76:79]
	v_mfma_f32_16x16x32_bf16 v[72:75], v[230:233], v[206:209], v[72:75]
	v_mfma_f32_16x16x32_bf16 v[68:71], v[222:225], v[214:217], v[68:71]
	v_mfma_f32_16x16x32_bf16 v[64:67], v[230:233], v[214:217], v[64:67]
	s_setprio 0
	s_barrier
	ds_read_b128 v[166:169], v146 offset:49152
	ds_read_b128 v[170:173], v146 offset:50176
	ds_read_b128 v[194:197], v147 offset:49152
	ds_read_b128 v[198:201], v147 offset:50176
	ds_read_b128 v[202:205], v148 offset:49152
	ds_read_b128 v[206:209], v148 offset:50176
	ds_read_b128 v[210:213], v149 offset:49152
	ds_read_b128 v[214:217], v149 offset:50176
	s_barrier
	s_waitcnt lgkmcnt(0)
	s_setprio 1
	s_waitcnt lgkmcnt(0)
	v_mfma_f32_16x16x32_bf16 v[60:63], v[130:133], v[166:169], v[60:63]
	v_mfma_f32_16x16x32_bf16 v[56:59], v[158:161], v[166:169], v[56:59]
	v_mfma_f32_16x16x32_bf16 v[52:55], v[130:133], v[194:197], v[52:55]
	v_mfma_f32_16x16x32_bf16 v[48:51], v[158:161], v[194:197], v[48:51]
	v_mfma_f32_16x16x32_bf16 v[44:47], v[130:133], v[202:205], v[44:47]
	v_mfma_f32_16x16x32_bf16 v[40:43], v[158:161], v[202:205], v[40:43]
	v_mfma_f32_16x16x32_bf16 v[36:39], v[130:133], v[210:213], v[36:39]
	v_mfma_f32_16x16x32_bf16 v[32:35], v[158:161], v[210:213], v[32:35]
	v_mfma_f32_16x16x32_bf16 v[60:63], v[154:157], v[170:173], v[60:63]
	v_mfma_f32_16x16x32_bf16 v[56:59], v[162:165], v[170:173], v[56:59]
	v_mfma_f32_16x16x32_bf16 v[52:55], v[154:157], v[198:201], v[52:55]
	v_mfma_f32_16x16x32_bf16 v[48:51], v[162:165], v[198:201], v[48:51]
	v_mfma_f32_16x16x32_bf16 v[44:47], v[154:157], v[206:209], v[44:47]
	v_mfma_f32_16x16x32_bf16 v[40:43], v[162:165], v[206:209], v[40:43]
	v_mfma_f32_16x16x32_bf16 v[36:39], v[154:157], v[214:217], v[36:39]
	v_mfma_f32_16x16x32_bf16 v[32:35], v[162:165], v[214:217], v[32:35]
	s_setprio 0
	s_setprio 1
	v_mfma_f32_16x16x32_bf16 v[28:31], v[218:221], v[166:169], v[28:31]
	v_mfma_f32_16x16x32_bf16 v[24:27], v[226:229], v[166:169], v[24:27]
	v_mfma_f32_16x16x32_bf16 v[20:23], v[218:221], v[194:197], v[20:23]
	v_mfma_f32_16x16x32_bf16 v[16:19], v[226:229], v[194:197], v[16:19]
	v_mfma_f32_16x16x32_bf16 v[12:15], v[218:221], v[202:205], v[12:15]
	v_mfma_f32_16x16x32_bf16 v[8:11], v[226:229], v[202:205], v[8:11]
	v_mfma_f32_16x16x32_bf16 v[4:7], v[218:221], v[210:213], v[4:7]
	v_mfma_f32_16x16x32_bf16 v[0:3], v[226:229], v[210:213], v[0:3]
	v_mfma_f32_16x16x32_bf16 v[28:31], v[222:225], v[170:173], v[28:31]
	v_mfma_f32_16x16x32_bf16 v[24:27], v[230:233], v[170:173], v[24:27]
	v_mfma_f32_16x16x32_bf16 v[20:23], v[222:225], v[198:201], v[20:23]
	v_mfma_f32_16x16x32_bf16 v[16:19], v[230:233], v[198:201], v[16:19]
	v_mfma_f32_16x16x32_bf16 v[12:15], v[222:225], v[206:209], v[12:15]
	v_mfma_f32_16x16x32_bf16 v[8:11], v[230:233], v[206:209], v[8:11]
	v_mfma_f32_16x16x32_bf16 v[4:7], v[222:225], v[214:217], v[4:7]
	v_mfma_f32_16x16x32_bf16 v[0:3], v[230:233], v[214:217], v[0:3]
	s_setprio 0
	s_barrier
	s_and_saveexec_b64 s[42:43], s[40:41]
	s_cbranch_execz .LBB0_320
	s_barrier
	s_branch .LBB0_320

.LBB0_340:
	ds_read_b128 v[166:169], v153
	ds_read_b128 v[170:173], v153 offset:1024
	ds_read_b128 v[194:197], v153 offset:2048
	ds_read_b128 v[198:201], v153 offset:3072
	v_add_u32_e32 v164, 0xc000, v134
	v_lshl_add_u64 v[188:189], s[70:71], 0, v[128:129]
	v_readfirstlane_b32 s23, v164
	v_add_u32_e32 v163, 0xe000, v134
	v_lshl_add_u64 v[190:191], v[188:189], 0, s[8:9]
	s_mov_b32 m0, s23
	v_readfirstlane_b32 s23, v163
	ds_read_b128 v[202:205], v154
	ds_read_b128 v[206:209], v154 offset:1024
	ds_read_b128 v[210:213], v155
	ds_read_b128 v[214:217], v155 offset:1024
	ds_read_b128 v[218:221], v156
	ds_read_b128 v[222:225], v156 offset:1024
	ds_read_b128 v[226:229], v157
	ds_read_b128 v[230:233], v157 offset:1024
	global_load_lds_dwordx4 v[190:191], off
	v_lshl_add_u64 v[190:191], v[188:189], 0, s[10:11]
	s_mov_b32 m0, s23
	s_nop 0
	global_load_lds_dwordx4 v[190:191], off
	s_waitcnt lgkmcnt(8)
	s_waitcnt vmcnt(10)
	s_barrier
	s_waitcnt lgkmcnt(0)
	s_setprio 1
	s_waitcnt lgkmcnt(0)
	v_mfma_f32_16x16x32_bf16 v[124:127], v[166:169], v[202:205], v[124:127]
	v_mfma_f32_16x16x32_bf16 v[120:123], v[194:197], v[202:205], v[120:123]
	v_mfma_f32_16x16x32_bf16 v[116:119], v[166:169], v[210:213], v[116:119]
	v_mfma_f32_16x16x32_bf16 v[112:115], v[194:197], v[210:213], v[112:115]
	v_mfma_f32_16x16x32_bf16 v[108:111], v[166:169], v[218:221], v[108:111]
	v_mfma_f32_16x16x32_bf16 v[104:107], v[194:197], v[218:221], v[104:107]
	v_mfma_f32_16x16x32_bf16 v[100:103], v[166:169], v[226:229], v[100:103]
	v_mfma_f32_16x16x32_bf16 v[96:99], v[194:197], v[226:229], v[96:99]
	v_mfma_f32_16x16x32_bf16 v[124:127], v[170:173], v[206:209], v[124:127]
	v_mfma_f32_16x16x32_bf16 v[120:123], v[198:201], v[206:209], v[120:123]
	v_mfma_f32_16x16x32_bf16 v[116:119], v[170:173], v[214:217], v[116:119]
	v_mfma_f32_16x16x32_bf16 v[112:115], v[198:201], v[214:217], v[112:115]
	v_mfma_f32_16x16x32_bf16 v[108:111], v[170:173], v[222:225], v[108:111]
	v_mfma_f32_16x16x32_bf16 v[104:107], v[198:201], v[222:225], v[104:107]
	v_mfma_f32_16x16x32_bf16 v[100:103], v[170:173], v[230:233], v[100:103]
	v_mfma_f32_16x16x32_bf16 v[96:99], v[198:201], v[230:233], v[96:99]
	s_setprio 0
	s_barrier
	v_lshl_add_u64 v[190:191], s[48:49], 0, v[128:129]
	v_readfirstlane_b32 s23, v132
	v_lshl_add_u64 v[192:193], v[190:191], 0, s[4:5]
	s_mov_b32 m0, s23
	v_readfirstlane_b32 s23, v133
	ds_read_b128 v[234:237], v158
	ds_read_b128 v[238:241], v158 offset:1024
	ds_read_b128 v[242:245], v158 offset:2048
	ds_read_b128 v[246:249], v158 offset:3072
	global_load_lds_dwordx4 v[192:193], off
	v_lshl_add_u64 v[192:193], v[190:191], 0, s[6:7]
	s_mov_b32 m0, s23
	s_nop 0
	global_load_lds_dwordx4 v[192:193], off
	s_waitcnt vmcnt(10)
	s_barrier
	s_waitcnt lgkmcnt(0)
	s_setprio 1
	s_waitcnt lgkmcnt(0)
	v_mfma_f32_16x16x32_bf16 v[92:95], v[234:237], v[202:205], v[92:95]
	v_mfma_f32_16x16x32_bf16 v[88:91], v[242:245], v[202:205], v[88:91]
	v_mfma_f32_16x16x32_bf16 v[84:87], v[234:237], v[210:213], v[84:87]
	v_mfma_f32_16x16x32_bf16 v[80:83], v[242:245], v[210:213], v[80:83]
	v_mfma_f32_16x16x32_bf16 v[76:79], v[234:237], v[218:221], v[76:79]
	v_mfma_f32_16x16x32_bf16 v[72:75], v[242:245], v[218:221], v[72:75]
	v_mfma_f32_16x16x32_bf16 v[68:71], v[234:237], v[226:229], v[68:71]
	v_mfma_f32_16x16x32_bf16 v[64:67], v[242:245], v[226:229], v[64:67]
	v_mfma_f32_16x16x32_bf16 v[92:95], v[238:241], v[206:209], v[92:95]
	v_mfma_f32_16x16x32_bf16 v[88:91], v[246:249], v[206:209], v[88:91]
	v_mfma_f32_16x16x32_bf16 v[84:87], v[238:241], v[214:217], v[84:87]
	v_mfma_f32_16x16x32_bf16 v[80:83], v[246:249], v[214:217], v[80:83]
	v_mfma_f32_16x16x32_bf16 v[76:79], v[238:241], v[222:225], v[76:79]
	v_mfma_f32_16x16x32_bf16 v[72:75], v[246:249], v[222:225], v[72:75]
	v_mfma_f32_16x16x32_bf16 v[68:71], v[238:241], v[230:233], v[68:71]
	v_mfma_f32_16x16x32_bf16 v[64:67], v[246:249], v[230:233], v[64:67]
	s_setprio 0
	v_readfirstlane_b32 s23, v134
	v_lshl_add_u64 v[192:193], v[188:189], 0, s[14:15]
	s_mov_b32 m0, s23
	v_readfirstlane_b32 s23, v135
	s_barrier
	ds_read_b128 v[202:205], v154 offset:16384
	ds_read_b128 v[206:209], v154 offset:17408
	ds_read_b128 v[210:213], v155 offset:16384
	ds_read_b128 v[214:217], v155 offset:17408
	ds_read_b128 v[218:221], v156 offset:16384
	ds_read_b128 v[222:225], v156 offset:17408
	ds_read_b128 v[226:229], v157 offset:16384
	ds_read_b128 v[230:233], v157 offset:17408
	global_load_lds_dwordx4 v[192:193], off
	v_lshl_add_u64 v[192:193], v[188:189], 0, s[38:39]
	s_mov_b32 m0, s23
	s_nop 0
	global_load_lds_dwordx4 v[192:193], off
	s_barrier
	s_waitcnt lgkmcnt(0)
	s_setprio 1
	s_waitcnt lgkmcnt(0)
	v_mfma_f32_16x16x32_bf16 v[60:63], v[166:169], v[202:205], v[60:63]
	v_mfma_f32_16x16x32_bf16 v[56:59], v[194:197], v[202:205], v[56:59]
	v_mfma_f32_16x16x32_bf16 v[52:55], v[166:169], v[210:213], v[52:55]
	v_mfma_f32_16x16x32_bf16 v[48:51], v[194:197], v[210:213], v[48:51]
	v_mfma_f32_16x16x32_bf16 v[44:47], v[166:169], v[218:221], v[44:47]
	v_mfma_f32_16x16x32_bf16 v[40:43], v[194:197], v[218:221], v[40:43]
	v_mfma_f32_16x16x32_bf16 v[36:39], v[166:169], v[226:229], v[36:39]
	v_mfma_f32_16x16x32_bf16 v[32:35], v[194:197], v[226:229], v[32:35]
	v_mfma_f32_16x16x32_bf16 v[60:63], v[170:173], v[206:209], v[60:63]
	v_mfma_f32_16x16x32_bf16 v[56:59], v[198:201], v[206:209], v[56:59]
	v_mfma_f32_16x16x32_bf16 v[52:55], v[170:173], v[214:217], v[52:55]
	v_mfma_f32_16x16x32_bf16 v[48:51], v[198:201], v[214:217], v[48:51]
	v_mfma_f32_16x16x32_bf16 v[44:47], v[170:173], v[222:225], v[44:47]
	v_mfma_f32_16x16x32_bf16 v[40:43], v[198:201], v[222:225], v[40:43]
	v_mfma_f32_16x16x32_bf16 v[36:39], v[170:173], v[230:233], v[36:39]
	v_mfma_f32_16x16x32_bf16 v[32:35], v[198:201], v[230:233], v[32:35]
	s_setprio 0
	s_barrier
	v_readfirstlane_b32 s23, v142
	v_lshl_add_u64 v[166:167], v[190:191], 0, s[34:35]
	s_mov_b32 m0, s23
	v_readfirstlane_b32 s23, v143
	global_load_lds_dwordx4 v[166:167], off
	v_lshl_add_u64 v[166:167], v[190:191], 0, s[76:77]
	s_mov_b32 m0, s23
	s_nop 0
	global_load_lds_dwordx4 v[166:167], off
	s_waitcnt vmcnt(10)
	s_barrier
	s_setprio 1
	v_mfma_f32_16x16x32_bf16 v[28:31], v[234:237], v[202:205], v[28:31]
	v_mfma_f32_16x16x32_bf16 v[24:27], v[242:245], v[202:205], v[24:27]
	v_mfma_f32_16x16x32_bf16 v[20:23], v[234:237], v[210:213], v[20:23]
	v_mfma_f32_16x16x32_bf16 v[16:19], v[242:245], v[210:213], v[16:19]
	v_mfma_f32_16x16x32_bf16 v[12:15], v[234:237], v[218:221], v[12:15]
	v_mfma_f32_16x16x32_bf16 v[8:11], v[242:245], v[218:221], v[8:11]
	v_mfma_f32_16x16x32_bf16 v[4:7], v[234:237], v[226:229], v[4:7]
	v_mfma_f32_16x16x32_bf16 v[0:3], v[242:245], v[226:229], v[0:3]
	v_mfma_f32_16x16x32_bf16 v[28:31], v[238:241], v[206:209], v[28:31]
	v_mfma_f32_16x16x32_bf16 v[24:27], v[246:249], v[206:209], v[24:27]
	v_mfma_f32_16x16x32_bf16 v[20:23], v[238:241], v[214:217], v[20:23]
	v_mfma_f32_16x16x32_bf16 v[16:19], v[246:249], v[214:217], v[16:19]
	v_mfma_f32_16x16x32_bf16 v[12:15], v[238:241], v[222:225], v[12:15]
	v_mfma_f32_16x16x32_bf16 v[8:11], v[246:249], v[222:225], v[8:11]
	v_mfma_f32_16x16x32_bf16 v[4:7], v[238:241], v[230:233], v[4:7]
	v_mfma_f32_16x16x32_bf16 v[0:3], v[246:249], v[230:233], v[0:3]
	s_setprio 0
	s_barrier
	ds_read_b128 v[166:169], v159
	ds_read_b128 v[170:173], v159 offset:1024
	ds_read_b128 v[194:197], v159 offset:2048
	ds_read_b128 v[198:201], v159 offset:3072
	v_readfirstlane_b32 s23, v144
	v_lshl_add_u64 v[192:193], v[188:189], 0, s[74:75]
	s_mov_b32 m0, s23
	v_readfirstlane_b32 s23, v145
	ds_read_b128 v[202:205], v154 offset:32768
	ds_read_b128 v[206:209], v154 offset:33792
	ds_read_b128 v[210:213], v155 offset:32768
	ds_read_b128 v[214:217], v155 offset:33792
	ds_read_b128 v[218:221], v156 offset:32768
	ds_read_b128 v[222:225], v156 offset:33792
	ds_read_b128 v[226:229], v157 offset:32768
	ds_read_b128 v[230:233], v157 offset:33792
	global_load_lds_dwordx4 v[192:193], off
	v_lshl_add_u64 v[192:193], v[188:189], 0, s[12:13]
	s_mov_b32 m0, s23
	s_nop 0
	global_load_lds_dwordx4 v[192:193], off
	s_waitcnt lgkmcnt(8)
	s_waitcnt vmcnt(10)
	s_barrier
	s_waitcnt lgkmcnt(0)
	s_setprio 1
	s_waitcnt lgkmcnt(0)
	v_mfma_f32_16x16x32_bf16 v[124:127], v[166:169], v[202:205], v[124:127]
	v_mfma_f32_16x16x32_bf16 v[120:123], v[194:197], v[202:205], v[120:123]
	v_mfma_f32_16x16x32_bf16 v[116:119], v[166:169], v[210:213], v[116:119]
	v_mfma_f32_16x16x32_bf16 v[112:115], v[194:197], v[210:213], v[112:115]
	v_mfma_f32_16x16x32_bf16 v[108:111], v[166:169], v[218:221], v[108:111]
	v_mfma_f32_16x16x32_bf16 v[104:107], v[194:197], v[218:221], v[104:107]
	v_mfma_f32_16x16x32_bf16 v[100:103], v[166:169], v[226:229], v[100:103]
	v_mfma_f32_16x16x32_bf16 v[96:99], v[194:197], v[226:229], v[96:99]
	v_mfma_f32_16x16x32_bf16 v[124:127], v[170:173], v[206:209], v[124:127]
	v_mfma_f32_16x16x32_bf16 v[120:123], v[198:201], v[206:209], v[120:123]
	v_mfma_f32_16x16x32_bf16 v[116:119], v[170:173], v[214:217], v[116:119]
	v_mfma_f32_16x16x32_bf16 v[112:115], v[198:201], v[214:217], v[112:115]
	v_mfma_f32_16x16x32_bf16 v[108:111], v[170:173], v[222:225], v[108:111]
	v_mfma_f32_16x16x32_bf16 v[104:107], v[198:201], v[222:225], v[104:107]
	v_mfma_f32_16x16x32_bf16 v[100:103], v[170:173], v[230:233], v[100:103]
	v_mfma_f32_16x16x32_bf16 v[96:99], v[198:201], v[230:233], v[96:99]
	s_setprio 0
	s_barrier
	v_readfirstlane_b32 s23, v146
	v_lshl_add_u64 v[192:193], v[190:191], 0, s[78:79]
	s_mov_b32 m0, s23
	v_readfirstlane_b32 s23, v147
	ds_read_b128 v[234:237], v160
	ds_read_b128 v[238:241], v160 offset:1024
	ds_read_b128 v[242:245], v160 offset:2048
	ds_read_b128 v[246:249], v160 offset:3072
	global_load_lds_dwordx4 v[192:193], off
	v_lshl_add_u64 v[192:193], v[190:191], 0, s[80:81]
	s_mov_b32 m0, s23
	s_nop 0
	global_load_lds_dwordx4 v[192:193], off
	s_waitcnt vmcnt(10)
	s_barrier
	s_waitcnt lgkmcnt(0)
	s_setprio 1
	s_waitcnt lgkmcnt(0)
	v_mfma_f32_16x16x32_bf16 v[92:95], v[234:237], v[202:205], v[92:95]
	v_mfma_f32_16x16x32_bf16 v[88:91], v[242:245], v[202:205], v[88:91]
	v_mfma_f32_16x16x32_bf16 v[84:87], v[234:237], v[210:213], v[84:87]
	v_mfma_f32_16x16x32_bf16 v[80:83], v[242:245], v[210:213], v[80:83]
	v_mfma_f32_16x16x32_bf16 v[76:79], v[234:237], v[218:221], v[76:79]
	v_mfma_f32_16x16x32_bf16 v[72:75], v[242:245], v[218:221], v[72:75]
	v_mfma_f32_16x16x32_bf16 v[68:71], v[234:237], v[226:229], v[68:71]
	v_mfma_f32_16x16x32_bf16 v[64:67], v[242:245], v[226:229], v[64:67]
	v_mfma_f32_16x16x32_bf16 v[92:95], v[238:241], v[206:209], v[92:95]
	v_mfma_f32_16x16x32_bf16 v[88:91], v[246:249], v[206:209], v[88:91]
	v_mfma_f32_16x16x32_bf16 v[84:87], v[238:241], v[214:217], v[84:87]
	v_mfma_f32_16x16x32_bf16 v[80:83], v[246:249], v[214:217], v[80:83]
	v_mfma_f32_16x16x32_bf16 v[76:79], v[238:241], v[222:225], v[76:79]
	v_mfma_f32_16x16x32_bf16 v[72:75], v[246:249], v[222:225], v[72:75]
	v_mfma_f32_16x16x32_bf16 v[68:71], v[238:241], v[230:233], v[68:71]
	v_mfma_f32_16x16x32_bf16 v[64:67], v[246:249], v[230:233], v[64:67]
	s_setprio 0
	v_readfirstlane_b32 s23, v148
	v_lshl_add_u64 v[192:193], v[188:189], 0, s[18:19]
	s_mov_b32 m0, s23
	v_readfirstlane_b32 s23, v149
	s_barrier
	ds_read_b128 v[202:205], v154 offset:49152
	ds_read_b128 v[206:209], v154 offset:50176
	ds_read_b128 v[210:213], v155 offset:49152
	ds_read_b128 v[214:217], v155 offset:50176
	ds_read_b128 v[218:221], v156 offset:49152
	ds_read_b128 v[222:225], v156 offset:50176
	ds_read_b128 v[226:229], v157 offset:49152
	ds_read_b128 v[230:233], v157 offset:50176
	global_load_lds_dwordx4 v[192:193], off
	v_lshl_add_u64 v[188:189], v[188:189], 0, s[86:87]
	s_mov_b32 m0, s23
	s_nop 0
	global_load_lds_dwordx4 v[188:189], off
	s_barrier
	s_waitcnt lgkmcnt(0)
	s_setprio 1
	s_waitcnt lgkmcnt(0)
	v_mfma_f32_16x16x32_bf16 v[60:63], v[166:169], v[202:205], v[60:63]
	v_mfma_f32_16x16x32_bf16 v[56:59], v[194:197], v[202:205], v[56:59]
	v_mfma_f32_16x16x32_bf16 v[52:55], v[166:169], v[210:213], v[52:55]
	v_mfma_f32_16x16x32_bf16 v[48:51], v[194:197], v[210:213], v[48:51]
	v_mfma_f32_16x16x32_bf16 v[44:47], v[166:169], v[218:221], v[44:47]
	v_mfma_f32_16x16x32_bf16 v[40:43], v[194:197], v[218:221], v[40:43]
	v_mfma_f32_16x16x32_bf16 v[36:39], v[166:169], v[226:229], v[36:39]
	v_mfma_f32_16x16x32_bf16 v[32:35], v[194:197], v[226:229], v[32:35]
	v_mfma_f32_16x16x32_bf16 v[60:63], v[170:173], v[206:209], v[60:63]
	v_mfma_f32_16x16x32_bf16 v[56:59], v[198:201], v[206:209], v[56:59]
	v_mfma_f32_16x16x32_bf16 v[52:55], v[170:173], v[214:217], v[52:55]
	v_mfma_f32_16x16x32_bf16 v[48:51], v[198:201], v[214:217], v[48:51]
	v_mfma_f32_16x16x32_bf16 v[44:47], v[170:173], v[222:225], v[44:47]
	v_mfma_f32_16x16x32_bf16 v[40:43], v[198:201], v[222:225], v[40:43]
	v_mfma_f32_16x16x32_bf16 v[36:39], v[170:173], v[230:233], v[36:39]
	v_mfma_f32_16x16x32_bf16 v[32:35], v[198:201], v[230:233], v[32:35]
	s_setprio 0
	s_barrier
	v_readfirstlane_b32 s23, v161
	v_lshl_add_u64 v[166:167], v[190:191], 0, s[82:83]
	s_mov_b32 m0, s23
	v_readfirstlane_b32 s23, v162
	global_load_lds_dwordx4 v[166:167], off
	v_lshl_add_u64 v[166:167], v[190:191], 0, s[16:17]
	s_mov_b32 m0, s23
	s_nop 0
	global_load_lds_dwordx4 v[166:167], off
	s_waitcnt vmcnt(10)
	s_barrier
	s_setprio 1
	v_mfma_f32_16x16x32_bf16 v[28:31], v[234:237], v[202:205], v[28:31]
	v_mfma_f32_16x16x32_bf16 v[24:27], v[242:245], v[202:205], v[24:27]
	v_mfma_f32_16x16x32_bf16 v[20:23], v[234:237], v[210:213], v[20:23]
	v_mfma_f32_16x16x32_bf16 v[16:19], v[242:245], v[210:213], v[16:19]
	v_mfma_f32_16x16x32_bf16 v[12:15], v[234:237], v[218:221], v[12:15]
	v_mfma_f32_16x16x32_bf16 v[8:11], v[242:245], v[218:221], v[8:11]
	v_mfma_f32_16x16x32_bf16 v[4:7], v[234:237], v[226:229], v[4:7]
	v_mfma_f32_16x16x32_bf16 v[0:3], v[242:245], v[226:229], v[0:3]
	v_mfma_f32_16x16x32_bf16 v[28:31], v[238:241], v[206:209], v[28:31]
	v_mfma_f32_16x16x32_bf16 v[24:27], v[246:249], v[206:209], v[24:27]
	v_mfma_f32_16x16x32_bf16 v[20:23], v[238:241], v[214:217], v[20:23]
	v_mfma_f32_16x16x32_bf16 v[16:19], v[246:249], v[214:217], v[16:19]
	v_mfma_f32_16x16x32_bf16 v[12:15], v[238:241], v[222:225], v[12:15]
	v_mfma_f32_16x16x32_bf16 v[8:11], v[246:249], v[222:225], v[8:11]
	v_mfma_f32_16x16x32_bf16 v[4:7], v[238:241], v[230:233], v[4:7]
	v_mfma_f32_16x16x32_bf16 v[0:3], v[246:249], v[230:233], v[0:3]
	s_setprio 0
	s_add_i32 s3, s3, 2
	s_add_u32 s48, s48, 0x100
	s_addc_u32 s49, s49, 0
	s_add_u32 s70, s70, 0x100
	s_addc_u32 s71, s71, 0
	s_cmp_gt_u32 s3, 11
	s_barrier
	s_cbranch_scc0 .LBB0_340
	s_mov_b64 s[4:5], 0x780
	v_readfirstlane_b32 s3, v164
	v_lshl_add_u64 v[130:131], v[130:131], 0, s[4:5]
	s_mov_b32 m0, s3
	ds_read_b128 v[132:135], v153
	ds_read_b128 v[142:145], v153 offset:1024
	ds_read_b128 v[146:149], v153 offset:2048
	ds_read_b128 v[166:169], v153 offset:3072
	ds_read_b128 v[170:173], v154
	ds_read_b128 v[194:197], v154 offset:1024
	ds_read_b128 v[198:201], v155
	ds_read_b128 v[202:205], v155 offset:1024
	ds_read_b128 v[206:209], v156
	ds_read_b128 v[210:213], v156 offset:1024
	ds_read_b128 v[214:217], v157
	ds_read_b128 v[218:221], v157 offset:1024
	global_load_lds_dwordx4 v[130:131], off
	v_lshl_add_u64 v[130:131], v[136:137], 1, s[44:45]
	s_mov_b64 s[4:5], 0x20780
	v_readfirstlane_b32 s3, v163
	v_lshl_add_u64 v[130:131], v[130:131], 0, s[4:5]
	s_mov_b32 m0, s3
	s_nop 0
	global_load_lds_dwordx4 v[130:131], off
	s_waitcnt vmcnt(10)
	s_barrier
	s_waitcnt lgkmcnt(0)
	s_setprio 1
	s_waitcnt lgkmcnt(0)
	v_mfma_f32_16x16x32_bf16 v[124:127], v[132:135], v[170:173], v[124:127]
	v_mfma_f32_16x16x32_bf16 v[120:123], v[146:149], v[170:173], v[120:123]
	v_mfma_f32_16x16x32_bf16 v[116:119], v[132:135], v[198:201], v[116:119]
	v_mfma_f32_16x16x32_bf16 v[112:115], v[146:149], v[198:201], v[112:115]
	v_mfma_f32_16x16x32_bf16 v[108:111], v[132:135], v[206:209], v[108:111]
	v_mfma_f32_16x16x32_bf16 v[104:107], v[146:149], v[206:209], v[104:107]
	v_mfma_f32_16x16x32_bf16 v[100:103], v[132:135], v[214:217], v[100:103]
	v_mfma_f32_16x16x32_bf16 v[96:99], v[146:149], v[214:217], v[96:99]
	v_mfma_f32_16x16x32_bf16 v[124:127], v[142:145], v[194:197], v[124:127]
	v_mfma_f32_16x16x32_bf16 v[120:123], v[166:169], v[194:197], v[120:123]
	v_mfma_f32_16x16x32_bf16 v[116:119], v[142:145], v[202:205], v[116:119]
	v_mfma_f32_16x16x32_bf16 v[112:115], v[166:169], v[202:205], v[112:115]
	v_mfma_f32_16x16x32_bf16 v[108:111], v[142:145], v[210:213], v[108:111]
	v_mfma_f32_16x16x32_bf16 v[104:107], v[166:169], v[210:213], v[104:107]
	v_mfma_f32_16x16x32_bf16 v[100:103], v[142:145], v[218:221], v[100:103]
	v_mfma_f32_16x16x32_bf16 v[96:99], v[166:169], v[218:221], v[96:99]
	s_setprio 0
	s_barrier
	ds_read_b128 v[162:165], v158
	ds_read_b128 v[222:225], v158 offset:1024
	ds_read_b128 v[226:229], v158 offset:2048
	ds_read_b128 v[230:233], v158 offset:3072
	s_waitcnt vmcnt(8)
	s_barrier
	s_waitcnt lgkmcnt(0)
	s_setprio 1
	s_waitcnt lgkmcnt(0)
	v_mfma_f32_16x16x32_bf16 v[84:87], v[162:165], v[198:201], v[84:87]
	v_mfma_f32_16x16x32_bf16 v[80:83], v[226:229], v[198:201], v[80:83]
	v_mfma_f32_16x16x32_bf16 v[76:79], v[162:165], v[206:209], v[76:79]
	v_mfma_f32_16x16x32_bf16 v[72:75], v[226:229], v[206:209], v[72:75]
	v_mfma_f32_16x16x32_bf16 v[68:71], v[162:165], v[214:217], v[68:71]
	v_mfma_f32_16x16x32_bf16 v[64:67], v[226:229], v[214:217], v[64:67]
	v_mfma_f32_16x16x32_bf16 v[92:95], v[162:165], v[170:173], v[92:95]
	v_mfma_f32_16x16x32_bf16 v[88:91], v[226:229], v[170:173], v[88:91]
	v_mfma_f32_16x16x32_bf16 v[84:87], v[222:225], v[202:205], v[84:87]
	v_mfma_f32_16x16x32_bf16 v[80:83], v[230:233], v[202:205], v[80:83]
	v_mfma_f32_16x16x32_bf16 v[76:79], v[222:225], v[210:213], v[76:79]
	v_mfma_f32_16x16x32_bf16 v[72:75], v[230:233], v[210:213], v[72:75]
	v_mfma_f32_16x16x32_bf16 v[68:71], v[222:225], v[218:221], v[68:71]
	v_mfma_f32_16x16x32_bf16 v[64:67], v[230:233], v[218:221], v[64:67]
	v_mfma_f32_16x16x32_bf16 v[234:237], v[222:225], v[194:197], v[92:95]
	v_mfma_f32_16x16x32_bf16 v[170:173], v[230:233], v[194:197], v[88:91]
	s_setprio 0
	s_barrier
	s_nop 0
	ds_read_b128 v[88:91], v154 offset:16384
	ds_read_b128 v[92:95], v154 offset:17408
	ds_read_b128 v[194:197], v155 offset:16384
	ds_read_b128 v[198:201], v155 offset:17408
	ds_read_b128 v[202:205], v156 offset:16384
	ds_read_b128 v[206:209], v156 offset:17408
	ds_read_b128 v[210:213], v157 offset:16384
	ds_read_b128 v[214:217], v157 offset:17408
	s_waitcnt vmcnt(4)
	s_barrier
	s_waitcnt lgkmcnt(0)
	s_setprio 1
	s_waitcnt lgkmcnt(0)
	v_mfma_f32_16x16x32_bf16 v[60:63], v[132:135], v[88:91], v[60:63]
	v_mfma_f32_16x16x32_bf16 v[56:59], v[146:149], v[88:91], v[56:59]
	v_mfma_f32_16x16x32_bf16 v[52:55], v[132:135], v[194:197], v[52:55]
	v_mfma_f32_16x16x32_bf16 v[48:51], v[146:149], v[194:197], v[48:51]
	v_mfma_f32_16x16x32_bf16 v[44:47], v[132:135], v[202:205], v[44:47]
	v_mfma_f32_16x16x32_bf16 v[40:43], v[146:149], v[202:205], v[40:43]
	v_mfma_f32_16x16x32_bf16 v[36:39], v[132:135], v[210:213], v[36:39]
	v_mfma_f32_16x16x32_bf16 v[32:35], v[146:149], v[210:213], v[32:35]
	v_mfma_f32_16x16x32_bf16 v[60:63], v[142:145], v[92:95], v[60:63]
	v_mfma_f32_16x16x32_bf16 v[56:59], v[166:169], v[92:95], v[56:59]
	v_mfma_f32_16x16x32_bf16 v[52:55], v[142:145], v[198:201], v[52:55]
	v_mfma_f32_16x16x32_bf16 v[48:51], v[166:169], v[198:201], v[48:51]
	v_mfma_f32_16x16x32_bf16 v[44:47], v[142:145], v[206:209], v[44:47]
	v_mfma_f32_16x16x32_bf16 v[40:43], v[166:169], v[206:209], v[40:43]
	v_mfma_f32_16x16x32_bf16 v[36:39], v[142:145], v[214:217], v[36:39]
	v_mfma_f32_16x16x32_bf16 v[32:35], v[166:169], v[214:217], v[32:35]
	s_setprio 0
	s_setprio 1
	v_mfma_f32_16x16x32_bf16 v[28:31], v[162:165], v[88:91], v[28:31]
	v_mfma_f32_16x16x32_bf16 v[24:27], v[226:229], v[88:91], v[24:27]
	v_mfma_f32_16x16x32_bf16 v[20:23], v[162:165], v[194:197], v[20:23]
	v_mfma_f32_16x16x32_bf16 v[16:19], v[226:229], v[194:197], v[16:19]
	v_mfma_f32_16x16x32_bf16 v[12:15], v[162:165], v[202:205], v[12:15]
	v_mfma_f32_16x16x32_bf16 v[8:11], v[226:229], v[202:205], v[8:11]
	v_mfma_f32_16x16x32_bf16 v[4:7], v[162:165], v[210:213], v[4:7]
	v_mfma_f32_16x16x32_bf16 v[0:3], v[226:229], v[210:213], v[0:3]
	v_mfma_f32_16x16x32_bf16 v[28:31], v[222:225], v[92:95], v[28:31]
	v_mfma_f32_16x16x32_bf16 v[24:27], v[230:233], v[92:95], v[24:27]
	v_mfma_f32_16x16x32_bf16 v[20:23], v[222:225], v[198:201], v[20:23]
	v_mfma_f32_16x16x32_bf16 v[16:19], v[230:233], v[198:201], v[16:19]
	v_mfma_f32_16x16x32_bf16 v[12:15], v[222:225], v[206:209], v[12:15]
	v_mfma_f32_16x16x32_bf16 v[8:11], v[230:233], v[206:209], v[8:11]
	v_mfma_f32_16x16x32_bf16 v[4:7], v[222:225], v[214:217], v[4:7]
	v_mfma_f32_16x16x32_bf16 v[0:3], v[230:233], v[214:217], v[0:3]
	s_setprio 0
	s_barrier
	ds_read_b128 v[130:133], v159
	ds_read_b128 v[142:145], v159 offset:1024
	ds_read_b128 v[146:149], v159 offset:2048
	ds_read_b128 v[162:165], v159 offset:3072
	ds_read_b128 v[166:169], v154 offset:32768
	ds_read_b128 v[194:197], v154 offset:33792
	ds_read_b128 v[198:201], v155 offset:32768
	ds_read_b128 v[202:205], v155 offset:33792
	ds_read_b128 v[206:209], v156 offset:32768
	ds_read_b128 v[210:213], v156 offset:33792
	ds_read_b128 v[214:217], v157 offset:32768
	ds_read_b128 v[218:221], v157 offset:33792
	s_waitcnt vmcnt(2)
	s_barrier
	s_waitcnt lgkmcnt(0)
	s_setprio 1
	s_waitcnt lgkmcnt(0)
	v_mfma_f32_16x16x32_bf16 v[88:91], v[130:133], v[166:169], v[124:127]
	v_mfma_f32_16x16x32_bf16 v[124:127], v[142:145], v[194:197], v[88:91]
	v_mfma_f32_16x16x32_bf16 v[88:91], v[146:149], v[166:169], v[120:123]
	v_mfma_f32_16x16x32_bf16 v[120:123], v[162:165], v[194:197], v[88:91]
	v_mfma_f32_16x16x32_bf16 v[88:91], v[130:133], v[198:201], v[116:119]
	v_mfma_f32_16x16x32_bf16 v[116:119], v[142:145], v[202:205], v[88:91]
	v_mfma_f32_16x16x32_bf16 v[88:91], v[146:149], v[198:201], v[112:115]
	v_mfma_f32_16x16x32_bf16 v[112:115], v[162:165], v[202:205], v[88:91]
	v_mfma_f32_16x16x32_bf16 v[88:91], v[130:133], v[206:209], v[108:111]
	v_mfma_f32_16x16x32_bf16 v[108:111], v[142:145], v[210:213], v[88:91]
	v_mfma_f32_16x16x32_bf16 v[88:91], v[146:149], v[206:209], v[104:107]
	v_mfma_f32_16x16x32_bf16 v[104:107], v[162:165], v[210:213], v[88:91]
	v_mfma_f32_16x16x32_bf16 v[88:91], v[130:133], v[214:217], v[100:103]
	v_mfma_f32_16x16x32_bf16 v[92:95], v[142:145], v[218:221], v[88:91]
	v_mfma_f32_16x16x32_bf16 v[88:91], v[146:149], v[214:217], v[96:99]
	v_mfma_f32_16x16x32_bf16 v[88:91], v[162:165], v[218:221], v[88:91]
	s_setprio 0
	s_barrier
	ds_read_b128 v[222:225], v160
	ds_read_b128 v[226:229], v160 offset:1024
	ds_read_b128 v[230:233], v160 offset:2048
	ds_read_b128 v[238:241], v160 offset:3072
	s_waitcnt vmcnt(0)
	s_barrier
	s_waitcnt lgkmcnt(0)
	s_setprio 1
	s_waitcnt lgkmcnt(0)
	v_mfma_f32_16x16x32_bf16 v[96:99], v[222:225], v[166:169], v[234:237]
	v_mfma_f32_16x16x32_bf16 v[100:103], v[226:229], v[194:197], v[96:99]
	v_mfma_f32_16x16x32_bf16 v[96:99], v[230:233], v[166:169], v[170:173]
	v_mfma_f32_16x16x32_bf16 v[84:87], v[222:225], v[198:201], v[84:87]
	v_mfma_f32_16x16x32_bf16 v[80:83], v[230:233], v[198:201], v[80:83]
	v_mfma_f32_16x16x32_bf16 v[76:79], v[222:225], v[206:209], v[76:79]
	v_mfma_f32_16x16x32_bf16 v[72:75], v[230:233], v[206:209], v[72:75]
	v_mfma_f32_16x16x32_bf16 v[68:71], v[222:225], v[214:217], v[68:71]
	v_mfma_f32_16x16x32_bf16 v[64:67], v[230:233], v[214:217], v[64:67]
	v_mfma_f32_16x16x32_bf16 v[96:99], v[238:241], v[194:197], v[96:99]
	v_mfma_f32_16x16x32_bf16 v[84:87], v[226:229], v[202:205], v[84:87]
	v_mfma_f32_16x16x32_bf16 v[80:83], v[238:241], v[202:205], v[80:83]
	v_mfma_f32_16x16x32_bf16 v[76:79], v[226:229], v[210:213], v[76:79]
	v_mfma_f32_16x16x32_bf16 v[72:75], v[238:241], v[210:213], v[72:75]
	v_mfma_f32_16x16x32_bf16 v[68:71], v[226:229], v[218:221], v[68:71]
	v_mfma_f32_16x16x32_bf16 v[64:67], v[238:241], v[218:221], v[64:67]
	s_setprio 0
	s_barrier
	ds_read_b128 v[166:169], v154 offset:49152
	ds_read_b128 v[170:173], v154 offset:50176
	ds_read_b128 v[194:197], v155 offset:49152
	ds_read_b128 v[198:201], v155 offset:50176
	ds_read_b128 v[202:205], v156 offset:49152
	ds_read_b128 v[206:209], v156 offset:50176
	ds_read_b128 v[210:213], v157 offset:49152
	ds_read_b128 v[214:217], v157 offset:50176
	s_barrier
	s_waitcnt lgkmcnt(0)
	s_setprio 1
	s_waitcnt lgkmcnt(0)
	v_mfma_f32_16x16x32_bf16 v[60:63], v[130:133], v[166:169], v[60:63]
	v_mfma_f32_16x16x32_bf16 v[56:59], v[146:149], v[166:169], v[56:59]
	v_mfma_f32_16x16x32_bf16 v[52:55], v[130:133], v[194:197], v[52:55]
	v_mfma_f32_16x16x32_bf16 v[48:51], v[146:149], v[194:197], v[48:51]
	v_mfma_f32_16x16x32_bf16 v[44:47], v[130:133], v[202:205], v[44:47]
	v_mfma_f32_16x16x32_bf16 v[40:43], v[146:149], v[202:205], v[40:43]
	v_mfma_f32_16x16x32_bf16 v[36:39], v[130:133], v[210:213], v[36:39]
	v_mfma_f32_16x16x32_bf16 v[32:35], v[146:149], v[210:213], v[32:35]
	v_mfma_f32_16x16x32_bf16 v[60:63], v[142:145], v[170:173], v[60:63]
	v_mfma_f32_16x16x32_bf16 v[56:59], v[162:165], v[170:173], v[56:59]
	v_mfma_f32_16x16x32_bf16 v[52:55], v[142:145], v[198:201], v[52:55]
	v_mfma_f32_16x16x32_bf16 v[48:51], v[162:165], v[198:201], v[48:51]
	v_mfma_f32_16x16x32_bf16 v[44:47], v[142:145], v[206:209], v[44:47]
	v_mfma_f32_16x16x32_bf16 v[40:43], v[162:165], v[206:209], v[40:43]
	v_mfma_f32_16x16x32_bf16 v[36:39], v[142:145], v[214:217], v[36:39]
	v_mfma_f32_16x16x32_bf16 v[32:35], v[162:165], v[214:217], v[32:35]
	s_setprio 0
	s_setprio 1
	v_mfma_f32_16x16x32_bf16 v[28:31], v[222:225], v[166:169], v[28:31]
	v_mfma_f32_16x16x32_bf16 v[24:27], v[230:233], v[166:169], v[24:27]
	v_mfma_f32_16x16x32_bf16 v[20:23], v[222:225], v[194:197], v[20:23]
	v_mfma_f32_16x16x32_bf16 v[16:19], v[230:233], v[194:197], v[16:19]
	v_mfma_f32_16x16x32_bf16 v[12:15], v[222:225], v[202:205], v[12:15]
	v_mfma_f32_16x16x32_bf16 v[8:11], v[230:233], v[202:205], v[8:11]
	v_mfma_f32_16x16x32_bf16 v[4:7], v[222:225], v[210:213], v[4:7]
	v_mfma_f32_16x16x32_bf16 v[0:3], v[230:233], v[210:213], v[0:3]
	v_mfma_f32_16x16x32_bf16 v[28:31], v[226:229], v[170:173], v[28:31]
	v_mfma_f32_16x16x32_bf16 v[24:27], v[238:241], v[170:173], v[24:27]
	v_mfma_f32_16x16x32_bf16 v[20:23], v[226:229], v[198:201], v[20:23]
	v_mfma_f32_16x16x32_bf16 v[16:19], v[238:241], v[198:201], v[16:19]
	v_mfma_f32_16x16x32_bf16 v[12:15], v[226:229], v[206:209], v[12:15]
	v_mfma_f32_16x16x32_bf16 v[8:11], v[238:241], v[206:209], v[8:11]
	v_mfma_f32_16x16x32_bf16 v[4:7], v[226:229], v[214:217], v[4:7]
	v_mfma_f32_16x16x32_bf16 v[0:3], v[238:241], v[214:217], v[0:3]
	s_setprio 0
	s_barrier
	s_and_saveexec_b64 s[44:45], s[40:41]
	s_cbranch_execz .LBB0_336
	s_barrier
	s_branch .LBB0_336

.LBB0_1051:
	ds_read_b128 v[166:169], v135
	ds_read_b128 v[170:173], v135 offset:1024
	ds_read_b128 v[194:197], v135 offset:2048
	ds_read_b128 v[198:201], v135 offset:3072
	v_add_u32_e32 v164, 0xc000, v151
	v_lshl_add_u64 v[188:189], s[48:49], 0, v[128:129]
	v_readfirstlane_b32 s3, v164
	v_add_u32_e32 v163, 0xe000, v151
	v_lshl_add_u64 v[190:191], v[188:189], 0, s[4:5]
	s_mov_b32 m0, s3
	v_readfirstlane_b32 s3, v163
	ds_read_b128 v[202:205], v142
	ds_read_b128 v[206:209], v142 offset:1024
	ds_read_b128 v[210:213], v143
	ds_read_b128 v[214:217], v143 offset:1024
	ds_read_b128 v[218:221], v144
	ds_read_b128 v[222:225], v144 offset:1024
	ds_read_b128 v[226:229], v145
	ds_read_b128 v[230:233], v145 offset:1024
	global_load_lds_dwordx4 v[190:191], off
	v_lshl_add_u64 v[190:191], v[188:189], 0, s[6:7]
	s_mov_b32 m0, s3
	s_nop 0
	global_load_lds_dwordx4 v[190:191], off
	s_waitcnt lgkmcnt(8)
	s_waitcnt vmcnt(10)
	s_barrier
	s_waitcnt lgkmcnt(0)
	s_setprio 1
	s_waitcnt lgkmcnt(0)
	v_mfma_f32_16x16x32_bf16 v[124:127], v[166:169], v[202:205], v[124:127]
	v_mfma_f32_16x16x32_bf16 v[120:123], v[194:197], v[202:205], v[120:123]
	v_mfma_f32_16x16x32_bf16 v[116:119], v[166:169], v[210:213], v[116:119]
	v_mfma_f32_16x16x32_bf16 v[112:115], v[194:197], v[210:213], v[112:115]
	v_mfma_f32_16x16x32_bf16 v[108:111], v[166:169], v[218:221], v[108:111]
	v_mfma_f32_16x16x32_bf16 v[104:107], v[194:197], v[218:221], v[104:107]
	v_mfma_f32_16x16x32_bf16 v[100:103], v[166:169], v[226:229], v[100:103]
	v_mfma_f32_16x16x32_bf16 v[96:99], v[194:197], v[226:229], v[96:99]
	v_mfma_f32_16x16x32_bf16 v[124:127], v[170:173], v[206:209], v[124:127]
	v_mfma_f32_16x16x32_bf16 v[120:123], v[198:201], v[206:209], v[120:123]
	v_mfma_f32_16x16x32_bf16 v[116:119], v[170:173], v[214:217], v[116:119]
	v_mfma_f32_16x16x32_bf16 v[112:115], v[198:201], v[214:217], v[112:115]
	v_mfma_f32_16x16x32_bf16 v[108:111], v[170:173], v[222:225], v[108:111]
	v_mfma_f32_16x16x32_bf16 v[104:107], v[198:201], v[222:225], v[104:107]
	v_mfma_f32_16x16x32_bf16 v[100:103], v[170:173], v[230:233], v[100:103]
	v_mfma_f32_16x16x32_bf16 v[96:99], v[198:201], v[230:233], v[96:99]
	s_setprio 0
	s_barrier
	v_lshl_add_u64 v[190:191], s[44:45], 0, v[128:129]
	v_readfirstlane_b32 s3, v149
	v_lshl_add_u64 v[192:193], v[190:191], 0, s[12:13]
	s_mov_b32 m0, s3
	v_readfirstlane_b32 s3, v150
	ds_read_b128 v[234:237], v146
	ds_read_b128 v[238:241], v146 offset:1024
	ds_read_b128 v[242:245], v146 offset:2048
	ds_read_b128 v[246:249], v146 offset:3072
	global_load_lds_dwordx4 v[192:193], off
	v_lshl_add_u64 v[192:193], v[190:191], 0, s[16:17]
	s_mov_b32 m0, s3
	s_nop 0
	global_load_lds_dwordx4 v[192:193], off
	s_waitcnt vmcnt(10)
	s_barrier
	s_waitcnt lgkmcnt(0)
	s_setprio 1
	s_waitcnt lgkmcnt(0)
	v_mfma_f32_16x16x32_bf16 v[92:95], v[234:237], v[202:205], v[92:95]
	v_mfma_f32_16x16x32_bf16 v[88:91], v[242:245], v[202:205], v[88:91]
	v_mfma_f32_16x16x32_bf16 v[84:87], v[234:237], v[210:213], v[84:87]
	v_mfma_f32_16x16x32_bf16 v[80:83], v[242:245], v[210:213], v[80:83]
	v_mfma_f32_16x16x32_bf16 v[76:79], v[234:237], v[218:221], v[76:79]
	v_mfma_f32_16x16x32_bf16 v[72:75], v[242:245], v[218:221], v[72:75]
	v_mfma_f32_16x16x32_bf16 v[68:71], v[234:237], v[226:229], v[68:71]
	v_mfma_f32_16x16x32_bf16 v[64:67], v[242:245], v[226:229], v[64:67]
	v_mfma_f32_16x16x32_bf16 v[92:95], v[238:241], v[206:209], v[92:95]
	v_mfma_f32_16x16x32_bf16 v[88:91], v[246:249], v[206:209], v[88:91]
	v_mfma_f32_16x16x32_bf16 v[84:87], v[238:241], v[214:217], v[84:87]
	v_mfma_f32_16x16x32_bf16 v[80:83], v[246:249], v[214:217], v[80:83]
	v_mfma_f32_16x16x32_bf16 v[76:79], v[238:241], v[222:225], v[76:79]
	v_mfma_f32_16x16x32_bf16 v[72:75], v[246:249], v[222:225], v[72:75]
	v_mfma_f32_16x16x32_bf16 v[68:71], v[238:241], v[230:233], v[68:71]
	v_mfma_f32_16x16x32_bf16 v[64:67], v[246:249], v[230:233], v[64:67]
	s_setprio 0
	v_readfirstlane_b32 s3, v151
	v_lshl_add_u64 v[192:193], v[188:189], 0, s[8:9]
	s_mov_b32 m0, s3
	v_readfirstlane_b32 s3, v152
	s_barrier
	ds_read_b128 v[202:205], v142 offset:16384
	ds_read_b128 v[206:209], v142 offset:17408
	ds_read_b128 v[210:213], v143 offset:16384
	ds_read_b128 v[214:217], v143 offset:17408
	ds_read_b128 v[218:221], v144 offset:16384
	ds_read_b128 v[222:225], v144 offset:17408
	ds_read_b128 v[226:229], v145 offset:16384
	ds_read_b128 v[230:233], v145 offset:17408
	global_load_lds_dwordx4 v[192:193], off
	v_lshl_add_u64 v[192:193], v[188:189], 0, s[10:11]
	s_mov_b32 m0, s3
	s_nop 0
	global_load_lds_dwordx4 v[192:193], off
	s_barrier
	s_waitcnt lgkmcnt(0)
	s_setprio 1
	s_waitcnt lgkmcnt(0)
	v_mfma_f32_16x16x32_bf16 v[60:63], v[166:169], v[202:205], v[60:63]
	v_mfma_f32_16x16x32_bf16 v[56:59], v[194:197], v[202:205], v[56:59]
	v_mfma_f32_16x16x32_bf16 v[52:55], v[166:169], v[210:213], v[52:55]
	v_mfma_f32_16x16x32_bf16 v[48:51], v[194:197], v[210:213], v[48:51]
	v_mfma_f32_16x16x32_bf16 v[44:47], v[166:169], v[218:221], v[44:47]
	v_mfma_f32_16x16x32_bf16 v[40:43], v[194:197], v[218:221], v[40:43]
	v_mfma_f32_16x16x32_bf16 v[36:39], v[166:169], v[226:229], v[36:39]
	v_mfma_f32_16x16x32_bf16 v[32:35], v[194:197], v[226:229], v[32:35]
	v_mfma_f32_16x16x32_bf16 v[60:63], v[170:173], v[206:209], v[60:63]
	v_mfma_f32_16x16x32_bf16 v[56:59], v[198:201], v[206:209], v[56:59]
	v_mfma_f32_16x16x32_bf16 v[52:55], v[170:173], v[214:217], v[52:55]
	v_mfma_f32_16x16x32_bf16 v[48:51], v[198:201], v[214:217], v[48:51]
	v_mfma_f32_16x16x32_bf16 v[44:47], v[170:173], v[222:225], v[44:47]
	v_mfma_f32_16x16x32_bf16 v[40:43], v[198:201], v[222:225], v[40:43]
	v_mfma_f32_16x16x32_bf16 v[36:39], v[170:173], v[230:233], v[36:39]
	v_mfma_f32_16x16x32_bf16 v[32:35], v[198:201], v[230:233], v[32:35]
	s_setprio 0
	s_barrier
	v_readfirstlane_b32 s3, v153
	v_lshl_add_u64 v[166:167], v[190:191], 0, s[18:19]
	s_mov_b32 m0, s3
	v_readfirstlane_b32 s3, v154
	global_load_lds_dwordx4 v[166:167], off
	v_lshl_add_u64 v[166:167], v[190:191], 0, s[34:35]
	s_mov_b32 m0, s3
	s_nop 0
	global_load_lds_dwordx4 v[166:167], off
	s_waitcnt vmcnt(10)
	s_barrier
	s_setprio 1
	v_mfma_f32_16x16x32_bf16 v[28:31], v[234:237], v[202:205], v[28:31]
	v_mfma_f32_16x16x32_bf16 v[24:27], v[242:245], v[202:205], v[24:27]
	v_mfma_f32_16x16x32_bf16 v[20:23], v[234:237], v[210:213], v[20:23]
	v_mfma_f32_16x16x32_bf16 v[16:19], v[242:245], v[210:213], v[16:19]
	v_mfma_f32_16x16x32_bf16 v[12:15], v[234:237], v[218:221], v[12:15]
	v_mfma_f32_16x16x32_bf16 v[8:11], v[242:245], v[218:221], v[8:11]
	v_mfma_f32_16x16x32_bf16 v[4:7], v[234:237], v[226:229], v[4:7]
	v_mfma_f32_16x16x32_bf16 v[0:3], v[242:245], v[226:229], v[0:3]
	v_mfma_f32_16x16x32_bf16 v[28:31], v[238:241], v[206:209], v[28:31]
	v_mfma_f32_16x16x32_bf16 v[24:27], v[246:249], v[206:209], v[24:27]
	v_mfma_f32_16x16x32_bf16 v[20:23], v[238:241], v[214:217], v[20:23]
	v_mfma_f32_16x16x32_bf16 v[16:19], v[246:249], v[214:217], v[16:19]
	v_mfma_f32_16x16x32_bf16 v[12:15], v[238:241], v[222:225], v[12:15]
	v_mfma_f32_16x16x32_bf16 v[8:11], v[246:249], v[222:225], v[8:11]
	v_mfma_f32_16x16x32_bf16 v[4:7], v[238:241], v[230:233], v[4:7]
	v_mfma_f32_16x16x32_bf16 v[0:3], v[246:249], v[230:233], v[0:3]
	s_setprio 0
	s_barrier
	ds_read_b128 v[166:169], v147
	ds_read_b128 v[170:173], v147 offset:1024
	ds_read_b128 v[194:197], v147 offset:2048
	ds_read_b128 v[198:201], v147 offset:3072
	v_readfirstlane_b32 s3, v155
	v_lshl_add_u64 v[192:193], v[188:189], 0, s[14:15]
	s_mov_b32 m0, s3
	v_readfirstlane_b32 s3, v156
	ds_read_b128 v[202:205], v142 offset:32768
	ds_read_b128 v[206:209], v142 offset:33792
	ds_read_b128 v[210:213], v143 offset:32768
	ds_read_b128 v[214:217], v143 offset:33792
	ds_read_b128 v[218:221], v144 offset:32768
	ds_read_b128 v[222:225], v144 offset:33792
	ds_read_b128 v[226:229], v145 offset:32768
	ds_read_b128 v[230:233], v145 offset:33792
	global_load_lds_dwordx4 v[192:193], off
	v_lshl_add_u64 v[192:193], v[188:189], 0, s[46:47]
	s_mov_b32 m0, s3
	s_nop 0
	global_load_lds_dwordx4 v[192:193], off
	s_waitcnt lgkmcnt(8)
	s_waitcnt vmcnt(10)
	s_barrier
	s_waitcnt lgkmcnt(0)
	s_setprio 1
	s_waitcnt lgkmcnt(0)
	v_mfma_f32_16x16x32_bf16 v[124:127], v[166:169], v[202:205], v[124:127]
	v_mfma_f32_16x16x32_bf16 v[120:123], v[194:197], v[202:205], v[120:123]
	v_mfma_f32_16x16x32_bf16 v[116:119], v[166:169], v[210:213], v[116:119]
	v_mfma_f32_16x16x32_bf16 v[112:115], v[194:197], v[210:213], v[112:115]
	v_mfma_f32_16x16x32_bf16 v[108:111], v[166:169], v[218:221], v[108:111]
	v_mfma_f32_16x16x32_bf16 v[104:107], v[194:197], v[218:221], v[104:107]
	v_mfma_f32_16x16x32_bf16 v[100:103], v[166:169], v[226:229], v[100:103]
	v_mfma_f32_16x16x32_bf16 v[96:99], v[194:197], v[226:229], v[96:99]
	v_mfma_f32_16x16x32_bf16 v[124:127], v[170:173], v[206:209], v[124:127]
	v_mfma_f32_16x16x32_bf16 v[120:123], v[198:201], v[206:209], v[120:123]
	v_mfma_f32_16x16x32_bf16 v[116:119], v[170:173], v[214:217], v[116:119]
	v_mfma_f32_16x16x32_bf16 v[112:115], v[198:201], v[214:217], v[112:115]
	v_mfma_f32_16x16x32_bf16 v[108:111], v[170:173], v[222:225], v[108:111]
	v_mfma_f32_16x16x32_bf16 v[104:107], v[198:201], v[222:225], v[104:107]
	v_mfma_f32_16x16x32_bf16 v[100:103], v[170:173], v[230:233], v[100:103]
	v_mfma_f32_16x16x32_bf16 v[96:99], v[198:201], v[230:233], v[96:99]
	s_setprio 0
	s_barrier
	v_readfirstlane_b32 s3, v157
	v_lshl_add_u64 v[192:193], v[190:191], 0, s[38:39]
	s_mov_b32 m0, s3
	v_readfirstlane_b32 s3, v158
	ds_read_b128 v[234:237], v148
	ds_read_b128 v[238:241], v148 offset:1024
	ds_read_b128 v[242:245], v148 offset:2048
	ds_read_b128 v[246:249], v148 offset:3072
	global_load_lds_dwordx4 v[192:193], off
	v_lshl_add_u64 v[192:193], v[190:191], 0, s[70:71]
	s_mov_b32 m0, s3
	s_nop 0
	global_load_lds_dwordx4 v[192:193], off
	s_waitcnt vmcnt(10)
	s_barrier
	s_waitcnt lgkmcnt(0)
	s_setprio 1
	s_waitcnt lgkmcnt(0)
	v_mfma_f32_16x16x32_bf16 v[92:95], v[234:237], v[202:205], v[92:95]
	v_mfma_f32_16x16x32_bf16 v[88:91], v[242:245], v[202:205], v[88:91]
	v_mfma_f32_16x16x32_bf16 v[84:87], v[234:237], v[210:213], v[84:87]
	v_mfma_f32_16x16x32_bf16 v[80:83], v[242:245], v[210:213], v[80:83]
	v_mfma_f32_16x16x32_bf16 v[76:79], v[234:237], v[218:221], v[76:79]
	v_mfma_f32_16x16x32_bf16 v[72:75], v[242:245], v[218:221], v[72:75]
	v_mfma_f32_16x16x32_bf16 v[68:71], v[234:237], v[226:229], v[68:71]
	v_mfma_f32_16x16x32_bf16 v[64:67], v[242:245], v[226:229], v[64:67]
	v_mfma_f32_16x16x32_bf16 v[92:95], v[238:241], v[206:209], v[92:95]
	v_mfma_f32_16x16x32_bf16 v[88:91], v[246:249], v[206:209], v[88:91]
	v_mfma_f32_16x16x32_bf16 v[84:87], v[238:241], v[214:217], v[84:87]
	v_mfma_f32_16x16x32_bf16 v[80:83], v[246:249], v[214:217], v[80:83]
	v_mfma_f32_16x16x32_bf16 v[76:79], v[238:241], v[222:225], v[76:79]
	v_mfma_f32_16x16x32_bf16 v[72:75], v[246:249], v[222:225], v[72:75]
	v_mfma_f32_16x16x32_bf16 v[68:71], v[238:241], v[230:233], v[68:71]
	v_mfma_f32_16x16x32_bf16 v[64:67], v[246:249], v[230:233], v[64:67]
	s_setprio 0
	v_readfirstlane_b32 s3, v159
	v_lshl_add_u64 v[192:193], v[188:189], 0, s[50:51]
	s_mov_b32 m0, s3
	v_readfirstlane_b32 s3, v160
	s_barrier
	ds_read_b128 v[202:205], v142 offset:49152
	ds_read_b128 v[206:209], v142 offset:50176
	ds_read_b128 v[210:213], v143 offset:49152
	ds_read_b128 v[214:217], v143 offset:50176
	ds_read_b128 v[218:221], v144 offset:49152
	ds_read_b128 v[222:225], v144 offset:50176
	ds_read_b128 v[226:229], v145 offset:49152
	ds_read_b128 v[230:233], v145 offset:50176
	global_load_lds_dwordx4 v[192:193], off
	v_lshl_add_u64 v[188:189], v[188:189], 0, s[86:87]
	s_mov_b32 m0, s3
	s_nop 0
	global_load_lds_dwordx4 v[188:189], off
	s_barrier
	s_waitcnt lgkmcnt(0)
	s_setprio 1
	s_waitcnt lgkmcnt(0)
	v_mfma_f32_16x16x32_bf16 v[60:63], v[166:169], v[202:205], v[60:63]
	v_mfma_f32_16x16x32_bf16 v[56:59], v[194:197], v[202:205], v[56:59]
	v_mfma_f32_16x16x32_bf16 v[52:55], v[166:169], v[210:213], v[52:55]
	v_mfma_f32_16x16x32_bf16 v[48:51], v[194:197], v[210:213], v[48:51]
	v_mfma_f32_16x16x32_bf16 v[44:47], v[166:169], v[218:221], v[44:47]
	v_mfma_f32_16x16x32_bf16 v[40:43], v[194:197], v[218:221], v[40:43]
	v_mfma_f32_16x16x32_bf16 v[36:39], v[166:169], v[226:229], v[36:39]
	v_mfma_f32_16x16x32_bf16 v[32:35], v[194:197], v[226:229], v[32:35]
	v_mfma_f32_16x16x32_bf16 v[60:63], v[170:173], v[206:209], v[60:63]
	v_mfma_f32_16x16x32_bf16 v[56:59], v[198:201], v[206:209], v[56:59]
	v_mfma_f32_16x16x32_bf16 v[52:55], v[170:173], v[214:217], v[52:55]
	v_mfma_f32_16x16x32_bf16 v[48:51], v[198:201], v[214:217], v[48:51]
	v_mfma_f32_16x16x32_bf16 v[44:47], v[170:173], v[222:225], v[44:47]
	v_mfma_f32_16x16x32_bf16 v[40:43], v[198:201], v[222:225], v[40:43]
	v_mfma_f32_16x16x32_bf16 v[36:39], v[170:173], v[230:233], v[36:39]
	v_mfma_f32_16x16x32_bf16 v[32:35], v[198:201], v[230:233], v[32:35]
	s_setprio 0
	s_barrier
	v_readfirstlane_b32 s3, v161
	v_lshl_add_u64 v[166:167], v[190:191], 0, s[72:73]
	s_mov_b32 m0, s3
	v_readfirstlane_b32 s3, v162
	global_load_lds_dwordx4 v[166:167], off
	v_lshl_add_u64 v[166:167], v[190:191], 0, s[74:75]
	s_mov_b32 m0, s3
	s_nop 0
	global_load_lds_dwordx4 v[166:167], off
	s_waitcnt vmcnt(10)
	s_barrier
	s_setprio 1
	v_mfma_f32_16x16x32_bf16 v[28:31], v[234:237], v[202:205], v[28:31]
	v_mfma_f32_16x16x32_bf16 v[24:27], v[242:245], v[202:205], v[24:27]
	v_mfma_f32_16x16x32_bf16 v[20:23], v[234:237], v[210:213], v[20:23]
	v_mfma_f32_16x16x32_bf16 v[16:19], v[242:245], v[210:213], v[16:19]
	v_mfma_f32_16x16x32_bf16 v[12:15], v[234:237], v[218:221], v[12:15]
	v_mfma_f32_16x16x32_bf16 v[8:11], v[242:245], v[218:221], v[8:11]
	v_mfma_f32_16x16x32_bf16 v[4:7], v[234:237], v[226:229], v[4:7]
	v_mfma_f32_16x16x32_bf16 v[0:3], v[242:245], v[226:229], v[0:3]
	v_mfma_f32_16x16x32_bf16 v[28:31], v[238:241], v[206:209], v[28:31]
	v_mfma_f32_16x16x32_bf16 v[24:27], v[246:249], v[206:209], v[24:27]
	v_mfma_f32_16x16x32_bf16 v[20:23], v[238:241], v[214:217], v[20:23]
	v_mfma_f32_16x16x32_bf16 v[16:19], v[246:249], v[214:217], v[16:19]
	v_mfma_f32_16x16x32_bf16 v[12:15], v[238:241], v[222:225], v[12:15]
	v_mfma_f32_16x16x32_bf16 v[8:11], v[246:249], v[222:225], v[8:11]
	v_mfma_f32_16x16x32_bf16 v[4:7], v[238:241], v[230:233], v[4:7]
	v_mfma_f32_16x16x32_bf16 v[0:3], v[246:249], v[230:233], v[0:3]
	s_setprio 0
	s_add_i32 s1, s1, 2
	s_add_u32 s44, s44, 0x100
	s_addc_u32 s45, s45, 0
	s_add_u32 s48, s48, 0x100
	s_addc_u32 s49, s49, 0
	s_cmp_lt_u32 s1, 12
	s_barrier
	s_cbranch_scc1 .LBB0_1051
	s_mov_b64 s[4:5], 0x780
	v_readfirstlane_b32 s1, v164
	v_lshl_add_u64 v[130:131], v[130:131], 0, s[4:5]
	s_mov_b32 m0, s1
	ds_read_b128 v[150:153], v135
	ds_read_b128 v[154:157], v135 offset:1024
	ds_read_b128 v[158:161], v135 offset:2048
	ds_read_b128 v[166:169], v135 offset:3072
	ds_read_b128 v[170:173], v142
	ds_read_b128 v[194:197], v142 offset:1024
	ds_read_b128 v[198:201], v143
	ds_read_b128 v[202:205], v143 offset:1024
	ds_read_b128 v[206:209], v144
	ds_read_b128 v[210:213], v144 offset:1024
	ds_read_b128 v[214:217], v145
	ds_read_b128 v[218:221], v145 offset:1024
	global_load_lds_dwordx4 v[130:131], off
	v_lshl_add_u64 v[130:131], v[136:137], 1, s[42:43]
	s_mov_b64 s[4:5], 0x20780
	v_readfirstlane_b32 s1, v163
	v_lshl_add_u64 v[130:131], v[130:131], 0, s[4:5]
	s_mov_b32 m0, s1
	s_nop 0
	global_load_lds_dwordx4 v[130:131], off
	s_waitcnt vmcnt(10)
	s_barrier
	s_waitcnt lgkmcnt(0)
	s_setprio 1
	s_waitcnt lgkmcnt(0)
	v_mfma_f32_16x16x32_bf16 v[124:127], v[150:153], v[170:173], v[124:127]
	v_mfma_f32_16x16x32_bf16 v[120:123], v[158:161], v[170:173], v[120:123]
	v_mfma_f32_16x16x32_bf16 v[116:119], v[150:153], v[198:201], v[116:119]
	v_mfma_f32_16x16x32_bf16 v[112:115], v[158:161], v[198:201], v[112:115]
	v_mfma_f32_16x16x32_bf16 v[108:111], v[150:153], v[206:209], v[108:111]
	v_mfma_f32_16x16x32_bf16 v[104:107], v[158:161], v[206:209], v[104:107]
	v_mfma_f32_16x16x32_bf16 v[100:103], v[150:153], v[214:217], v[100:103]
	v_mfma_f32_16x16x32_bf16 v[96:99], v[158:161], v[214:217], v[96:99]
	v_mfma_f32_16x16x32_bf16 v[124:127], v[154:157], v[194:197], v[124:127]
	v_mfma_f32_16x16x32_bf16 v[120:123], v[166:169], v[194:197], v[120:123]
	v_mfma_f32_16x16x32_bf16 v[116:119], v[154:157], v[202:205], v[116:119]
	v_mfma_f32_16x16x32_bf16 v[112:115], v[166:169], v[202:205], v[112:115]
	v_mfma_f32_16x16x32_bf16 v[108:111], v[154:157], v[210:213], v[108:111]
	v_mfma_f32_16x16x32_bf16 v[104:107], v[166:169], v[210:213], v[104:107]
	v_mfma_f32_16x16x32_bf16 v[100:103], v[154:157], v[218:221], v[100:103]
	v_mfma_f32_16x16x32_bf16 v[96:99], v[166:169], v[218:221], v[96:99]
	s_setprio 0
	s_barrier
	ds_read_b128 v[162:165], v146
	ds_read_b128 v[222:225], v146 offset:1024
	ds_read_b128 v[226:229], v146 offset:2048
	ds_read_b128 v[230:233], v146 offset:3072
	s_waitcnt vmcnt(8)
	s_barrier
	s_waitcnt lgkmcnt(0)
	s_setprio 1
	s_waitcnt lgkmcnt(0)
	v_mfma_f32_16x16x32_bf16 v[88:91], v[226:229], v[170:173], v[88:91]
	v_mfma_f32_16x16x32_bf16 v[80:83], v[226:229], v[198:201], v[80:83]
	v_mfma_f32_16x16x32_bf16 v[76:79], v[162:165], v[206:209], v[76:79]
	v_mfma_f32_16x16x32_bf16 v[72:75], v[226:229], v[206:209], v[72:75]
	v_mfma_f32_16x16x32_bf16 v[64:67], v[226:229], v[214:217], v[64:67]
	v_mfma_f32_16x16x32_bf16 v[92:95], v[162:165], v[170:173], v[92:95]
	v_mfma_f32_16x16x32_bf16 v[88:91], v[230:233], v[194:197], v[88:91]
	v_mfma_f32_16x16x32_bf16 v[84:87], v[162:165], v[198:201], v[84:87]
	v_mfma_f32_16x16x32_bf16 v[80:83], v[230:233], v[202:205], v[80:83]
	v_mfma_f32_16x16x32_bf16 v[76:79], v[222:225], v[210:213], v[76:79]
	v_mfma_f32_16x16x32_bf16 v[72:75], v[230:233], v[210:213], v[72:75]
	v_mfma_f32_16x16x32_bf16 v[68:71], v[162:165], v[214:217], v[68:71]
	v_mfma_f32_16x16x32_bf16 v[64:67], v[230:233], v[218:221], v[64:67]
	v_mfma_f32_16x16x32_bf16 v[234:237], v[222:225], v[194:197], v[92:95]
	v_mfma_f32_16x16x32_bf16 v[170:173], v[222:225], v[202:205], v[84:87]
	v_mfma_f32_16x16x32_bf16 v[194:197], v[222:225], v[218:221], v[68:71]
	s_setprio 0
	s_barrier
	s_nop 1
	ds_read_b128 v[68:71], v142 offset:16384
	ds_read_b128 v[84:87], v142 offset:17408
	ds_read_b128 v[92:95], v143 offset:16384
	ds_read_b128 v[198:201], v143 offset:17408
	ds_read_b128 v[202:205], v144 offset:16384
	ds_read_b128 v[206:209], v144 offset:17408
	ds_read_b128 v[210:213], v145 offset:16384
	ds_read_b128 v[214:217], v145 offset:17408
	s_waitcnt vmcnt(4)
	s_barrier
	s_waitcnt lgkmcnt(0)
	s_setprio 1
	s_waitcnt lgkmcnt(0)
	v_mfma_f32_16x16x32_bf16 v[56:59], v[158:161], v[68:71], v[56:59]
	v_mfma_f32_16x16x32_bf16 v[48:51], v[158:161], v[92:95], v[48:51]
	v_mfma_f32_16x16x32_bf16 v[44:47], v[150:153], v[202:205], v[44:47]
	v_mfma_f32_16x16x32_bf16 v[40:43], v[158:161], v[202:205], v[40:43]
	v_mfma_f32_16x16x32_bf16 v[36:39], v[150:153], v[210:213], v[36:39]
	v_mfma_f32_16x16x32_bf16 v[32:35], v[158:161], v[210:213], v[32:35]
	v_mfma_f32_16x16x32_bf16 v[60:63], v[150:153], v[68:71], v[60:63]
	v_mfma_f32_16x16x32_bf16 v[56:59], v[166:169], v[84:87], v[56:59]
	v_mfma_f32_16x16x32_bf16 v[52:55], v[150:153], v[92:95], v[52:55]
	v_mfma_f32_16x16x32_bf16 v[48:51], v[166:169], v[198:201], v[48:51]
	v_mfma_f32_16x16x32_bf16 v[44:47], v[154:157], v[206:209], v[44:47]
	v_mfma_f32_16x16x32_bf16 v[40:43], v[166:169], v[206:209], v[40:43]
	v_mfma_f32_16x16x32_bf16 v[36:39], v[154:157], v[214:217], v[36:39]
	v_mfma_f32_16x16x32_bf16 v[32:35], v[166:169], v[214:217], v[32:35]
	v_mfma_f32_16x16x32_bf16 v[218:221], v[154:157], v[84:87], v[60:63]
	v_mfma_f32_16x16x32_bf16 v[238:241], v[154:157], v[198:201], v[52:55]
	s_setprio 0
	s_setprio 1
	v_mfma_f32_16x16x32_bf16 v[28:31], v[162:165], v[68:71], v[28:31]
	v_mfma_f32_16x16x32_bf16 v[24:27], v[226:229], v[68:71], v[24:27]
	v_mfma_f32_16x16x32_bf16 v[20:23], v[162:165], v[92:95], v[20:23]
	v_mfma_f32_16x16x32_bf16 v[16:19], v[226:229], v[92:95], v[16:19]
	v_mfma_f32_16x16x32_bf16 v[12:15], v[162:165], v[202:205], v[12:15]
	v_mfma_f32_16x16x32_bf16 v[8:11], v[226:229], v[202:205], v[8:11]
	v_mfma_f32_16x16x32_bf16 v[4:7], v[162:165], v[210:213], v[4:7]
	v_mfma_f32_16x16x32_bf16 v[0:3], v[226:229], v[210:213], v[0:3]
	v_mfma_f32_16x16x32_bf16 v[28:31], v[222:225], v[84:87], v[28:31]
	v_mfma_f32_16x16x32_bf16 v[24:27], v[230:233], v[84:87], v[24:27]
	v_mfma_f32_16x16x32_bf16 v[20:23], v[222:225], v[198:201], v[20:23]
	v_mfma_f32_16x16x32_bf16 v[16:19], v[230:233], v[198:201], v[16:19]
	v_mfma_f32_16x16x32_bf16 v[12:15], v[222:225], v[206:209], v[12:15]
	v_mfma_f32_16x16x32_bf16 v[8:11], v[230:233], v[206:209], v[8:11]
	v_mfma_f32_16x16x32_bf16 v[4:7], v[222:225], v[214:217], v[4:7]
	v_mfma_f32_16x16x32_bf16 v[0:3], v[230:233], v[214:217], v[0:3]
	s_setprio 0
	s_barrier
	ds_read_b128 v[150:153], v147
	ds_read_b128 v[154:157], v147 offset:1024
	ds_read_b128 v[158:161], v147 offset:2048
	ds_read_b128 v[162:165], v147 offset:3072
	ds_read_b128 v[52:55], v142 offset:32768
	ds_read_b128 v[60:63], v142 offset:33792
	ds_read_b128 v[68:71], v143 offset:32768
	ds_read_b128 v[166:169], v143 offset:33792
	ds_read_b128 v[198:201], v144 offset:32768
	ds_read_b128 v[202:205], v144 offset:33792
	ds_read_b128 v[206:209], v145 offset:32768
	ds_read_b128 v[210:213], v145 offset:33792
	s_waitcnt vmcnt(2)
	s_barrier
	s_waitcnt lgkmcnt(0)
	s_setprio 1
	s_waitcnt lgkmcnt(0)
	v_mfma_f32_16x16x32_bf16 v[84:87], v[150:153], v[52:55], v[124:127]
	v_mfma_f32_16x16x32_bf16 v[124:127], v[154:157], v[60:63], v[84:87]
	v_mfma_f32_16x16x32_bf16 v[84:87], v[158:161], v[52:55], v[120:123]
	v_mfma_f32_16x16x32_bf16 v[120:123], v[162:165], v[60:63], v[84:87]
	v_mfma_f32_16x16x32_bf16 v[84:87], v[150:153], v[68:71], v[116:119]
	v_mfma_f32_16x16x32_bf16 v[116:119], v[154:157], v[166:169], v[84:87]
	v_mfma_f32_16x16x32_bf16 v[84:87], v[158:161], v[68:71], v[112:115]
	v_mfma_f32_16x16x32_bf16 v[112:115], v[162:165], v[166:169], v[84:87]
	v_mfma_f32_16x16x32_bf16 v[84:87], v[150:153], v[198:201], v[108:111]
	v_mfma_f32_16x16x32_bf16 v[108:111], v[154:157], v[202:205], v[84:87]
	v_mfma_f32_16x16x32_bf16 v[84:87], v[158:161], v[198:201], v[104:107]
	v_mfma_f32_16x16x32_bf16 v[104:107], v[162:165], v[202:205], v[84:87]
	v_mfma_f32_16x16x32_bf16 v[84:87], v[150:153], v[206:209], v[100:103]
	v_mfma_f32_16x16x32_bf16 v[92:95], v[154:157], v[210:213], v[84:87]
	v_mfma_f32_16x16x32_bf16 v[84:87], v[158:161], v[206:209], v[96:99]
	v_mfma_f32_16x16x32_bf16 v[84:87], v[162:165], v[210:213], v[84:87]
	s_setprio 0
	s_barrier
	ds_read_b128 v[214:217], v148
	ds_read_b128 v[222:225], v148 offset:1024
	ds_read_b128 v[226:229], v148 offset:2048
	ds_read_b128 v[230:233], v148 offset:3072
	s_waitcnt vmcnt(0)
	s_barrier
	s_waitcnt lgkmcnt(0)
	s_setprio 1
	s_waitcnt lgkmcnt(0)
	v_mfma_f32_16x16x32_bf16 v[96:99], v[214:217], v[52:55], v[234:237]
	v_mfma_f32_16x16x32_bf16 v[52:55], v[226:229], v[52:55], v[88:91]
	v_mfma_f32_16x16x32_bf16 v[100:103], v[222:225], v[60:63], v[96:99]
	v_mfma_f32_16x16x32_bf16 v[96:99], v[230:233], v[60:63], v[52:55]
	v_mfma_f32_16x16x32_bf16 v[52:55], v[214:217], v[68:71], v[170:173]
	v_mfma_f32_16x16x32_bf16 v[88:91], v[222:225], v[166:169], v[52:55]
	v_mfma_f32_16x16x32_bf16 v[52:55], v[226:229], v[68:71], v[80:83]
	v_mfma_f32_16x16x32_bf16 v[80:83], v[230:233], v[166:169], v[52:55]
	v_mfma_f32_16x16x32_bf16 v[52:55], v[214:217], v[198:201], v[76:79]
	v_mfma_f32_16x16x32_bf16 v[76:79], v[222:225], v[202:205], v[52:55]
	v_mfma_f32_16x16x32_bf16 v[52:55], v[226:229], v[198:201], v[72:75]
	v_mfma_f32_16x16x32_bf16 v[68:71], v[230:233], v[202:205], v[52:55]
	v_mfma_f32_16x16x32_bf16 v[52:55], v[214:217], v[206:209], v[194:197]
	v_mfma_f32_16x16x32_bf16 v[60:63], v[222:225], v[210:213], v[52:55]
	v_mfma_f32_16x16x32_bf16 v[52:55], v[226:229], v[206:209], v[64:67]
	v_mfma_f32_16x16x32_bf16 v[52:55], v[230:233], v[210:213], v[52:55]
	s_setprio 0
	s_barrier
	ds_read_b128 v[166:169], v142 offset:49152
	ds_read_b128 v[170:173], v142 offset:50176
	ds_read_b128 v[194:197], v143 offset:49152
	ds_read_b128 v[198:201], v143 offset:50176
	ds_read_b128 v[202:205], v144 offset:49152
	ds_read_b128 v[206:209], v144 offset:50176
	ds_read_b128 v[210:213], v145 offset:49152
	ds_read_b128 v[234:237], v145 offset:50176
	s_barrier
	s_waitcnt lgkmcnt(0)
	s_setprio 1
	s_waitcnt lgkmcnt(0)
	v_mfma_f32_16x16x32_bf16 v[64:67], v[150:153], v[166:169], v[218:221]
	v_mfma_f32_16x16x32_bf16 v[56:59], v[158:161], v[166:169], v[56:59]
	v_mfma_f32_16x16x32_bf16 v[72:75], v[154:157], v[170:173], v[64:67]
	v_mfma_f32_16x16x32_bf16 v[64:67], v[162:165], v[170:173], v[56:59]
	v_mfma_f32_16x16x32_bf16 v[56:59], v[150:153], v[194:197], v[238:241]
	v_mfma_f32_16x16x32_bf16 v[48:51], v[158:161], v[194:197], v[48:51]
	v_mfma_f32_16x16x32_bf16 v[44:47], v[150:153], v[202:205], v[44:47]
	v_mfma_f32_16x16x32_bf16 v[40:43], v[158:161], v[202:205], v[40:43]
	v_mfma_f32_16x16x32_bf16 v[36:39], v[150:153], v[210:213], v[36:39]
	v_mfma_f32_16x16x32_bf16 v[32:35], v[158:161], v[210:213], v[32:35]
	v_mfma_f32_16x16x32_bf16 v[56:59], v[154:157], v[198:201], v[56:59]
	v_mfma_f32_16x16x32_bf16 v[48:51], v[162:165], v[198:201], v[48:51]
	v_mfma_f32_16x16x32_bf16 v[44:47], v[154:157], v[206:209], v[44:47]
	v_mfma_f32_16x16x32_bf16 v[40:43], v[162:165], v[206:209], v[40:43]
	v_mfma_f32_16x16x32_bf16 v[36:39], v[154:157], v[234:237], v[36:39]
	v_mfma_f32_16x16x32_bf16 v[32:35], v[162:165], v[234:237], v[32:35]
	s_setprio 0
	s_setprio 1
	v_mfma_f32_16x16x32_bf16 v[28:31], v[214:217], v[166:169], v[28:31]
	v_mfma_f32_16x16x32_bf16 v[24:27], v[226:229], v[166:169], v[24:27]
	v_mfma_f32_16x16x32_bf16 v[20:23], v[214:217], v[194:197], v[20:23]
	v_mfma_f32_16x16x32_bf16 v[16:19], v[226:229], v[194:197], v[16:19]
	v_mfma_f32_16x16x32_bf16 v[12:15], v[214:217], v[202:205], v[12:15]
	v_mfma_f32_16x16x32_bf16 v[8:11], v[226:229], v[202:205], v[8:11]
	v_mfma_f32_16x16x32_bf16 v[4:7], v[214:217], v[210:213], v[4:7]
	v_mfma_f32_16x16x32_bf16 v[0:3], v[226:229], v[210:213], v[0:3]
	v_mfma_f32_16x16x32_bf16 v[28:31], v[222:225], v[170:173], v[28:31]
	v_mfma_f32_16x16x32_bf16 v[24:27], v[230:233], v[170:173], v[24:27]
	v_mfma_f32_16x16x32_bf16 v[20:23], v[222:225], v[198:201], v[20:23]
	v_mfma_f32_16x16x32_bf16 v[16:19], v[230:233], v[198:201], v[16:19]
	v_mfma_f32_16x16x32_bf16 v[12:15], v[222:225], v[206:209], v[12:15]
	v_mfma_f32_16x16x32_bf16 v[8:11], v[230:233], v[206:209], v[8:11]
	v_mfma_f32_16x16x32_bf16 v[4:7], v[222:225], v[234:237], v[4:7]
	v_mfma_f32_16x16x32_bf16 v[0:3], v[230:233], v[234:237], v[0:3]
	s_setprio 0
	s_barrier
	s_and_saveexec_b64 s[42:43], s[40:41]
	s_cbranch_execz .LBB0_1047
	s_barrier
	s_branch .LBB0_1047
